# barrier v2 + removed per-phase s_setprio flips from the 13 GEMM main loops
# speedup vs baseline: 1.0160x; 1.0033x over previous
.LBB0_111:
	ds_read_b128 v[162:165], v155
	ds_read_b128 v[166:169], v155 offset:1024
	ds_read_b128 v[170:173], v155 offset:2048
	ds_read_b128 v[174:177], v155 offset:3072
	ds_read_b128 v[178:181], v157
	ds_read_b128 v[186:189], v157 offset:1024
	ds_read_b128 v[190:193], v157 offset:2048
	ds_read_b128 v[194:197], v157 offset:3072
	s_add_u32 s19, s40, 0xfffc0080
	s_addc_u32 s20, s41, -1
	s_cmp_eq_u32 s18, 12
	s_cselect_b32 s89, s12, s20
	s_cselect_b32 s88, s13, s19
	s_cselect_b32 s81, s14, s17
	s_cselect_b32 s80, s15, s16
	v_lshl_add_u64 v[144:145], s[40:41], 0, v[136:137]
	s_add_i32 m0, s62, 0xc000
	ds_read_b128 v[198:201], v159
	ds_read_b128 v[202:205], v159 offset:1024
	ds_read_b128 v[206:209], v159 offset:2048
	ds_read_b128 v[210:213], v159 offset:3072
	ds_read_b128 v[214:217], v159 offset:4096
	ds_read_b128 v[218:221], v159 offset:5120
	ds_read_b128 v[222:225], v159 offset:6144
	ds_read_b128 v[226:229], v159 offset:7168
	global_load_lds_dwordx4 v[144:145], off
	v_lshl_add_u64 v[144:145], s[40:41], 0, v[138:139]
	s_add_i32 m0, s62, 0xe000
	s_nop 0
	global_load_lds_dwordx4 v[144:145], off
	s_waitcnt vmcnt(8)
	s_waitcnt lgkmcnt(0)
	s_barrier
	s_waitcnt lgkmcnt(0)
	v_mfma_f32_16x16x32_bf16 v[124:127], v[162:165], v[198:201], v[124:127]
	v_mfma_f32_16x16x32_bf16 v[120:123], v[170:173], v[198:201], v[120:123]
	v_mfma_f32_16x16x32_bf16 v[108:111], v[162:165], v[206:209], v[108:111]
	v_mfma_f32_16x16x32_bf16 v[100:103], v[170:173], v[206:209], v[100:103]
	v_mfma_f32_16x16x32_bf16 v[92:95], v[162:165], v[214:217], v[92:95]
	v_mfma_f32_16x16x32_bf16 v[84:87], v[170:173], v[214:217], v[84:87]
	v_mfma_f32_16x16x32_bf16 v[76:79], v[162:165], v[222:225], v[76:79]
	v_mfma_f32_16x16x32_bf16 v[68:71], v[170:173], v[222:225], v[68:71]
	v_mfma_f32_16x16x32_bf16 v[124:127], v[166:169], v[202:205], v[124:127]
	v_mfma_f32_16x16x32_bf16 v[120:123], v[174:177], v[202:205], v[120:123]
	v_mfma_f32_16x16x32_bf16 v[108:111], v[166:169], v[210:213], v[108:111]
	v_mfma_f32_16x16x32_bf16 v[100:103], v[174:177], v[210:213], v[100:103]
	v_mfma_f32_16x16x32_bf16 v[92:95], v[166:169], v[218:221], v[92:95]
	v_mfma_f32_16x16x32_bf16 v[84:87], v[174:177], v[218:221], v[84:87]
	v_mfma_f32_16x16x32_bf16 v[76:79], v[166:169], v[226:229], v[76:79]
	v_mfma_f32_16x16x32_bf16 v[68:71], v[174:177], v[226:229], v[68:71]
	v_mfma_f32_16x16x32_bf16 v[116:119], v[178:181], v[198:201], v[116:119]
	v_mfma_f32_16x16x32_bf16 v[112:115], v[190:193], v[198:201], v[112:115]
	v_mfma_f32_16x16x32_bf16 v[104:107], v[178:181], v[206:209], v[104:107]
	v_mfma_f32_16x16x32_bf16 v[96:99], v[190:193], v[206:209], v[96:99]
	v_mfma_f32_16x16x32_bf16 v[88:91], v[178:181], v[214:217], v[88:91]
	v_mfma_f32_16x16x32_bf16 v[80:83], v[190:193], v[214:217], v[80:83]
	v_mfma_f32_16x16x32_bf16 v[72:75], v[178:181], v[222:225], v[72:75]
	v_mfma_f32_16x16x32_bf16 v[64:67], v[190:193], v[222:225], v[64:67]
	v_mfma_f32_16x16x32_bf16 v[116:119], v[186:189], v[202:205], v[116:119]
	v_mfma_f32_16x16x32_bf16 v[112:115], v[194:197], v[202:205], v[112:115]
	v_mfma_f32_16x16x32_bf16 v[104:107], v[186:189], v[210:213], v[104:107]
	v_mfma_f32_16x16x32_bf16 v[96:99], v[194:197], v[210:213], v[96:99]
	v_mfma_f32_16x16x32_bf16 v[88:91], v[186:189], v[218:221], v[88:91]
	v_mfma_f32_16x16x32_bf16 v[80:83], v[194:197], v[218:221], v[80:83]
	v_mfma_f32_16x16x32_bf16 v[72:75], v[186:189], v[226:229], v[72:75]
	v_mfma_f32_16x16x32_bf16 v[64:67], v[194:197], v[226:229], v[64:67]
	s_barrier
	s_add_i32 s19, s73, s3
	v_lshl_add_u64 v[144:145], s[80:81], 0, v[132:133]
	s_mov_b32 m0, s19
	ds_read_b128 v[198:201], v159 offset:16384
	ds_read_b128 v[202:205], v159 offset:17408
	ds_read_b128 v[206:209], v159 offset:18432
	ds_read_b128 v[210:213], v159 offset:19456
	ds_read_b128 v[214:217], v159 offset:20480
	ds_read_b128 v[218:221], v159 offset:21504
	ds_read_b128 v[222:225], v159 offset:22528
	ds_read_b128 v[226:229], v159 offset:23552
	global_load_lds_dwordx4 v[144:145], off
	s_add_i32 m0, s19, 0x2000
	s_add_u32 s20, s80, 0x40000
	v_lshl_add_u64 v[148:149], s[80:81], 0, v[128:129]
	s_addc_u32 s21, s81, 0
	s_add_i32 s19, s74, s3
	global_load_lds_dwordx4 v[148:149], off
	v_lshl_add_u64 v[182:183], s[20:21], 0, v[132:133]
	s_mov_b32 m0, s19
	v_lshl_add_u64 v[230:231], s[88:89], 0, v[130:131]
	global_load_lds_dwordx4 v[182:183], off
	v_lshl_add_u64 v[182:183], s[20:21], 0, v[128:129]
	s_add_i32 m0, s19, 0x2000
	s_nop 0
	global_load_lds_dwordx4 v[182:183], off
	v_lshl_add_u64 v[182:183], s[88:89], 0, v[134:135]
	s_mov_b32 m0, s62
	s_nop 0
	global_load_lds_dwordx4 v[182:183], off
	s_mov_b32 m0, s63
	s_nop 0
	global_load_lds_dwordx4 v[230:231], off
	s_waitcnt vmcnt(8)
	s_waitcnt lgkmcnt(0)
	s_barrier
	s_waitcnt lgkmcnt(0)
	v_mfma_f32_16x16x32_bf16 v[60:63], v[162:165], v[198:201], v[60:63]
	v_mfma_f32_16x16x32_bf16 v[52:55], v[170:173], v[198:201], v[52:55]
	v_mfma_f32_16x16x32_bf16 v[44:47], v[162:165], v[206:209], v[44:47]
	v_mfma_f32_16x16x32_bf16 v[36:39], v[170:173], v[206:209], v[36:39]
	v_mfma_f32_16x16x32_bf16 v[28:31], v[162:165], v[214:217], v[28:31]
	v_mfma_f32_16x16x32_bf16 v[20:23], v[170:173], v[214:217], v[20:23]
	v_mfma_f32_16x16x32_bf16 v[12:15], v[162:165], v[222:225], v[12:15]
	v_mfma_f32_16x16x32_bf16 v[4:7], v[170:173], v[222:225], v[4:7]
	v_mfma_f32_16x16x32_bf16 v[60:63], v[166:169], v[202:205], v[60:63]
	v_mfma_f32_16x16x32_bf16 v[52:55], v[174:177], v[202:205], v[52:55]
	v_mfma_f32_16x16x32_bf16 v[44:47], v[166:169], v[210:213], v[44:47]
	v_mfma_f32_16x16x32_bf16 v[36:39], v[174:177], v[210:213], v[36:39]
	v_mfma_f32_16x16x32_bf16 v[28:31], v[166:169], v[218:221], v[28:31]
	v_mfma_f32_16x16x32_bf16 v[20:23], v[174:177], v[218:221], v[20:23]
	v_mfma_f32_16x16x32_bf16 v[12:15], v[166:169], v[226:229], v[12:15]
	v_mfma_f32_16x16x32_bf16 v[4:7], v[174:177], v[226:229], v[4:7]
	v_mfma_f32_16x16x32_bf16 v[56:59], v[178:181], v[198:201], v[56:59]
	v_mfma_f32_16x16x32_bf16 v[48:51], v[190:193], v[198:201], v[48:51]
	v_mfma_f32_16x16x32_bf16 v[40:43], v[178:181], v[206:209], v[40:43]
	v_mfma_f32_16x16x32_bf16 v[32:35], v[190:193], v[206:209], v[32:35]
	v_mfma_f32_16x16x32_bf16 v[24:27], v[178:181], v[214:217], v[24:27]
	v_mfma_f32_16x16x32_bf16 v[16:19], v[190:193], v[214:217], v[16:19]
	v_mfma_f32_16x16x32_bf16 v[8:11], v[178:181], v[222:225], v[8:11]
	v_mfma_f32_16x16x32_bf16 v[0:3], v[190:193], v[222:225], v[0:3]
	v_mfma_f32_16x16x32_bf16 v[56:59], v[186:189], v[202:205], v[56:59]
	v_mfma_f32_16x16x32_bf16 v[48:51], v[194:197], v[202:205], v[48:51]
	v_mfma_f32_16x16x32_bf16 v[40:43], v[186:189], v[210:213], v[40:43]
	v_mfma_f32_16x16x32_bf16 v[32:35], v[194:197], v[210:213], v[32:35]
	v_mfma_f32_16x16x32_bf16 v[24:27], v[186:189], v[218:221], v[24:27]
	v_mfma_f32_16x16x32_bf16 v[16:19], v[194:197], v[218:221], v[16:19]
	v_mfma_f32_16x16x32_bf16 v[8:11], v[186:189], v[226:229], v[8:11]
	v_mfma_f32_16x16x32_bf16 v[0:3], v[194:197], v[226:229], v[0:3]
	s_barrier
	s_add_i32 s19, 0, 0x18000
	v_add_u32_e32 v146, s19, v151
	s_add_i32 s22, 0, 0x1c000
	ds_read_b128 v[162:165], v146
	ds_read_b128 v[166:169], v146 offset:1024
	ds_read_b128 v[170:173], v146 offset:2048
	ds_read_b128 v[174:177], v146 offset:3072
	v_add_u32_e32 v146, s22, v151
	ds_read_b128 v[178:181], v146
	ds_read_b128 v[186:189], v146 offset:1024
	ds_read_b128 v[190:193], v146 offset:2048
	ds_read_b128 v[194:197], v146 offset:3072
	s_add_u32 s20, s88, 0x40000
	s_addc_u32 s21, s89, 0
	s_mov_b32 m0, s64
	v_lshl_add_u64 v[232:233], s[20:21], 0, v[134:135]
	ds_read_b128 v[198:201], v159 offset:32768
	ds_read_b128 v[202:205], v159 offset:33792
	ds_read_b128 v[206:209], v159 offset:34816
	ds_read_b128 v[210:213], v159 offset:35840
	ds_read_b128 v[214:217], v159 offset:36864
	ds_read_b128 v[218:221], v159 offset:37888
	ds_read_b128 v[222:225], v159 offset:38912
	ds_read_b128 v[226:229], v159 offset:39936
	global_load_lds_dwordx4 v[232:233], off
	v_lshl_add_u64 v[232:233], s[20:21], 0, v[130:131]
	s_mov_b32 m0, s65
	s_nop 0
	global_load_lds_dwordx4 v[232:233], off
	s_waitcnt vmcnt(8)
	s_waitcnt lgkmcnt(0)
	s_barrier
	s_waitcnt lgkmcnt(0)
	v_mfma_f32_16x16x32_bf16 v[124:127], v[162:165], v[198:201], v[124:127]
	v_mfma_f32_16x16x32_bf16 v[120:123], v[170:173], v[198:201], v[120:123]
	v_mfma_f32_16x16x32_bf16 v[108:111], v[162:165], v[206:209], v[108:111]
	v_mfma_f32_16x16x32_bf16 v[100:103], v[170:173], v[206:209], v[100:103]
	v_mfma_f32_16x16x32_bf16 v[92:95], v[162:165], v[214:217], v[92:95]
	v_mfma_f32_16x16x32_bf16 v[84:87], v[170:173], v[214:217], v[84:87]
	v_mfma_f32_16x16x32_bf16 v[76:79], v[162:165], v[222:225], v[76:79]
	v_mfma_f32_16x16x32_bf16 v[68:71], v[170:173], v[222:225], v[68:71]
	v_mfma_f32_16x16x32_bf16 v[124:127], v[166:169], v[202:205], v[124:127]
	v_mfma_f32_16x16x32_bf16 v[120:123], v[174:177], v[202:205], v[120:123]
	v_mfma_f32_16x16x32_bf16 v[108:111], v[166:169], v[210:213], v[108:111]
	v_mfma_f32_16x16x32_bf16 v[100:103], v[174:177], v[210:213], v[100:103]
	v_mfma_f32_16x16x32_bf16 v[92:95], v[166:169], v[218:221], v[92:95]
	v_mfma_f32_16x16x32_bf16 v[84:87], v[174:177], v[218:221], v[84:87]
	v_mfma_f32_16x16x32_bf16 v[76:79], v[166:169], v[226:229], v[76:79]
	v_mfma_f32_16x16x32_bf16 v[68:71], v[174:177], v[226:229], v[68:71]
	v_mfma_f32_16x16x32_bf16 v[116:119], v[178:181], v[198:201], v[116:119]
	v_mfma_f32_16x16x32_bf16 v[112:115], v[190:193], v[198:201], v[112:115]
	v_mfma_f32_16x16x32_bf16 v[104:107], v[178:181], v[206:209], v[104:107]
	v_mfma_f32_16x16x32_bf16 v[96:99], v[190:193], v[206:209], v[96:99]
	v_mfma_f32_16x16x32_bf16 v[88:91], v[178:181], v[214:217], v[88:91]
	v_mfma_f32_16x16x32_bf16 v[80:83], v[190:193], v[214:217], v[80:83]
	v_mfma_f32_16x16x32_bf16 v[72:75], v[178:181], v[222:225], v[72:75]
	v_mfma_f32_16x16x32_bf16 v[64:67], v[190:193], v[222:225], v[64:67]
	v_mfma_f32_16x16x32_bf16 v[116:119], v[186:189], v[202:205], v[116:119]
	v_mfma_f32_16x16x32_bf16 v[112:115], v[194:197], v[202:205], v[112:115]
	v_mfma_f32_16x16x32_bf16 v[104:107], v[186:189], v[210:213], v[104:107]
	v_mfma_f32_16x16x32_bf16 v[96:99], v[194:197], v[210:213], v[96:99]
	v_mfma_f32_16x16x32_bf16 v[88:91], v[186:189], v[218:221], v[88:91]
	v_mfma_f32_16x16x32_bf16 v[80:83], v[194:197], v[218:221], v[80:83]
	v_mfma_f32_16x16x32_bf16 v[72:75], v[186:189], v[226:229], v[72:75]
	v_mfma_f32_16x16x32_bf16 v[64:67], v[194:197], v[226:229], v[64:67]
	s_barrier
	s_add_i32 s19, s19, s3
	v_lshl_add_u64 v[144:145], v[144:145], 0, s[28:29]
	s_mov_b32 m0, s19
	ds_read_b128 v[198:201], v159 offset:49152
	ds_read_b128 v[202:205], v159 offset:50176
	ds_read_b128 v[206:209], v159 offset:51200
	ds_read_b128 v[210:213], v159 offset:52224
	ds_read_b128 v[214:217], v159 offset:53248
	ds_read_b128 v[218:221], v159 offset:54272
	ds_read_b128 v[222:225], v159 offset:55296
	ds_read_b128 v[226:229], v159 offset:56320
	global_load_lds_dwordx4 v[144:145], off
	s_add_i32 m0, s19, 0x2000
	s_add_u32 s20, s80, 0x40080
	v_lshl_add_u64 v[144:145], v[148:149], 0, s[28:29]
	s_addc_u32 s21, s81, 0
	s_add_i32 s19, s22, s3
	global_load_lds_dwordx4 v[144:145], off
	v_lshl_add_u64 v[144:145], s[20:21], 0, v[132:133]
	s_mov_b32 m0, s19
	s_nop 0
	global_load_lds_dwordx4 v[144:145], off
	v_lshl_add_u64 v[144:145], s[20:21], 0, v[128:129]
	s_add_i32 m0, s19, 0x2000
	s_nop 0
	global_load_lds_dwordx4 v[144:145], off
	v_lshl_add_u64 v[144:145], v[182:183], 0, s[28:29]
	s_mov_b32 m0, s67
	s_nop 0
	global_load_lds_dwordx4 v[144:145], off
	v_lshl_add_u64 v[144:145], v[230:231], 0, s[28:29]
	s_mov_b32 m0, s70
	s_nop 0
	global_load_lds_dwordx4 v[144:145], off
	s_waitcnt vmcnt(8)
	s_waitcnt lgkmcnt(0)
	s_barrier
	s_waitcnt lgkmcnt(0)
	v_mfma_f32_16x16x32_bf16 v[60:63], v[162:165], v[198:201], v[60:63]
	v_mfma_f32_16x16x32_bf16 v[52:55], v[170:173], v[198:201], v[52:55]
	v_mfma_f32_16x16x32_bf16 v[44:47], v[162:165], v[206:209], v[44:47]
	v_mfma_f32_16x16x32_bf16 v[36:39], v[170:173], v[206:209], v[36:39]
	v_mfma_f32_16x16x32_bf16 v[28:31], v[162:165], v[214:217], v[28:31]
	v_mfma_f32_16x16x32_bf16 v[20:23], v[170:173], v[214:217], v[20:23]
	v_mfma_f32_16x16x32_bf16 v[12:15], v[162:165], v[222:225], v[12:15]
	v_mfma_f32_16x16x32_bf16 v[4:7], v[170:173], v[222:225], v[4:7]
	v_mfma_f32_16x16x32_bf16 v[60:63], v[166:169], v[202:205], v[60:63]
	v_mfma_f32_16x16x32_bf16 v[52:55], v[174:177], v[202:205], v[52:55]
	v_mfma_f32_16x16x32_bf16 v[44:47], v[166:169], v[210:213], v[44:47]
	v_mfma_f32_16x16x32_bf16 v[36:39], v[174:177], v[210:213], v[36:39]
	v_mfma_f32_16x16x32_bf16 v[28:31], v[166:169], v[218:221], v[28:31]
	v_mfma_f32_16x16x32_bf16 v[20:23], v[174:177], v[218:221], v[20:23]
	v_mfma_f32_16x16x32_bf16 v[12:15], v[166:169], v[226:229], v[12:15]
	v_mfma_f32_16x16x32_bf16 v[4:7], v[174:177], v[226:229], v[4:7]
	v_mfma_f32_16x16x32_bf16 v[56:59], v[178:181], v[198:201], v[56:59]
	v_mfma_f32_16x16x32_bf16 v[48:51], v[190:193], v[198:201], v[48:51]
	v_mfma_f32_16x16x32_bf16 v[40:43], v[178:181], v[206:209], v[40:43]
	v_mfma_f32_16x16x32_bf16 v[32:35], v[190:193], v[206:209], v[32:35]
	v_mfma_f32_16x16x32_bf16 v[24:27], v[178:181], v[214:217], v[24:27]
	v_mfma_f32_16x16x32_bf16 v[16:19], v[190:193], v[214:217], v[16:19]
	v_mfma_f32_16x16x32_bf16 v[8:11], v[178:181], v[222:225], v[8:11]
	v_mfma_f32_16x16x32_bf16 v[0:3], v[190:193], v[222:225], v[0:3]
	v_mfma_f32_16x16x32_bf16 v[56:59], v[186:189], v[202:205], v[56:59]
	v_mfma_f32_16x16x32_bf16 v[48:51], v[194:197], v[202:205], v[48:51]
	v_mfma_f32_16x16x32_bf16 v[40:43], v[186:189], v[210:213], v[40:43]
	v_mfma_f32_16x16x32_bf16 v[32:35], v[194:197], v[210:213], v[32:35]
	v_mfma_f32_16x16x32_bf16 v[24:27], v[186:189], v[218:221], v[24:27]
	v_mfma_f32_16x16x32_bf16 v[16:19], v[194:197], v[218:221], v[16:19]
	v_mfma_f32_16x16x32_bf16 v[8:11], v[186:189], v[226:229], v[8:11]
	v_mfma_f32_16x16x32_bf16 v[0:3], v[194:197], v[226:229], v[0:3]
	s_barrier
	s_add_i32 s18, s18, 2
	s_add_u32 s40, s40, 0x100
	s_addc_u32 s41, s41, 0
	s_add_u32 s16, s16, 0x100
	s_addc_u32 s17, s17, 0
	s_cmp_gt_u32 s18, 13
	s_cbranch_scc0 .LBB0_111
	s_and_b64 vcc, exec, s[30:31]
	s_cbranch_vccz .LBB0_114
	s_barrier

.LBB0_445:
	ds_read_b128 v[128:131], v213
	ds_read_b128 v[132:135], v213 offset:1024
	ds_read_b128 v[136:139], v213 offset:2048
	ds_read_b128 v[140:143], v213 offset:3072
	ds_read_b128 v[144:147], v214
	ds_read_b128 v[148:151], v214 offset:1024
	ds_read_b128 v[152:155], v214 offset:2048
	ds_read_b128 v[156:159], v214 offset:3072
	s_add_u32 s42, s40, 0xfff50080
	s_addc_u32 s43, s41, -1
	s_cmp_eq_u32 s62, 40
	s_cselect_b32 s81, s1, s43
	s_cselect_b32 s80, s0, s42
	s_cselect_b32 s43, s37, s61
	s_cselect_b32 s42, s36, s39
	v_lshl_add_u64 v[222:223], s[40:41], 0, v[190:191]
	s_add_i32 m0, s14, 0xc000
	ds_read_b128 v[160:163], v215
	ds_read_b128 v[164:167], v215 offset:1024
	ds_read_b128 v[168:171], v215 offset:2048
	ds_read_b128 v[172:175], v215 offset:3072
	ds_read_b128 v[198:201], v215 offset:4096
	ds_read_b128 v[202:205], v215 offset:5120
	ds_read_b128 v[206:209], v215 offset:6144
	ds_read_b128 v[218:221], v215 offset:7168
	global_load_lds_dwordx4 v[222:223], off
	v_lshl_add_u64 v[222:223], s[40:41], 0, v[192:193]
	s_add_i32 m0, s14, 0xe000
	s_nop 0
	global_load_lds_dwordx4 v[222:223], off
	s_waitcnt vmcnt(8)
	s_waitcnt lgkmcnt(0)
	s_barrier
	s_waitcnt lgkmcnt(0)
	v_mfma_f32_16x16x32_bf16 v[124:127], v[128:131], v[160:163], v[124:127]
	v_mfma_f32_16x16x32_bf16 v[120:123], v[136:139], v[160:163], v[120:123]
	v_mfma_f32_16x16x32_bf16 v[108:111], v[128:131], v[168:171], v[108:111]
	v_mfma_f32_16x16x32_bf16 v[104:107], v[136:139], v[168:171], v[104:107]
	v_mfma_f32_16x16x32_bf16 v[92:95], v[128:131], v[198:201], v[92:95]
	v_mfma_f32_16x16x32_bf16 v[88:91], v[136:139], v[198:201], v[88:91]
	v_mfma_f32_16x16x32_bf16 v[76:79], v[128:131], v[206:209], v[76:79]
	v_mfma_f32_16x16x32_bf16 v[72:75], v[136:139], v[206:209], v[72:75]
	v_mfma_f32_16x16x32_bf16 v[124:127], v[132:135], v[164:167], v[124:127]
	v_mfma_f32_16x16x32_bf16 v[120:123], v[140:143], v[164:167], v[120:123]
	v_mfma_f32_16x16x32_bf16 v[108:111], v[132:135], v[172:175], v[108:111]
	v_mfma_f32_16x16x32_bf16 v[104:107], v[140:143], v[172:175], v[104:107]
	v_mfma_f32_16x16x32_bf16 v[92:95], v[132:135], v[202:205], v[92:95]
	v_mfma_f32_16x16x32_bf16 v[88:91], v[140:143], v[202:205], v[88:91]
	v_mfma_f32_16x16x32_bf16 v[76:79], v[132:135], v[218:221], v[76:79]
	v_mfma_f32_16x16x32_bf16 v[72:75], v[140:143], v[218:221], v[72:75]
	v_mfma_f32_16x16x32_bf16 v[116:119], v[144:147], v[160:163], v[116:119]
	v_mfma_f32_16x16x32_bf16 v[112:115], v[152:155], v[160:163], v[112:115]
	v_mfma_f32_16x16x32_bf16 v[100:103], v[144:147], v[168:171], v[100:103]
	v_mfma_f32_16x16x32_bf16 v[96:99], v[152:155], v[168:171], v[96:99]
	v_mfma_f32_16x16x32_bf16 v[84:87], v[144:147], v[198:201], v[84:87]
	v_mfma_f32_16x16x32_bf16 v[80:83], v[152:155], v[198:201], v[80:83]
	v_mfma_f32_16x16x32_bf16 v[68:71], v[144:147], v[206:209], v[68:71]
	v_mfma_f32_16x16x32_bf16 v[64:67], v[152:155], v[206:209], v[64:67]
	v_mfma_f32_16x16x32_bf16 v[116:119], v[148:151], v[164:167], v[116:119]
	v_mfma_f32_16x16x32_bf16 v[112:115], v[156:159], v[164:167], v[112:115]
	v_mfma_f32_16x16x32_bf16 v[100:103], v[148:151], v[172:175], v[100:103]
	v_mfma_f32_16x16x32_bf16 v[96:99], v[156:159], v[172:175], v[96:99]
	v_mfma_f32_16x16x32_bf16 v[84:87], v[148:151], v[202:205], v[84:87]
	v_mfma_f32_16x16x32_bf16 v[80:83], v[156:159], v[202:205], v[80:83]
	v_mfma_f32_16x16x32_bf16 v[68:71], v[148:151], v[218:221], v[68:71]
	v_mfma_f32_16x16x32_bf16 v[64:67], v[156:159], v[218:221], v[64:67]
	s_barrier
	s_add_i32 s63, s24, s13
	v_lshl_add_u64 v[222:223], s[42:43], 0, v[178:179]
	s_mov_b32 m0, s63
	ds_read_b128 v[160:163], v215 offset:16384
	ds_read_b128 v[164:167], v215 offset:17408
	ds_read_b128 v[168:171], v215 offset:18432
	ds_read_b128 v[172:175], v215 offset:19456
	ds_read_b128 v[198:201], v215 offset:20480
	ds_read_b128 v[202:205], v215 offset:21504
	ds_read_b128 v[206:209], v215 offset:22528
	ds_read_b128 v[218:221], v215 offset:23552
	global_load_lds_dwordx4 v[222:223], off
	s_add_i32 m0, s63, 0x2000
	s_add_u32 s64, s42, 0xb0000
	v_lshl_add_u64 v[224:225], s[42:43], 0, v[182:183]
	s_addc_u32 s65, s43, 0
	s_add_i32 s63, s25, s13
	global_load_lds_dwordx4 v[224:225], off
	v_lshl_add_u64 v[226:227], s[64:65], 0, v[178:179]
	s_mov_b32 m0, s63
	v_lshl_add_u64 v[228:229], s[80:81], 0, v[180:181]
	global_load_lds_dwordx4 v[226:227], off
	v_lshl_add_u64 v[226:227], s[64:65], 0, v[182:183]
	s_add_i32 m0, s63, 0x2000
	s_nop 0
	global_load_lds_dwordx4 v[226:227], off
	v_lshl_add_u64 v[226:227], s[80:81], 0, v[176:177]
	s_mov_b32 m0, s14
	s_nop 0
	global_load_lds_dwordx4 v[226:227], off
	s_mov_b32 m0, s15
	s_nop 0
	global_load_lds_dwordx4 v[228:229], off
	s_waitcnt vmcnt(8)
	s_waitcnt lgkmcnt(0)
	s_barrier
	s_waitcnt lgkmcnt(0)
	v_mfma_f32_16x16x32_bf16 v[60:63], v[128:131], v[160:163], v[60:63]
	v_mfma_f32_16x16x32_bf16 v[56:59], v[136:139], v[160:163], v[56:59]
	v_mfma_f32_16x16x32_bf16 v[44:47], v[128:131], v[168:171], v[44:47]
	v_mfma_f32_16x16x32_bf16 v[40:43], v[136:139], v[168:171], v[40:43]
	v_mfma_f32_16x16x32_bf16 v[28:31], v[128:131], v[198:201], v[28:31]
	v_mfma_f32_16x16x32_bf16 v[24:27], v[136:139], v[198:201], v[24:27]
	v_mfma_f32_16x16x32_bf16 v[12:15], v[128:131], v[206:209], v[12:15]
	v_mfma_f32_16x16x32_bf16 v[8:11], v[136:139], v[206:209], v[8:11]
	v_mfma_f32_16x16x32_bf16 v[60:63], v[132:135], v[164:167], v[60:63]
	v_mfma_f32_16x16x32_bf16 v[56:59], v[140:143], v[164:167], v[56:59]
	v_mfma_f32_16x16x32_bf16 v[44:47], v[132:135], v[172:175], v[44:47]
	v_mfma_f32_16x16x32_bf16 v[40:43], v[140:143], v[172:175], v[40:43]
	v_mfma_f32_16x16x32_bf16 v[28:31], v[132:135], v[202:205], v[28:31]
	v_mfma_f32_16x16x32_bf16 v[24:27], v[140:143], v[202:205], v[24:27]
	v_mfma_f32_16x16x32_bf16 v[12:15], v[132:135], v[218:221], v[12:15]
	v_mfma_f32_16x16x32_bf16 v[8:11], v[140:143], v[218:221], v[8:11]
	v_mfma_f32_16x16x32_bf16 v[52:55], v[144:147], v[160:163], v[52:55]
	v_mfma_f32_16x16x32_bf16 v[48:51], v[152:155], v[160:163], v[48:51]
	v_mfma_f32_16x16x32_bf16 v[36:39], v[144:147], v[168:171], v[36:39]
	v_mfma_f32_16x16x32_bf16 v[32:35], v[152:155], v[168:171], v[32:35]
	v_mfma_f32_16x16x32_bf16 v[20:23], v[144:147], v[198:201], v[20:23]
	v_mfma_f32_16x16x32_bf16 v[16:19], v[152:155], v[198:201], v[16:19]
	v_mfma_f32_16x16x32_bf16 v[4:7], v[144:147], v[206:209], v[4:7]
	v_mfma_f32_16x16x32_bf16 v[0:3], v[152:155], v[206:209], v[0:3]
	v_mfma_f32_16x16x32_bf16 v[52:55], v[148:151], v[164:167], v[52:55]
	v_mfma_f32_16x16x32_bf16 v[48:51], v[156:159], v[164:167], v[48:51]
	v_mfma_f32_16x16x32_bf16 v[36:39], v[148:151], v[172:175], v[36:39]
	v_mfma_f32_16x16x32_bf16 v[32:35], v[156:159], v[172:175], v[32:35]
	v_mfma_f32_16x16x32_bf16 v[20:23], v[148:151], v[202:205], v[20:23]
	v_mfma_f32_16x16x32_bf16 v[16:19], v[156:159], v[202:205], v[16:19]
	v_mfma_f32_16x16x32_bf16 v[4:7], v[148:151], v[218:221], v[4:7]
	v_mfma_f32_16x16x32_bf16 v[0:3], v[156:159], v[218:221], v[0:3]
	s_barrier
	s_add_i32 s63, 0, 0x18000
	s_add_i32 s66, 0, 0x1c000
	v_add_u32_e32 v140, s63, v210
	v_add_u32_e32 v156, s66, v210
	ds_read_b128 v[128:131], v140
	ds_read_b128 v[132:135], v140 offset:1024
	ds_read_b128 v[136:139], v140 offset:2048
	ds_read_b128 v[140:143], v140 offset:3072
	ds_read_b128 v[144:147], v156
	ds_read_b128 v[148:151], v156 offset:1024
	ds_read_b128 v[152:155], v156 offset:2048
	ds_read_b128 v[156:159], v156 offset:3072
	s_add_u32 s64, s80, 0xb0000
	s_addc_u32 s65, s81, 0
	s_mov_b32 m0, s16
	v_lshl_add_u64 v[230:231], s[64:65], 0, v[176:177]
	ds_read_b128 v[160:163], v215 offset:32768
	ds_read_b128 v[164:167], v215 offset:33792
	ds_read_b128 v[168:171], v215 offset:34816
	ds_read_b128 v[172:175], v215 offset:35840
	ds_read_b128 v[198:201], v215 offset:36864
	ds_read_b128 v[202:205], v215 offset:37888
	ds_read_b128 v[206:209], v215 offset:38912
	ds_read_b128 v[218:221], v215 offset:39936
	global_load_lds_dwordx4 v[230:231], off
	v_lshl_add_u64 v[230:231], s[64:65], 0, v[180:181]
	s_mov_b32 m0, s17
	s_nop 0
	global_load_lds_dwordx4 v[230:231], off
	s_waitcnt vmcnt(8)
	s_waitcnt lgkmcnt(0)
	s_barrier
	s_waitcnt lgkmcnt(0)
	v_mfma_f32_16x16x32_bf16 v[124:127], v[128:131], v[160:163], v[124:127]
	v_mfma_f32_16x16x32_bf16 v[120:123], v[136:139], v[160:163], v[120:123]
	v_mfma_f32_16x16x32_bf16 v[108:111], v[128:131], v[168:171], v[108:111]
	v_mfma_f32_16x16x32_bf16 v[104:107], v[136:139], v[168:171], v[104:107]
	v_mfma_f32_16x16x32_bf16 v[92:95], v[128:131], v[198:201], v[92:95]
	v_mfma_f32_16x16x32_bf16 v[88:91], v[136:139], v[198:201], v[88:91]
	v_mfma_f32_16x16x32_bf16 v[76:79], v[128:131], v[206:209], v[76:79]
	v_mfma_f32_16x16x32_bf16 v[72:75], v[136:139], v[206:209], v[72:75]
	v_mfma_f32_16x16x32_bf16 v[124:127], v[132:135], v[164:167], v[124:127]
	v_mfma_f32_16x16x32_bf16 v[120:123], v[140:143], v[164:167], v[120:123]
	v_mfma_f32_16x16x32_bf16 v[108:111], v[132:135], v[172:175], v[108:111]
	v_mfma_f32_16x16x32_bf16 v[104:107], v[140:143], v[172:175], v[104:107]
	v_mfma_f32_16x16x32_bf16 v[92:95], v[132:135], v[202:205], v[92:95]
	v_mfma_f32_16x16x32_bf16 v[88:91], v[140:143], v[202:205], v[88:91]
	v_mfma_f32_16x16x32_bf16 v[76:79], v[132:135], v[218:221], v[76:79]
	v_mfma_f32_16x16x32_bf16 v[72:75], v[140:143], v[218:221], v[72:75]
	v_mfma_f32_16x16x32_bf16 v[116:119], v[144:147], v[160:163], v[116:119]
	v_mfma_f32_16x16x32_bf16 v[112:115], v[152:155], v[160:163], v[112:115]
	v_mfma_f32_16x16x32_bf16 v[100:103], v[144:147], v[168:171], v[100:103]
	v_mfma_f32_16x16x32_bf16 v[96:99], v[152:155], v[168:171], v[96:99]
	v_mfma_f32_16x16x32_bf16 v[84:87], v[144:147], v[198:201], v[84:87]
	v_mfma_f32_16x16x32_bf16 v[80:83], v[152:155], v[198:201], v[80:83]
	v_mfma_f32_16x16x32_bf16 v[68:71], v[144:147], v[206:209], v[68:71]
	v_mfma_f32_16x16x32_bf16 v[64:67], v[152:155], v[206:209], v[64:67]
	v_mfma_f32_16x16x32_bf16 v[116:119], v[148:151], v[164:167], v[116:119]
	v_mfma_f32_16x16x32_bf16 v[112:115], v[156:159], v[164:167], v[112:115]
	v_mfma_f32_16x16x32_bf16 v[100:103], v[148:151], v[172:175], v[100:103]
	v_mfma_f32_16x16x32_bf16 v[96:99], v[156:159], v[172:175], v[96:99]
	v_mfma_f32_16x16x32_bf16 v[84:87], v[148:151], v[202:205], v[84:87]
	v_mfma_f32_16x16x32_bf16 v[80:83], v[156:159], v[202:205], v[80:83]
	v_mfma_f32_16x16x32_bf16 v[68:71], v[148:151], v[218:221], v[68:71]
	v_mfma_f32_16x16x32_bf16 v[64:67], v[156:159], v[218:221], v[64:67]
	s_barrier
	s_add_i32 s63, s63, s13
	v_lshl_add_u64 v[222:223], v[222:223], 0, s[30:31]
	s_mov_b32 m0, s63
	ds_read_b128 v[160:163], v215 offset:49152
	ds_read_b128 v[164:167], v215 offset:50176
	ds_read_b128 v[168:171], v215 offset:51200
	ds_read_b128 v[172:175], v215 offset:52224
	ds_read_b128 v[198:201], v215 offset:53248
	ds_read_b128 v[202:205], v215 offset:54272
	ds_read_b128 v[206:209], v215 offset:55296
	ds_read_b128 v[218:221], v215 offset:56320
	global_load_lds_dwordx4 v[222:223], off
	s_add_i32 m0, s63, 0x2000
	s_add_u32 s42, s42, 0xb0080
	v_lshl_add_u64 v[222:223], v[224:225], 0, s[30:31]
	s_addc_u32 s43, s43, 0
	s_add_i32 s63, s66, s13
	global_load_lds_dwordx4 v[222:223], off
	v_lshl_add_u64 v[222:223], s[42:43], 0, v[178:179]
	s_mov_b32 m0, s63
	s_nop 0
	global_load_lds_dwordx4 v[222:223], off
	v_lshl_add_u64 v[222:223], s[42:43], 0, v[182:183]
	s_add_i32 m0, s63, 0x2000
	s_nop 0
	global_load_lds_dwordx4 v[222:223], off
	v_lshl_add_u64 v[222:223], v[226:227], 0, s[30:31]
	s_mov_b32 m0, s19
	s_nop 0
	global_load_lds_dwordx4 v[222:223], off
	v_lshl_add_u64 v[222:223], v[228:229], 0, s[30:31]
	s_mov_b32 m0, s20
	s_nop 0
	global_load_lds_dwordx4 v[222:223], off
	s_waitcnt vmcnt(8)
	s_waitcnt lgkmcnt(0)
	s_barrier
	s_waitcnt lgkmcnt(0)
	v_mfma_f32_16x16x32_bf16 v[60:63], v[128:131], v[160:163], v[60:63]
	v_mfma_f32_16x16x32_bf16 v[56:59], v[136:139], v[160:163], v[56:59]
	v_mfma_f32_16x16x32_bf16 v[44:47], v[128:131], v[168:171], v[44:47]
	v_mfma_f32_16x16x32_bf16 v[40:43], v[136:139], v[168:171], v[40:43]
	v_mfma_f32_16x16x32_bf16 v[28:31], v[128:131], v[198:201], v[28:31]
	v_mfma_f32_16x16x32_bf16 v[24:27], v[136:139], v[198:201], v[24:27]
	v_mfma_f32_16x16x32_bf16 v[12:15], v[128:131], v[206:209], v[12:15]
	v_mfma_f32_16x16x32_bf16 v[8:11], v[136:139], v[206:209], v[8:11]
	v_mfma_f32_16x16x32_bf16 v[60:63], v[132:135], v[164:167], v[60:63]
	v_mfma_f32_16x16x32_bf16 v[56:59], v[140:143], v[164:167], v[56:59]
	v_mfma_f32_16x16x32_bf16 v[44:47], v[132:135], v[172:175], v[44:47]
	v_mfma_f32_16x16x32_bf16 v[40:43], v[140:143], v[172:175], v[40:43]
	v_mfma_f32_16x16x32_bf16 v[28:31], v[132:135], v[202:205], v[28:31]
	v_mfma_f32_16x16x32_bf16 v[24:27], v[140:143], v[202:205], v[24:27]
	v_mfma_f32_16x16x32_bf16 v[12:15], v[132:135], v[218:221], v[12:15]
	v_mfma_f32_16x16x32_bf16 v[8:11], v[140:143], v[218:221], v[8:11]
	v_mfma_f32_16x16x32_bf16 v[52:55], v[144:147], v[160:163], v[52:55]
	v_mfma_f32_16x16x32_bf16 v[48:51], v[152:155], v[160:163], v[48:51]
	v_mfma_f32_16x16x32_bf16 v[36:39], v[144:147], v[168:171], v[36:39]
	v_mfma_f32_16x16x32_bf16 v[32:35], v[152:155], v[168:171], v[32:35]
	v_mfma_f32_16x16x32_bf16 v[20:23], v[144:147], v[198:201], v[20:23]
	v_mfma_f32_16x16x32_bf16 v[16:19], v[152:155], v[198:201], v[16:19]
	v_mfma_f32_16x16x32_bf16 v[4:7], v[144:147], v[206:209], v[4:7]
	v_mfma_f32_16x16x32_bf16 v[0:3], v[152:155], v[206:209], v[0:3]
	v_mfma_f32_16x16x32_bf16 v[52:55], v[148:151], v[164:167], v[52:55]
	v_mfma_f32_16x16x32_bf16 v[48:51], v[156:159], v[164:167], v[48:51]
	v_mfma_f32_16x16x32_bf16 v[36:39], v[148:151], v[172:175], v[36:39]
	v_mfma_f32_16x16x32_bf16 v[32:35], v[156:159], v[172:175], v[32:35]
	v_mfma_f32_16x16x32_bf16 v[20:23], v[148:151], v[202:205], v[20:23]
	v_mfma_f32_16x16x32_bf16 v[16:19], v[156:159], v[202:205], v[16:19]
	v_mfma_f32_16x16x32_bf16 v[4:7], v[148:151], v[218:221], v[4:7]
	v_mfma_f32_16x16x32_bf16 v[0:3], v[156:159], v[218:221], v[0:3]
	s_barrier
	s_add_i32 s62, s62, 2
	s_add_u32 s40, s40, 0x100
	s_addc_u32 s41, s41, 0
	s_add_u32 s39, s39, 0x100
	s_addc_u32 s61, s61, 0
	s_cmp_gt_u32 s62, 41
	s_cbranch_scc0 .LBB0_445
	s_and_b64 vcc, exec, s[34:35]
	s_cbranch_vccz .LBB0_448
	s_barrier

.LBB0_546:
	ds_read_b128 v[144:147], v155
	ds_read_b128 v[148:151], v155 offset:1024
	ds_read_b128 v[160:163], v155 offset:2048
	ds_read_b128 v[164:167], v155 offset:3072
	ds_read_b128 v[168:171], v156
	ds_read_b128 v[172:175], v156 offset:1024
	ds_read_b128 v[176:179], v156 offset:2048
	ds_read_b128 v[180:183], v156 offset:3072
	s_add_u32 s19, s6, 0xfffc0080
	s_addc_u32 s20, s7, -1
	s_cmp_eq_u32 s18, 12
	s_cselect_b32 s89, s8, s20
	s_cselect_b32 s88, s9, s19
	s_cselect_b32 s43, s14, s17
	s_cselect_b32 s42, s15, s16
	v_lshl_add_u64 v[218:219], s[6:7], 0, v[136:137]
	s_add_i32 m0, s63, 0xc000
	ds_read_b128 v[186:189], v157
	ds_read_b128 v[190:193], v157 offset:1024
	ds_read_b128 v[194:197], v157 offset:2048
	ds_read_b128 v[198:201], v157 offset:3072
	ds_read_b128 v[202:205], v157 offset:4096
	ds_read_b128 v[206:209], v157 offset:5120
	ds_read_b128 v[210:213], v157 offset:6144
	ds_read_b128 v[214:217], v157 offset:7168
	global_load_lds_dwordx4 v[218:219], off
	v_lshl_add_u64 v[218:219], s[6:7], 0, v[138:139]
	s_add_i32 m0, s63, 0xe000
	s_nop 0
	global_load_lds_dwordx4 v[218:219], off
	s_waitcnt vmcnt(8)
	s_waitcnt lgkmcnt(0)
	s_barrier
	s_waitcnt lgkmcnt(0)
	v_mfma_f32_16x16x32_bf16 v[124:127], v[144:147], v[186:189], v[124:127]
	v_mfma_f32_16x16x32_bf16 v[120:123], v[160:163], v[186:189], v[120:123]
	v_mfma_f32_16x16x32_bf16 v[108:111], v[144:147], v[194:197], v[108:111]
	v_mfma_f32_16x16x32_bf16 v[104:107], v[160:163], v[194:197], v[104:107]
	v_mfma_f32_16x16x32_bf16 v[92:95], v[144:147], v[202:205], v[92:95]
	v_mfma_f32_16x16x32_bf16 v[88:91], v[160:163], v[202:205], v[88:91]
	v_mfma_f32_16x16x32_bf16 v[76:79], v[144:147], v[210:213], v[76:79]
	v_mfma_f32_16x16x32_bf16 v[72:75], v[160:163], v[210:213], v[72:75]
	v_mfma_f32_16x16x32_bf16 v[124:127], v[148:151], v[190:193], v[124:127]
	v_mfma_f32_16x16x32_bf16 v[120:123], v[164:167], v[190:193], v[120:123]
	v_mfma_f32_16x16x32_bf16 v[108:111], v[148:151], v[198:201], v[108:111]
	v_mfma_f32_16x16x32_bf16 v[104:107], v[164:167], v[198:201], v[104:107]
	v_mfma_f32_16x16x32_bf16 v[92:95], v[148:151], v[206:209], v[92:95]
	v_mfma_f32_16x16x32_bf16 v[88:91], v[164:167], v[206:209], v[88:91]
	v_mfma_f32_16x16x32_bf16 v[76:79], v[148:151], v[214:217], v[76:79]
	v_mfma_f32_16x16x32_bf16 v[72:75], v[164:167], v[214:217], v[72:75]
	v_mfma_f32_16x16x32_bf16 v[116:119], v[168:171], v[186:189], v[116:119]
	v_mfma_f32_16x16x32_bf16 v[112:115], v[176:179], v[186:189], v[112:115]
	v_mfma_f32_16x16x32_bf16 v[100:103], v[168:171], v[194:197], v[100:103]
	v_mfma_f32_16x16x32_bf16 v[96:99], v[176:179], v[194:197], v[96:99]
	v_mfma_f32_16x16x32_bf16 v[84:87], v[168:171], v[202:205], v[84:87]
	v_mfma_f32_16x16x32_bf16 v[80:83], v[176:179], v[202:205], v[80:83]
	v_mfma_f32_16x16x32_bf16 v[68:71], v[168:171], v[210:213], v[68:71]
	v_mfma_f32_16x16x32_bf16 v[64:67], v[176:179], v[210:213], v[64:67]
	v_mfma_f32_16x16x32_bf16 v[116:119], v[172:175], v[190:193], v[116:119]
	v_mfma_f32_16x16x32_bf16 v[112:115], v[180:183], v[190:193], v[112:115]
	v_mfma_f32_16x16x32_bf16 v[100:103], v[172:175], v[198:201], v[100:103]
	v_mfma_f32_16x16x32_bf16 v[96:99], v[180:183], v[198:201], v[96:99]
	v_mfma_f32_16x16x32_bf16 v[84:87], v[172:175], v[206:209], v[84:87]
	v_mfma_f32_16x16x32_bf16 v[80:83], v[180:183], v[206:209], v[80:83]
	v_mfma_f32_16x16x32_bf16 v[68:71], v[172:175], v[214:217], v[68:71]
	v_mfma_f32_16x16x32_bf16 v[64:67], v[180:183], v[214:217], v[64:67]
	s_barrier
	s_add_i32 s19, s72, s62
	v_lshl_add_u64 v[218:219], s[42:43], 0, v[130:131]
	s_mov_b32 m0, s19
	ds_read_b128 v[186:189], v157 offset:16384
	ds_read_b128 v[190:193], v157 offset:17408
	ds_read_b128 v[194:197], v157 offset:18432
	ds_read_b128 v[198:201], v157 offset:19456
	ds_read_b128 v[202:205], v157 offset:20480
	ds_read_b128 v[206:209], v157 offset:21504
	ds_read_b128 v[210:213], v157 offset:22528
	ds_read_b128 v[214:217], v157 offset:23552
	global_load_lds_dwordx4 v[218:219], off
	s_add_i32 m0, s19, 0x2000
	s_add_u32 s20, s42, 0x40000
	v_lshl_add_u64 v[220:221], s[42:43], 0, v[134:135]
	s_addc_u32 s21, s43, 0
	s_add_i32 s19, s73, s62
	global_load_lds_dwordx4 v[220:221], off
	v_lshl_add_u64 v[222:223], s[20:21], 0, v[130:131]
	s_mov_b32 m0, s19
	v_lshl_add_u64 v[224:225], s[88:89], 0, v[132:133]
	global_load_lds_dwordx4 v[222:223], off
	v_lshl_add_u64 v[222:223], s[20:21], 0, v[134:135]
	s_add_i32 m0, s19, 0x2000
	s_nop 0
	global_load_lds_dwordx4 v[222:223], off
	v_lshl_add_u64 v[222:223], s[88:89], 0, v[128:129]
	s_mov_b32 m0, s63
	s_nop 0
	global_load_lds_dwordx4 v[222:223], off
	s_mov_b32 m0, s64
	s_nop 0
	global_load_lds_dwordx4 v[224:225], off
	s_waitcnt vmcnt(8)
	s_waitcnt lgkmcnt(0)
	s_barrier
	s_waitcnt lgkmcnt(0)
	v_mfma_f32_16x16x32_bf16 v[60:63], v[144:147], v[186:189], v[60:63]
	v_mfma_f32_16x16x32_bf16 v[56:59], v[160:163], v[186:189], v[56:59]
	v_mfma_f32_16x16x32_bf16 v[44:47], v[144:147], v[194:197], v[44:47]
	v_mfma_f32_16x16x32_bf16 v[40:43], v[160:163], v[194:197], v[40:43]
	v_mfma_f32_16x16x32_bf16 v[28:31], v[144:147], v[202:205], v[28:31]
	v_mfma_f32_16x16x32_bf16 v[24:27], v[160:163], v[202:205], v[24:27]
	v_mfma_f32_16x16x32_bf16 v[12:15], v[144:147], v[210:213], v[12:15]
	v_mfma_f32_16x16x32_bf16 v[8:11], v[160:163], v[210:213], v[8:11]
	v_mfma_f32_16x16x32_bf16 v[60:63], v[148:151], v[190:193], v[60:63]
	v_mfma_f32_16x16x32_bf16 v[56:59], v[164:167], v[190:193], v[56:59]
	v_mfma_f32_16x16x32_bf16 v[44:47], v[148:151], v[198:201], v[44:47]
	v_mfma_f32_16x16x32_bf16 v[40:43], v[164:167], v[198:201], v[40:43]
	v_mfma_f32_16x16x32_bf16 v[28:31], v[148:151], v[206:209], v[28:31]
	v_mfma_f32_16x16x32_bf16 v[24:27], v[164:167], v[206:209], v[24:27]
	v_mfma_f32_16x16x32_bf16 v[12:15], v[148:151], v[214:217], v[12:15]
	v_mfma_f32_16x16x32_bf16 v[8:11], v[164:167], v[214:217], v[8:11]
	v_mfma_f32_16x16x32_bf16 v[52:55], v[168:171], v[186:189], v[52:55]
	v_mfma_f32_16x16x32_bf16 v[48:51], v[176:179], v[186:189], v[48:51]
	v_mfma_f32_16x16x32_bf16 v[36:39], v[168:171], v[194:197], v[36:39]
	v_mfma_f32_16x16x32_bf16 v[32:35], v[176:179], v[194:197], v[32:35]
	v_mfma_f32_16x16x32_bf16 v[20:23], v[168:171], v[202:205], v[20:23]
	v_mfma_f32_16x16x32_bf16 v[16:19], v[176:179], v[202:205], v[16:19]
	v_mfma_f32_16x16x32_bf16 v[4:7], v[168:171], v[210:213], v[4:7]
	v_mfma_f32_16x16x32_bf16 v[0:3], v[176:179], v[210:213], v[0:3]
	v_mfma_f32_16x16x32_bf16 v[52:55], v[172:175], v[190:193], v[52:55]
	v_mfma_f32_16x16x32_bf16 v[48:51], v[180:183], v[190:193], v[48:51]
	v_mfma_f32_16x16x32_bf16 v[36:39], v[172:175], v[198:201], v[36:39]
	v_mfma_f32_16x16x32_bf16 v[32:35], v[180:183], v[198:201], v[32:35]
	v_mfma_f32_16x16x32_bf16 v[20:23], v[172:175], v[206:209], v[20:23]
	v_mfma_f32_16x16x32_bf16 v[16:19], v[180:183], v[206:209], v[16:19]
	v_mfma_f32_16x16x32_bf16 v[4:7], v[172:175], v[214:217], v[4:7]
	v_mfma_f32_16x16x32_bf16 v[0:3], v[180:183], v[214:217], v[0:3]
	s_barrier
	s_add_i32 s19, 0, 0x18000
	v_add_u32_e32 v159, s19, v153
	s_add_i32 s22, 0, 0x1c000
	ds_read_b128 v[144:147], v159
	ds_read_b128 v[148:151], v159 offset:1024
	ds_read_b128 v[160:163], v159 offset:2048
	ds_read_b128 v[164:167], v159 offset:3072
	v_add_u32_e32 v159, s22, v153
	ds_read_b128 v[168:171], v159
	ds_read_b128 v[172:175], v159 offset:1024
	ds_read_b128 v[176:179], v159 offset:2048
	ds_read_b128 v[180:183], v159 offset:3072
	s_add_u32 s20, s88, 0x40000
	s_addc_u32 s21, s89, 0
	s_mov_b32 m0, s65
	v_lshl_add_u64 v[226:227], s[20:21], 0, v[128:129]
	ds_read_b128 v[186:189], v157 offset:32768
	ds_read_b128 v[190:193], v157 offset:33792
	ds_read_b128 v[194:197], v157 offset:34816
	ds_read_b128 v[198:201], v157 offset:35840
	ds_read_b128 v[202:205], v157 offset:36864
	ds_read_b128 v[206:209], v157 offset:37888
	ds_read_b128 v[210:213], v157 offset:38912
	ds_read_b128 v[214:217], v157 offset:39936
	global_load_lds_dwordx4 v[226:227], off
	v_lshl_add_u64 v[226:227], s[20:21], 0, v[132:133]
	s_mov_b32 m0, s66
	s_nop 0
	global_load_lds_dwordx4 v[226:227], off
	s_waitcnt vmcnt(8)
	s_waitcnt lgkmcnt(0)
	s_barrier
	s_waitcnt lgkmcnt(0)
	v_mfma_f32_16x16x32_bf16 v[124:127], v[144:147], v[186:189], v[124:127]
	v_mfma_f32_16x16x32_bf16 v[120:123], v[160:163], v[186:189], v[120:123]
	v_mfma_f32_16x16x32_bf16 v[108:111], v[144:147], v[194:197], v[108:111]
	v_mfma_f32_16x16x32_bf16 v[104:107], v[160:163], v[194:197], v[104:107]
	v_mfma_f32_16x16x32_bf16 v[92:95], v[144:147], v[202:205], v[92:95]
	v_mfma_f32_16x16x32_bf16 v[88:91], v[160:163], v[202:205], v[88:91]
	v_mfma_f32_16x16x32_bf16 v[76:79], v[144:147], v[210:213], v[76:79]
	v_mfma_f32_16x16x32_bf16 v[72:75], v[160:163], v[210:213], v[72:75]
	v_mfma_f32_16x16x32_bf16 v[124:127], v[148:151], v[190:193], v[124:127]
	v_mfma_f32_16x16x32_bf16 v[120:123], v[164:167], v[190:193], v[120:123]
	v_mfma_f32_16x16x32_bf16 v[108:111], v[148:151], v[198:201], v[108:111]
	v_mfma_f32_16x16x32_bf16 v[104:107], v[164:167], v[198:201], v[104:107]
	v_mfma_f32_16x16x32_bf16 v[92:95], v[148:151], v[206:209], v[92:95]
	v_mfma_f32_16x16x32_bf16 v[88:91], v[164:167], v[206:209], v[88:91]
	v_mfma_f32_16x16x32_bf16 v[76:79], v[148:151], v[214:217], v[76:79]
	v_mfma_f32_16x16x32_bf16 v[72:75], v[164:167], v[214:217], v[72:75]
	v_mfma_f32_16x16x32_bf16 v[116:119], v[168:171], v[186:189], v[116:119]
	v_mfma_f32_16x16x32_bf16 v[112:115], v[176:179], v[186:189], v[112:115]
	v_mfma_f32_16x16x32_bf16 v[100:103], v[168:171], v[194:197], v[100:103]
	v_mfma_f32_16x16x32_bf16 v[96:99], v[176:179], v[194:197], v[96:99]
	v_mfma_f32_16x16x32_bf16 v[84:87], v[168:171], v[202:205], v[84:87]
	v_mfma_f32_16x16x32_bf16 v[80:83], v[176:179], v[202:205], v[80:83]
	v_mfma_f32_16x16x32_bf16 v[68:71], v[168:171], v[210:213], v[68:71]
	v_mfma_f32_16x16x32_bf16 v[64:67], v[176:179], v[210:213], v[64:67]
	v_mfma_f32_16x16x32_bf16 v[116:119], v[172:175], v[190:193], v[116:119]
	v_mfma_f32_16x16x32_bf16 v[112:115], v[180:183], v[190:193], v[112:115]
	v_mfma_f32_16x16x32_bf16 v[100:103], v[172:175], v[198:201], v[100:103]
	v_mfma_f32_16x16x32_bf16 v[96:99], v[180:183], v[198:201], v[96:99]
	v_mfma_f32_16x16x32_bf16 v[84:87], v[172:175], v[206:209], v[84:87]
	v_mfma_f32_16x16x32_bf16 v[80:83], v[180:183], v[206:209], v[80:83]
	v_mfma_f32_16x16x32_bf16 v[68:71], v[172:175], v[214:217], v[68:71]
	v_mfma_f32_16x16x32_bf16 v[64:67], v[180:183], v[214:217], v[64:67]
	s_barrier
	s_add_i32 s19, s19, s62
	v_lshl_add_u64 v[218:219], v[218:219], 0, s[28:29]
	s_mov_b32 m0, s19
	ds_read_b128 v[186:189], v157 offset:49152
	ds_read_b128 v[190:193], v157 offset:50176
	ds_read_b128 v[194:197], v157 offset:51200
	ds_read_b128 v[198:201], v157 offset:52224
	ds_read_b128 v[202:205], v157 offset:53248
	ds_read_b128 v[206:209], v157 offset:54272
	ds_read_b128 v[210:213], v157 offset:55296
	ds_read_b128 v[214:217], v157 offset:56320
	global_load_lds_dwordx4 v[218:219], off
	s_add_i32 m0, s19, 0x2000
	s_add_u32 s20, s42, 0x40080
	v_lshl_add_u64 v[218:219], v[220:221], 0, s[28:29]
	s_addc_u32 s21, s43, 0
	s_add_i32 s19, s22, s62
	global_load_lds_dwordx4 v[218:219], off
	v_lshl_add_u64 v[218:219], s[20:21], 0, v[130:131]
	s_mov_b32 m0, s19
	s_nop 0
	global_load_lds_dwordx4 v[218:219], off
	v_lshl_add_u64 v[218:219], s[20:21], 0, v[134:135]
	s_add_i32 m0, s19, 0x2000
	s_nop 0
	global_load_lds_dwordx4 v[218:219], off
	v_lshl_add_u64 v[218:219], v[222:223], 0, s[28:29]
	s_mov_b32 m0, s70
	s_nop 0
	global_load_lds_dwordx4 v[218:219], off
	v_lshl_add_u64 v[218:219], v[224:225], 0, s[28:29]
	s_mov_b32 m0, s71
	s_nop 0
	global_load_lds_dwordx4 v[218:219], off
	s_waitcnt vmcnt(8)
	s_waitcnt lgkmcnt(0)
	s_barrier
	s_waitcnt lgkmcnt(0)
	v_mfma_f32_16x16x32_bf16 v[60:63], v[144:147], v[186:189], v[60:63]
	v_mfma_f32_16x16x32_bf16 v[56:59], v[160:163], v[186:189], v[56:59]
	v_mfma_f32_16x16x32_bf16 v[44:47], v[144:147], v[194:197], v[44:47]
	v_mfma_f32_16x16x32_bf16 v[40:43], v[160:163], v[194:197], v[40:43]
	v_mfma_f32_16x16x32_bf16 v[28:31], v[144:147], v[202:205], v[28:31]
	v_mfma_f32_16x16x32_bf16 v[24:27], v[160:163], v[202:205], v[24:27]
	v_mfma_f32_16x16x32_bf16 v[12:15], v[144:147], v[210:213], v[12:15]
	v_mfma_f32_16x16x32_bf16 v[8:11], v[160:163], v[210:213], v[8:11]
	v_mfma_f32_16x16x32_bf16 v[60:63], v[148:151], v[190:193], v[60:63]
	v_mfma_f32_16x16x32_bf16 v[56:59], v[164:167], v[190:193], v[56:59]
	v_mfma_f32_16x16x32_bf16 v[44:47], v[148:151], v[198:201], v[44:47]
	v_mfma_f32_16x16x32_bf16 v[40:43], v[164:167], v[198:201], v[40:43]
	v_mfma_f32_16x16x32_bf16 v[28:31], v[148:151], v[206:209], v[28:31]
	v_mfma_f32_16x16x32_bf16 v[24:27], v[164:167], v[206:209], v[24:27]
	v_mfma_f32_16x16x32_bf16 v[12:15], v[148:151], v[214:217], v[12:15]
	v_mfma_f32_16x16x32_bf16 v[8:11], v[164:167], v[214:217], v[8:11]
	v_mfma_f32_16x16x32_bf16 v[52:55], v[168:171], v[186:189], v[52:55]
	v_mfma_f32_16x16x32_bf16 v[48:51], v[176:179], v[186:189], v[48:51]
	v_mfma_f32_16x16x32_bf16 v[36:39], v[168:171], v[194:197], v[36:39]
	v_mfma_f32_16x16x32_bf16 v[32:35], v[176:179], v[194:197], v[32:35]
	v_mfma_f32_16x16x32_bf16 v[20:23], v[168:171], v[202:205], v[20:23]
	v_mfma_f32_16x16x32_bf16 v[16:19], v[176:179], v[202:205], v[16:19]
	v_mfma_f32_16x16x32_bf16 v[4:7], v[168:171], v[210:213], v[4:7]
	v_mfma_f32_16x16x32_bf16 v[0:3], v[176:179], v[210:213], v[0:3]
	v_mfma_f32_16x16x32_bf16 v[52:55], v[172:175], v[190:193], v[52:55]
	v_mfma_f32_16x16x32_bf16 v[48:51], v[180:183], v[190:193], v[48:51]
	v_mfma_f32_16x16x32_bf16 v[36:39], v[172:175], v[198:201], v[36:39]
	v_mfma_f32_16x16x32_bf16 v[32:35], v[180:183], v[198:201], v[32:35]
	v_mfma_f32_16x16x32_bf16 v[20:23], v[172:175], v[206:209], v[20:23]
	v_mfma_f32_16x16x32_bf16 v[16:19], v[180:183], v[206:209], v[16:19]
	v_mfma_f32_16x16x32_bf16 v[4:7], v[172:175], v[214:217], v[4:7]
	v_mfma_f32_16x16x32_bf16 v[0:3], v[180:183], v[214:217], v[0:3]
	s_barrier
	s_add_i32 s18, s18, 2
	s_add_u32 s6, s6, 0x100
	s_addc_u32 s7, s7, 0
	s_add_u32 s16, s16, 0x100
	s_addc_u32 s17, s17, 0
	s_cmp_gt_u32 s18, 13
	s_cbranch_scc0 .LBB0_546
	s_and_b64 vcc, exec, s[30:31]
	s_cbranch_vccz .LBB0_549
	s_barrier

.LBB0_860:
	s_add_u32 s17, s88, s90
	s_addc_u32 s20, s89, s91
	s_add_u32 s21, s17, 0x100
	s_addc_u32 s22, s20, 0
	s_and_b64 s[18:19], s[42:43], exec
	s_cselect_b32 s93, s39, s22
	s_cselect_b32 s92, s38, s21
	s_add_u32 s18, s80, s90
	s_addc_u32 s19, s81, s91
	s_add_u32 s21, s18, 0x100
	s_addc_u32 s22, s19, 0
	s_and_b64 s[18:19], s[42:43], exec
	s_cselect_b32 s95, s15, s22
	s_cselect_b32 s94, s16, s21
	s_add_u32 vcc_lo, s17, 0x40080
	ds_read_b128 v[36:39], v219
	ds_read_b128 v[40:43], v219 offset:1024
	ds_read_b128 v[44:47], v219 offset:2048
	ds_read_b128 v[52:55], v219 offset:3072
	ds_read_b128 v[60:63], v220
	ds_read_b128 v[64:67], v220 offset:1024
	ds_read_b128 v[68:71], v220 offset:2048
	ds_read_b128 v[84:87], v220 offset:3072
	s_addc_u32 vcc_hi, s20, 0
	s_add_i32 s74, s72, s63
	s_add_i32 m0, s41, 0xc000
	s_add_i32 s75, s41, 0xe000
	s_add_i32 s23, s74, 0x2000
	s_add_u32 s96, s94, 0x10000
	s_addc_u32 s97, s95, 0
	s_add_i32 s37, s73, s63
	s_add_i32 s35, s37, 0x2000
	s_add_i32 s22, 0, 0x18000
	s_add_i32 s21, 0, 0x1c000
	s_add_u32 s90, s92, 0x40000
	s_addc_u32 s91, s93, 0
	s_add_i32 s20, s22, s63
	s_add_i32 s18, s20, 0x2000
	s_add_u32 s42, s94, 0x10080
	s_addc_u32 s43, s95, 0
	s_add_i32 s19, s21, s63
	s_add_i32 s17, s19, 0x2000
	v_lshl_add_u64 v[206:207], vcc, 0, v[186:187]
	ds_read_b128 v[100:103], v221
	ds_read_b128 v[120:123], v221 offset:1024
	ds_read_b128 v[136:139], v221 offset:2048
	ds_read_b128 v[156:159], v221 offset:3072
	ds_read_b128 v[176:179], v221 offset:4096
	ds_read_b128 v[180:183], v221 offset:5120
	ds_read_b128 v[198:201], v221 offset:6144
	ds_read_b128 v[202:205], v221 offset:7168
	global_load_lds_dwordx4 v[206:207], off
	v_lshl_add_u64 v[206:207], vcc, 0, v[190:191]
	s_mov_b32 m0, s75
	s_nop 0
	global_load_lds_dwordx4 v[206:207], off
	s_waitcnt vmcnt(8)
	s_waitcnt lgkmcnt(0)
	s_barrier
	s_waitcnt lgkmcnt(0)
	v_mfma_f32_16x16x32_bf16 v[172:175], v[36:39], v[100:103], v[172:175]
	v_mfma_f32_16x16x32_bf16 v[164:167], v[44:47], v[100:103], v[164:167]
	v_mfma_f32_16x16x32_bf16 v[152:155], v[36:39], v[136:139], v[152:155]
	v_mfma_f32_16x16x32_bf16 v[144:147], v[44:47], v[136:139], v[144:147]
	v_mfma_f32_16x16x32_bf16 v[132:135], v[36:39], v[176:179], v[132:135]
	v_mfma_f32_16x16x32_bf16 v[124:127], v[44:47], v[176:179], v[124:127]
	v_mfma_f32_16x16x32_bf16 v[112:115], v[36:39], v[198:201], v[112:115]
	v_mfma_f32_16x16x32_bf16 v[104:107], v[44:47], v[198:201], v[104:107]
	v_mfma_f32_16x16x32_bf16 v[172:175], v[40:43], v[120:123], v[172:175]
	v_mfma_f32_16x16x32_bf16 v[164:167], v[52:55], v[120:123], v[164:167]
	v_mfma_f32_16x16x32_bf16 v[152:155], v[40:43], v[156:159], v[152:155]
	v_mfma_f32_16x16x32_bf16 v[144:147], v[52:55], v[156:159], v[144:147]
	v_mfma_f32_16x16x32_bf16 v[132:135], v[40:43], v[180:183], v[132:135]
	v_mfma_f32_16x16x32_bf16 v[124:127], v[52:55], v[180:183], v[124:127]
	v_mfma_f32_16x16x32_bf16 v[112:115], v[40:43], v[202:205], v[112:115]
	v_mfma_f32_16x16x32_bf16 v[104:107], v[52:55], v[202:205], v[104:107]
	v_mfma_f32_16x16x32_bf16 v[168:171], v[60:63], v[100:103], v[168:171]
	v_mfma_f32_16x16x32_bf16 v[100:103], v[68:71], v[100:103], v[160:163]
	v_mfma_f32_16x16x32_bf16 v[128:131], v[60:63], v[176:179], v[128:131]
	v_mfma_f32_16x16x32_bf16 v[116:119], v[68:71], v[176:179], v[116:119]
	v_mfma_f32_16x16x32_bf16 v[108:111], v[60:63], v[198:201], v[108:111]
	v_mfma_f32_16x16x32_bf16 v[96:99], v[68:71], v[198:201], v[96:99]
	v_mfma_f32_16x16x32_bf16 v[168:171], v[64:67], v[120:123], v[168:171]
	v_mfma_f32_16x16x32_bf16 v[100:103], v[84:87], v[120:123], v[100:103]
	v_mfma_f32_16x16x32_bf16 v[120:123], v[60:63], v[136:139], v[148:151]
	v_mfma_f32_16x16x32_bf16 v[136:139], v[68:71], v[136:139], v[140:143]
	v_mfma_f32_16x16x32_bf16 v[128:131], v[64:67], v[180:183], v[128:131]
	v_mfma_f32_16x16x32_bf16 v[116:119], v[84:87], v[180:183], v[116:119]
	v_mfma_f32_16x16x32_bf16 v[108:111], v[64:67], v[202:205], v[108:111]
	v_mfma_f32_16x16x32_bf16 v[96:99], v[84:87], v[202:205], v[96:99]
	v_mfma_f32_16x16x32_bf16 v[120:123], v[64:67], v[156:159], v[120:123]
	v_mfma_f32_16x16x32_bf16 v[136:139], v[84:87], v[156:159], v[136:139]
	s_barrier
	s_mov_b32 m0, s74
	v_lshl_add_u64 v[214:215], s[94:95], 0, v[188:189]
	ds_read_b128 v[140:143], v221 offset:16384
	ds_read_b128 v[148:151], v221 offset:17408
	ds_read_b128 v[156:159], v221 offset:18432
	ds_read_b128 v[160:163], v221 offset:19456
	ds_read_b128 v[176:179], v221 offset:20480
	ds_read_b128 v[180:183], v221 offset:21504
	ds_read_b128 v[198:201], v221 offset:22528
	ds_read_b128 v[202:205], v221 offset:23552
	global_load_lds_dwordx4 v[214:215], off
	v_lshl_add_u64 v[222:223], s[94:95], 0, v[192:193]
	s_mov_b32 m0, s23
	v_lshl_add_u64 v[206:207], s[96:97], 0, v[188:189]
	global_load_lds_dwordx4 v[222:223], off
	s_mov_b32 m0, s37
	v_lshl_add_u64 v[224:225], s[92:93], 0, v[186:187]
	global_load_lds_dwordx4 v[206:207], off
	v_lshl_add_u64 v[206:207], s[96:97], 0, v[192:193]
	s_mov_b32 m0, s35
	v_lshl_add_u64 v[226:227], s[92:93], 0, v[190:191]
	global_load_lds_dwordx4 v[206:207], off
	s_mov_b32 m0, s41
	s_nop 0
	global_load_lds_dwordx4 v[224:225], off
	s_mov_b32 m0, s64
	s_nop 0
	global_load_lds_dwordx4 v[226:227], off
	s_waitcnt vmcnt(8)
	s_waitcnt lgkmcnt(0)
	s_barrier
	s_waitcnt lgkmcnt(0)
	v_mfma_f32_16x16x32_bf16 v[92:95], v[36:39], v[140:143], v[92:95]
	v_mfma_f32_16x16x32_bf16 v[80:83], v[44:47], v[140:143], v[80:83]
	v_mfma_f32_16x16x32_bf16 v[72:75], v[36:39], v[156:159], v[72:75]
	v_mfma_f32_16x16x32_bf16 v[48:51], v[44:47], v[156:159], v[48:51]
	v_mfma_f32_16x16x32_bf16 v[28:31], v[36:39], v[176:179], v[28:31]
	v_mfma_f32_16x16x32_bf16 v[20:23], v[44:47], v[176:179], v[20:23]
	v_mfma_f32_16x16x32_bf16 v[12:15], v[36:39], v[198:201], v[12:15]
	v_mfma_f32_16x16x32_bf16 v[4:7], v[44:47], v[198:201], v[4:7]
	v_mfma_f32_16x16x32_bf16 v[92:95], v[40:43], v[148:151], v[92:95]
	v_mfma_f32_16x16x32_bf16 v[80:83], v[52:55], v[148:151], v[80:83]
	v_mfma_f32_16x16x32_bf16 v[72:75], v[40:43], v[160:163], v[72:75]
	v_mfma_f32_16x16x32_bf16 v[48:51], v[52:55], v[160:163], v[48:51]
	v_mfma_f32_16x16x32_bf16 v[28:31], v[40:43], v[180:183], v[28:31]
	v_mfma_f32_16x16x32_bf16 v[20:23], v[52:55], v[180:183], v[20:23]
	v_mfma_f32_16x16x32_bf16 v[12:15], v[40:43], v[202:205], v[12:15]
	v_mfma_f32_16x16x32_bf16 v[4:7], v[52:55], v[202:205], v[4:7]
	v_mfma_f32_16x16x32_bf16 v[32:35], v[68:71], v[156:159], v[32:35]
	v_mfma_f32_16x16x32_bf16 v[24:27], v[60:63], v[176:179], v[24:27]
	v_mfma_f32_16x16x32_bf16 v[16:19], v[68:71], v[176:179], v[16:19]
	v_mfma_f32_16x16x32_bf16 v[8:11], v[60:63], v[198:201], v[8:11]
	v_mfma_f32_16x16x32_bf16 v[0:3], v[68:71], v[198:201], v[0:3]
	v_mfma_f32_16x16x32_bf16 v[36:39], v[60:63], v[140:143], v[88:91]
	v_mfma_f32_16x16x32_bf16 v[40:43], v[68:71], v[140:143], v[76:79]
	v_mfma_f32_16x16x32_bf16 v[44:47], v[60:63], v[156:159], v[56:59]
	v_mfma_f32_16x16x32_bf16 v[32:35], v[84:87], v[160:163], v[32:35]
	v_mfma_f32_16x16x32_bf16 v[24:27], v[64:67], v[180:183], v[24:27]
	v_mfma_f32_16x16x32_bf16 v[16:19], v[84:87], v[180:183], v[16:19]
	v_mfma_f32_16x16x32_bf16 v[8:11], v[64:67], v[202:205], v[8:11]
	v_mfma_f32_16x16x32_bf16 v[0:3], v[84:87], v[202:205], v[0:3]
	v_mfma_f32_16x16x32_bf16 v[36:39], v[64:67], v[148:151], v[36:39]
	v_mfma_f32_16x16x32_bf16 v[40:43], v[84:87], v[148:151], v[40:43]
	v_mfma_f32_16x16x32_bf16 v[44:47], v[64:67], v[160:163], v[44:47]
	s_barrier
	v_add_u32_e32 v64, s22, v217
	v_add_u32_e32 v76, s21, v217
	ds_read_b128 v[52:55], v64
	ds_read_b128 v[56:59], v64 offset:1024
	ds_read_b128 v[60:63], v64 offset:2048
	ds_read_b128 v[64:67], v64 offset:3072
	ds_read_b128 v[68:71], v76
	ds_read_b128 v[84:87], v76 offset:1024
	ds_read_b128 v[156:159], v76 offset:2048
	ds_read_b128 v[176:179], v76 offset:3072
	s_mov_b32 m0, s65
	v_lshl_add_u64 v[148:149], s[90:91], 0, v[186:187]
	ds_read_b128 v[76:79], v221 offset:32768
	ds_read_b128 v[88:91], v221 offset:33792
	ds_read_b128 v[140:143], v221 offset:34816
	ds_read_b128 v[180:183], v221 offset:35840
	ds_read_b128 v[198:201], v221 offset:36864
	ds_read_b128 v[202:205], v221 offset:37888
	ds_read_b128 v[206:209], v221 offset:38912
	ds_read_b128 v[210:213], v221 offset:39936
	global_load_lds_dwordx4 v[148:149], off
	v_lshl_add_u64 v[148:149], s[90:91], 0, v[190:191]
	s_mov_b32 m0, s66
	s_nop 0
	global_load_lds_dwordx4 v[148:149], off
	s_waitcnt vmcnt(8)
	s_waitcnt lgkmcnt(0)
	s_barrier
	s_waitcnt lgkmcnt(0)
	v_mfma_f32_16x16x32_bf16 v[148:151], v[52:55], v[76:79], v[172:175]
	v_mfma_f32_16x16x32_bf16 v[172:175], v[56:59], v[88:91], v[148:151]
	v_mfma_f32_16x16x32_bf16 v[148:151], v[60:63], v[76:79], v[164:167]
	v_mfma_f32_16x16x32_bf16 v[164:167], v[64:67], v[88:91], v[148:151]
	v_mfma_f32_16x16x32_bf16 v[148:151], v[52:55], v[140:143], v[152:155]
	v_mfma_f32_16x16x32_bf16 v[144:147], v[60:63], v[140:143], v[144:147]
	v_mfma_f32_16x16x32_bf16 v[132:135], v[52:55], v[198:201], v[132:135]
	v_mfma_f32_16x16x32_bf16 v[124:127], v[60:63], v[198:201], v[124:127]
	v_mfma_f32_16x16x32_bf16 v[112:115], v[52:55], v[206:209], v[112:115]
	v_mfma_f32_16x16x32_bf16 v[104:107], v[60:63], v[206:209], v[104:107]
	v_mfma_f32_16x16x32_bf16 v[152:155], v[56:59], v[180:183], v[148:151]
	v_mfma_f32_16x16x32_bf16 v[144:147], v[64:67], v[180:183], v[144:147]
	v_mfma_f32_16x16x32_bf16 v[132:135], v[56:59], v[202:205], v[132:135]
	v_mfma_f32_16x16x32_bf16 v[124:127], v[64:67], v[202:205], v[124:127]
	v_mfma_f32_16x16x32_bf16 v[112:115], v[56:59], v[210:213], v[112:115]
	v_mfma_f32_16x16x32_bf16 v[104:107], v[64:67], v[210:213], v[104:107]
	v_mfma_f32_16x16x32_bf16 v[148:151], v[68:71], v[76:79], v[168:171]
	v_mfma_f32_16x16x32_bf16 v[76:79], v[156:159], v[76:79], v[100:103]
	v_mfma_f32_16x16x32_bf16 v[160:163], v[176:179], v[88:91], v[76:79]
	v_mfma_f32_16x16x32_bf16 v[76:79], v[68:71], v[140:143], v[120:123]
	v_mfma_f32_16x16x32_bf16 v[168:171], v[84:87], v[88:91], v[148:151]
	v_mfma_f32_16x16x32_bf16 v[148:151], v[84:87], v[180:183], v[76:79]
	v_mfma_f32_16x16x32_bf16 v[76:79], v[156:159], v[140:143], v[136:139]
	v_mfma_f32_16x16x32_bf16 v[140:143], v[176:179], v[180:183], v[76:79]
	v_mfma_f32_16x16x32_bf16 v[76:79], v[68:71], v[198:201], v[128:131]
	v_mfma_f32_16x16x32_bf16 v[128:131], v[84:87], v[202:205], v[76:79]
	v_mfma_f32_16x16x32_bf16 v[76:79], v[156:159], v[198:201], v[116:119]
	v_mfma_f32_16x16x32_bf16 v[116:119], v[176:179], v[202:205], v[76:79]
	v_mfma_f32_16x16x32_bf16 v[76:79], v[68:71], v[206:209], v[108:111]
	v_mfma_f32_16x16x32_bf16 v[108:111], v[84:87], v[210:213], v[76:79]
	v_mfma_f32_16x16x32_bf16 v[76:79], v[156:159], v[206:209], v[96:99]
	v_mfma_f32_16x16x32_bf16 v[96:99], v[176:179], v[210:213], v[76:79]
	s_barrier
	s_mov_b32 m0, s20
	v_lshl_add_u64 v[88:89], v[214:215], 0, s[28:29]
	s_nop 2
	ds_read_b128 v[76:79], v221 offset:49152
	ds_read_b128 v[100:103], v221 offset:50176
	ds_read_b128 v[120:123], v221 offset:51200
	ds_read_b128 v[136:139], v221 offset:52224
	ds_read_b128 v[180:183], v221 offset:53248
	ds_read_b128 v[198:201], v221 offset:54272
	ds_read_b128 v[202:205], v221 offset:55296
	ds_read_b128 v[206:209], v221 offset:56320
	global_load_lds_dwordx4 v[88:89], off
	v_lshl_add_u64 v[88:89], v[222:223], 0, s[28:29]
	s_mov_b32 m0, s18
	s_nop 0
	global_load_lds_dwordx4 v[88:89], off
	v_lshl_add_u64 v[88:89], s[42:43], 0, v[188:189]
	s_mov_b32 m0, s19
	s_nop 0
	global_load_lds_dwordx4 v[88:89], off
	v_lshl_add_u64 v[88:89], s[42:43], 0, v[192:193]
	s_mov_b32 m0, s17
	s_nop 0
	global_load_lds_dwordx4 v[88:89], off
	v_lshl_add_u64 v[88:89], v[224:225], 0, s[28:29]
	s_mov_b32 m0, s70
	s_nop 0
	global_load_lds_dwordx4 v[88:89], off
	v_lshl_add_u64 v[88:89], v[226:227], 0, s[28:29]
	s_mov_b32 m0, s71
	s_nop 0
	global_load_lds_dwordx4 v[88:89], off
	s_waitcnt vmcnt(8)
	s_waitcnt lgkmcnt(0)
	s_barrier
	s_waitcnt lgkmcnt(0)
	v_mfma_f32_16x16x32_bf16 v[88:91], v[52:55], v[76:79], v[92:95]
	v_mfma_f32_16x16x32_bf16 v[80:83], v[60:63], v[76:79], v[80:83]
	v_mfma_f32_16x16x32_bf16 v[72:75], v[52:55], v[120:123], v[72:75]
	v_mfma_f32_16x16x32_bf16 v[48:51], v[60:63], v[120:123], v[48:51]
	v_mfma_f32_16x16x32_bf16 v[28:31], v[52:55], v[180:183], v[28:31]
	v_mfma_f32_16x16x32_bf16 v[20:23], v[60:63], v[180:183], v[20:23]
	v_mfma_f32_16x16x32_bf16 v[12:15], v[52:55], v[202:205], v[12:15]
	v_mfma_f32_16x16x32_bf16 v[4:7], v[60:63], v[202:205], v[4:7]
	v_mfma_f32_16x16x32_bf16 v[92:95], v[56:59], v[100:103], v[88:91]
	v_mfma_f32_16x16x32_bf16 v[80:83], v[64:67], v[100:103], v[80:83]
	v_mfma_f32_16x16x32_bf16 v[72:75], v[56:59], v[136:139], v[72:75]
	v_mfma_f32_16x16x32_bf16 v[48:51], v[64:67], v[136:139], v[48:51]
	v_mfma_f32_16x16x32_bf16 v[28:31], v[56:59], v[198:201], v[28:31]
	v_mfma_f32_16x16x32_bf16 v[20:23], v[64:67], v[198:201], v[20:23]
	v_mfma_f32_16x16x32_bf16 v[12:15], v[56:59], v[206:209], v[12:15]
	v_mfma_f32_16x16x32_bf16 v[4:7], v[64:67], v[206:209], v[4:7]
	v_mfma_f32_16x16x32_bf16 v[36:39], v[68:71], v[76:79], v[36:39]
	v_mfma_f32_16x16x32_bf16 v[88:91], v[84:87], v[100:103], v[36:39]
	v_mfma_f32_16x16x32_bf16 v[36:39], v[156:159], v[76:79], v[40:43]
	v_mfma_f32_16x16x32_bf16 v[76:79], v[176:179], v[100:103], v[36:39]
	v_mfma_f32_16x16x32_bf16 v[36:39], v[68:71], v[120:123], v[44:47]
	v_mfma_f32_16x16x32_bf16 v[32:35], v[156:159], v[120:123], v[32:35]
	v_mfma_f32_16x16x32_bf16 v[24:27], v[68:71], v[180:183], v[24:27]
	v_mfma_f32_16x16x32_bf16 v[16:19], v[156:159], v[180:183], v[16:19]
	v_mfma_f32_16x16x32_bf16 v[8:11], v[68:71], v[202:205], v[8:11]
	v_mfma_f32_16x16x32_bf16 v[0:3], v[156:159], v[202:205], v[0:3]
	v_mfma_f32_16x16x32_bf16 v[56:59], v[84:87], v[136:139], v[36:39]
	v_mfma_f32_16x16x32_bf16 v[32:35], v[176:179], v[136:139], v[32:35]
	v_mfma_f32_16x16x32_bf16 v[24:27], v[84:87], v[198:201], v[24:27]
	v_mfma_f32_16x16x32_bf16 v[16:19], v[176:179], v[198:201], v[16:19]
	v_mfma_f32_16x16x32_bf16 v[8:11], v[84:87], v[206:209], v[8:11]
	v_mfma_f32_16x16x32_bf16 v[0:3], v[176:179], v[206:209], v[0:3]
	s_barrier
	s_andn2_b64 vcc, exec, s[0:1]
	s_mov_b64 s[42:43], -1
	s_mov_b64 s[0:1], 0
	s_mov_b64 s[90:91], 0x100
	s_cbranch_vccz .LBB0_860
	s_and_b64 vcc, exec, s[30:31]
	s_cbranch_vccz .LBB0_863
	s_barrier

.LBB0_1026:
	ds_read_b128 v[128:131], v189
	ds_read_b128 v[132:135], v189 offset:1024
	ds_read_b128 v[136:139], v189 offset:2048
	ds_read_b128 v[140:143], v189 offset:3072
	ds_read_b128 v[144:147], v190
	ds_read_b128 v[148:151], v190 offset:1024
	ds_read_b128 v[172:175], v190 offset:2048
	ds_read_b128 v[176:179], v190 offset:3072
	s_add_u32 s42, s40, 0xfffc0080
	s_addc_u32 s43, s41, -1
	s_cmp_eq_u32 s72, 12
	s_cselect_b32 s63, s27, s43
	s_cselect_b32 s62, s37, s42
	s_cselect_b32 s43, s29, s71
	s_cselect_b32 s42, s39, s70
	v_lshl_add_u64 v[222:223], s[40:41], 0, v[164:165]
	s_add_i32 m0, s18, 0xc000
	ds_read_b128 v[180:183], v191
	ds_read_b128 v[194:197], v191 offset:1024
	ds_read_b128 v[198:201], v191 offset:2048
	ds_read_b128 v[202:205], v191 offset:3072
	ds_read_b128 v[206:209], v191 offset:4096
	ds_read_b128 v[210:213], v191 offset:5120
	ds_read_b128 v[214:217], v191 offset:6144
	ds_read_b128 v[218:221], v191 offset:7168
	global_load_lds_dwordx4 v[222:223], off
	v_lshl_add_u64 v[222:223], s[40:41], 0, v[166:167]
	s_add_i32 m0, s18, 0xe000
	s_nop 0
	global_load_lds_dwordx4 v[222:223], off
	s_waitcnt vmcnt(8)
	s_waitcnt lgkmcnt(0)
	s_barrier
	s_waitcnt lgkmcnt(0)
	v_mfma_f32_16x16x32_bf16 v[124:127], v[128:131], v[180:183], v[124:127]
	v_mfma_f32_16x16x32_bf16 v[120:123], v[136:139], v[180:183], v[120:123]
	v_mfma_f32_16x16x32_bf16 v[108:111], v[128:131], v[198:201], v[108:111]
	v_mfma_f32_16x16x32_bf16 v[104:107], v[136:139], v[198:201], v[104:107]
	v_mfma_f32_16x16x32_bf16 v[92:95], v[128:131], v[206:209], v[92:95]
	v_mfma_f32_16x16x32_bf16 v[88:91], v[136:139], v[206:209], v[88:91]
	v_mfma_f32_16x16x32_bf16 v[76:79], v[128:131], v[214:217], v[76:79]
	v_mfma_f32_16x16x32_bf16 v[72:75], v[136:139], v[214:217], v[72:75]
	v_mfma_f32_16x16x32_bf16 v[124:127], v[132:135], v[194:197], v[124:127]
	v_mfma_f32_16x16x32_bf16 v[120:123], v[140:143], v[194:197], v[120:123]
	v_mfma_f32_16x16x32_bf16 v[108:111], v[132:135], v[202:205], v[108:111]
	v_mfma_f32_16x16x32_bf16 v[104:107], v[140:143], v[202:205], v[104:107]
	v_mfma_f32_16x16x32_bf16 v[92:95], v[132:135], v[210:213], v[92:95]
	v_mfma_f32_16x16x32_bf16 v[88:91], v[140:143], v[210:213], v[88:91]
	v_mfma_f32_16x16x32_bf16 v[76:79], v[132:135], v[218:221], v[76:79]
	v_mfma_f32_16x16x32_bf16 v[72:75], v[140:143], v[218:221], v[72:75]
	v_mfma_f32_16x16x32_bf16 v[116:119], v[144:147], v[180:183], v[116:119]
	v_mfma_f32_16x16x32_bf16 v[112:115], v[172:175], v[180:183], v[112:115]
	v_mfma_f32_16x16x32_bf16 v[100:103], v[144:147], v[198:201], v[100:103]
	v_mfma_f32_16x16x32_bf16 v[96:99], v[172:175], v[198:201], v[96:99]
	v_mfma_f32_16x16x32_bf16 v[84:87], v[144:147], v[206:209], v[84:87]
	v_mfma_f32_16x16x32_bf16 v[80:83], v[172:175], v[206:209], v[80:83]
	v_mfma_f32_16x16x32_bf16 v[68:71], v[144:147], v[214:217], v[68:71]
	v_mfma_f32_16x16x32_bf16 v[64:67], v[172:175], v[214:217], v[64:67]
	v_mfma_f32_16x16x32_bf16 v[116:119], v[148:151], v[194:197], v[116:119]
	v_mfma_f32_16x16x32_bf16 v[112:115], v[176:179], v[194:197], v[112:115]
	v_mfma_f32_16x16x32_bf16 v[100:103], v[148:151], v[202:205], v[100:103]
	v_mfma_f32_16x16x32_bf16 v[96:99], v[176:179], v[202:205], v[96:99]
	v_mfma_f32_16x16x32_bf16 v[84:87], v[148:151], v[210:213], v[84:87]
	v_mfma_f32_16x16x32_bf16 v[80:83], v[176:179], v[210:213], v[80:83]
	v_mfma_f32_16x16x32_bf16 v[68:71], v[148:151], v[218:221], v[68:71]
	v_mfma_f32_16x16x32_bf16 v[64:67], v[176:179], v[218:221], v[64:67]
	s_barrier
	s_add_i32 s73, s66, s17
	v_lshl_add_u64 v[222:223], s[42:43], 0, v[154:155]
	s_mov_b32 m0, s73
	ds_read_b128 v[180:183], v191 offset:16384
	ds_read_b128 v[194:197], v191 offset:17408
	ds_read_b128 v[198:201], v191 offset:18432
	ds_read_b128 v[202:205], v191 offset:19456
	ds_read_b128 v[206:209], v191 offset:20480
	ds_read_b128 v[210:213], v191 offset:21504
	ds_read_b128 v[214:217], v191 offset:22528
	ds_read_b128 v[218:221], v191 offset:23552
	global_load_lds_dwordx4 v[222:223], off
	s_add_i32 m0, s73, 0x2000
	s_add_u32 s74, s42, 0x40000
	v_lshl_add_u64 v[224:225], s[42:43], 0, v[158:159]
	s_addc_u32 s75, s43, 0
	s_add_i32 s73, s67, s17
	global_load_lds_dwordx4 v[224:225], off
	v_lshl_add_u64 v[226:227], s[74:75], 0, v[154:155]
	s_mov_b32 m0, s73
	v_lshl_add_u64 v[228:229], s[62:63], 0, v[156:157]
	global_load_lds_dwordx4 v[226:227], off
	v_lshl_add_u64 v[226:227], s[74:75], 0, v[158:159]
	s_add_i32 m0, s73, 0x2000
	s_nop 0
	global_load_lds_dwordx4 v[226:227], off
	v_lshl_add_u64 v[226:227], s[62:63], 0, v[152:153]
	s_mov_b32 m0, s18
	s_nop 0
	global_load_lds_dwordx4 v[226:227], off
	s_mov_b32 m0, s19
	s_nop 0
	global_load_lds_dwordx4 v[228:229], off
	s_waitcnt vmcnt(8)
	s_waitcnt lgkmcnt(0)
	s_barrier
	s_waitcnt lgkmcnt(0)
	v_mfma_f32_16x16x32_bf16 v[60:63], v[128:131], v[180:183], v[60:63]
	v_mfma_f32_16x16x32_bf16 v[56:59], v[136:139], v[180:183], v[56:59]
	v_mfma_f32_16x16x32_bf16 v[44:47], v[128:131], v[198:201], v[44:47]
	v_mfma_f32_16x16x32_bf16 v[40:43], v[136:139], v[198:201], v[40:43]
	v_mfma_f32_16x16x32_bf16 v[28:31], v[128:131], v[206:209], v[28:31]
	v_mfma_f32_16x16x32_bf16 v[24:27], v[136:139], v[206:209], v[24:27]
	v_mfma_f32_16x16x32_bf16 v[12:15], v[128:131], v[214:217], v[12:15]
	v_mfma_f32_16x16x32_bf16 v[8:11], v[136:139], v[214:217], v[8:11]
	v_mfma_f32_16x16x32_bf16 v[60:63], v[132:135], v[194:197], v[60:63]
	v_mfma_f32_16x16x32_bf16 v[56:59], v[140:143], v[194:197], v[56:59]
	v_mfma_f32_16x16x32_bf16 v[44:47], v[132:135], v[202:205], v[44:47]
	v_mfma_f32_16x16x32_bf16 v[40:43], v[140:143], v[202:205], v[40:43]
	v_mfma_f32_16x16x32_bf16 v[28:31], v[132:135], v[210:213], v[28:31]
	v_mfma_f32_16x16x32_bf16 v[24:27], v[140:143], v[210:213], v[24:27]
	v_mfma_f32_16x16x32_bf16 v[12:15], v[132:135], v[218:221], v[12:15]
	v_mfma_f32_16x16x32_bf16 v[8:11], v[140:143], v[218:221], v[8:11]
	v_mfma_f32_16x16x32_bf16 v[52:55], v[144:147], v[180:183], v[52:55]
	v_mfma_f32_16x16x32_bf16 v[48:51], v[172:175], v[180:183], v[48:51]
	v_mfma_f32_16x16x32_bf16 v[36:39], v[144:147], v[198:201], v[36:39]
	v_mfma_f32_16x16x32_bf16 v[32:35], v[172:175], v[198:201], v[32:35]
	v_mfma_f32_16x16x32_bf16 v[20:23], v[144:147], v[206:209], v[20:23]
	v_mfma_f32_16x16x32_bf16 v[16:19], v[172:175], v[206:209], v[16:19]
	v_mfma_f32_16x16x32_bf16 v[4:7], v[144:147], v[214:217], v[4:7]
	v_mfma_f32_16x16x32_bf16 v[0:3], v[172:175], v[214:217], v[0:3]
	v_mfma_f32_16x16x32_bf16 v[52:55], v[148:151], v[194:197], v[52:55]
	v_mfma_f32_16x16x32_bf16 v[48:51], v[176:179], v[194:197], v[48:51]
	v_mfma_f32_16x16x32_bf16 v[36:39], v[148:151], v[202:205], v[36:39]
	v_mfma_f32_16x16x32_bf16 v[32:35], v[176:179], v[202:205], v[32:35]
	v_mfma_f32_16x16x32_bf16 v[20:23], v[148:151], v[210:213], v[20:23]
	v_mfma_f32_16x16x32_bf16 v[16:19], v[176:179], v[210:213], v[16:19]
	v_mfma_f32_16x16x32_bf16 v[4:7], v[148:151], v[218:221], v[4:7]
	v_mfma_f32_16x16x32_bf16 v[0:3], v[176:179], v[218:221], v[0:3]
	s_barrier
	s_add_i32 s73, 0, 0x18000
	s_add_i32 s74, 0, 0x1c000
	v_add_u32_e32 v140, s73, v186
	v_add_u32_e32 v176, s74, v186
	ds_read_b128 v[128:131], v140
	ds_read_b128 v[132:135], v140 offset:1024
	ds_read_b128 v[136:139], v140 offset:2048
	ds_read_b128 v[140:143], v140 offset:3072
	ds_read_b128 v[144:147], v176
	ds_read_b128 v[148:151], v176 offset:1024
	ds_read_b128 v[172:175], v176 offset:2048
	ds_read_b128 v[176:179], v176 offset:3072
	s_add_u32 s62, s62, 0x40000
	s_addc_u32 s63, s63, 0
	s_mov_b32 m0, s20
	v_lshl_add_u64 v[230:231], s[62:63], 0, v[152:153]
	ds_read_b128 v[180:183], v191 offset:32768
	ds_read_b128 v[194:197], v191 offset:33792
	ds_read_b128 v[198:201], v191 offset:34816
	ds_read_b128 v[202:205], v191 offset:35840
	ds_read_b128 v[206:209], v191 offset:36864
	ds_read_b128 v[210:213], v191 offset:37888
	ds_read_b128 v[214:217], v191 offset:38912
	ds_read_b128 v[218:221], v191 offset:39936
	global_load_lds_dwordx4 v[230:231], off
	v_lshl_add_u64 v[230:231], s[62:63], 0, v[156:157]
	s_mov_b32 m0, s21
	s_nop 0
	global_load_lds_dwordx4 v[230:231], off
	s_waitcnt vmcnt(8)
	s_waitcnt lgkmcnt(0)
	s_barrier
	s_waitcnt lgkmcnt(0)
	v_mfma_f32_16x16x32_bf16 v[124:127], v[128:131], v[180:183], v[124:127]
	v_mfma_f32_16x16x32_bf16 v[120:123], v[136:139], v[180:183], v[120:123]
	v_mfma_f32_16x16x32_bf16 v[108:111], v[128:131], v[198:201], v[108:111]
	v_mfma_f32_16x16x32_bf16 v[104:107], v[136:139], v[198:201], v[104:107]
	v_mfma_f32_16x16x32_bf16 v[92:95], v[128:131], v[206:209], v[92:95]
	v_mfma_f32_16x16x32_bf16 v[88:91], v[136:139], v[206:209], v[88:91]
	v_mfma_f32_16x16x32_bf16 v[76:79], v[128:131], v[214:217], v[76:79]
	v_mfma_f32_16x16x32_bf16 v[72:75], v[136:139], v[214:217], v[72:75]
	v_mfma_f32_16x16x32_bf16 v[124:127], v[132:135], v[194:197], v[124:127]
	v_mfma_f32_16x16x32_bf16 v[120:123], v[140:143], v[194:197], v[120:123]
	v_mfma_f32_16x16x32_bf16 v[108:111], v[132:135], v[202:205], v[108:111]
	v_mfma_f32_16x16x32_bf16 v[104:107], v[140:143], v[202:205], v[104:107]
	v_mfma_f32_16x16x32_bf16 v[92:95], v[132:135], v[210:213], v[92:95]
	v_mfma_f32_16x16x32_bf16 v[88:91], v[140:143], v[210:213], v[88:91]
	v_mfma_f32_16x16x32_bf16 v[76:79], v[132:135], v[218:221], v[76:79]
	v_mfma_f32_16x16x32_bf16 v[72:75], v[140:143], v[218:221], v[72:75]
	v_mfma_f32_16x16x32_bf16 v[116:119], v[144:147], v[180:183], v[116:119]
	v_mfma_f32_16x16x32_bf16 v[112:115], v[172:175], v[180:183], v[112:115]
	v_mfma_f32_16x16x32_bf16 v[100:103], v[144:147], v[198:201], v[100:103]
	v_mfma_f32_16x16x32_bf16 v[96:99], v[172:175], v[198:201], v[96:99]
	v_mfma_f32_16x16x32_bf16 v[84:87], v[144:147], v[206:209], v[84:87]
	v_mfma_f32_16x16x32_bf16 v[80:83], v[172:175], v[206:209], v[80:83]
	v_mfma_f32_16x16x32_bf16 v[68:71], v[144:147], v[214:217], v[68:71]
	v_mfma_f32_16x16x32_bf16 v[64:67], v[172:175], v[214:217], v[64:67]
	v_mfma_f32_16x16x32_bf16 v[116:119], v[148:151], v[194:197], v[116:119]
	v_mfma_f32_16x16x32_bf16 v[112:115], v[176:179], v[194:197], v[112:115]
	v_mfma_f32_16x16x32_bf16 v[100:103], v[148:151], v[202:205], v[100:103]
	v_mfma_f32_16x16x32_bf16 v[96:99], v[176:179], v[202:205], v[96:99]
	v_mfma_f32_16x16x32_bf16 v[84:87], v[148:151], v[210:213], v[84:87]
	v_mfma_f32_16x16x32_bf16 v[80:83], v[176:179], v[210:213], v[80:83]
	v_mfma_f32_16x16x32_bf16 v[68:71], v[148:151], v[218:221], v[68:71]
	v_mfma_f32_16x16x32_bf16 v[64:67], v[176:179], v[218:221], v[64:67]
	s_barrier
	s_add_i32 s62, s73, s17
	v_lshl_add_u64 v[222:223], v[222:223], 0, s[12:13]
	s_mov_b32 m0, s62
	ds_read_b128 v[180:183], v191 offset:49152
	ds_read_b128 v[194:197], v191 offset:50176
	ds_read_b128 v[198:201], v191 offset:51200
	ds_read_b128 v[202:205], v191 offset:52224
	ds_read_b128 v[206:209], v191 offset:53248
	ds_read_b128 v[210:213], v191 offset:54272
	ds_read_b128 v[214:217], v191 offset:55296
	ds_read_b128 v[218:221], v191 offset:56320
	global_load_lds_dwordx4 v[222:223], off
	s_add_i32 m0, s62, 0x2000
	s_add_u32 s42, s42, 0x40080
	v_lshl_add_u64 v[222:223], v[224:225], 0, s[12:13]
	s_addc_u32 s43, s43, 0
	s_add_i32 s62, s74, s17
	global_load_lds_dwordx4 v[222:223], off
	v_lshl_add_u64 v[222:223], s[42:43], 0, v[154:155]
	s_mov_b32 m0, s62
	s_nop 0
	global_load_lds_dwordx4 v[222:223], off
	v_lshl_add_u64 v[222:223], s[42:43], 0, v[158:159]
	s_add_i32 m0, s62, 0x2000
	s_nop 0
	global_load_lds_dwordx4 v[222:223], off
	v_lshl_add_u64 v[222:223], v[226:227], 0, s[12:13]
	s_mov_b32 m0, s23
	s_nop 0
	global_load_lds_dwordx4 v[222:223], off
	v_lshl_add_u64 v[222:223], v[228:229], 0, s[12:13]
	s_mov_b32 m0, s60
	s_nop 0
	global_load_lds_dwordx4 v[222:223], off
	s_waitcnt vmcnt(8)
	s_waitcnt lgkmcnt(0)
	s_barrier
	s_waitcnt lgkmcnt(0)
	v_mfma_f32_16x16x32_bf16 v[60:63], v[128:131], v[180:183], v[60:63]
	v_mfma_f32_16x16x32_bf16 v[56:59], v[136:139], v[180:183], v[56:59]
	v_mfma_f32_16x16x32_bf16 v[44:47], v[128:131], v[198:201], v[44:47]
	v_mfma_f32_16x16x32_bf16 v[40:43], v[136:139], v[198:201], v[40:43]
	v_mfma_f32_16x16x32_bf16 v[28:31], v[128:131], v[206:209], v[28:31]
	v_mfma_f32_16x16x32_bf16 v[24:27], v[136:139], v[206:209], v[24:27]
	v_mfma_f32_16x16x32_bf16 v[12:15], v[128:131], v[214:217], v[12:15]
	v_mfma_f32_16x16x32_bf16 v[8:11], v[136:139], v[214:217], v[8:11]
	v_mfma_f32_16x16x32_bf16 v[60:63], v[132:135], v[194:197], v[60:63]
	v_mfma_f32_16x16x32_bf16 v[56:59], v[140:143], v[194:197], v[56:59]
	v_mfma_f32_16x16x32_bf16 v[44:47], v[132:135], v[202:205], v[44:47]
	v_mfma_f32_16x16x32_bf16 v[40:43], v[140:143], v[202:205], v[40:43]
	v_mfma_f32_16x16x32_bf16 v[28:31], v[132:135], v[210:213], v[28:31]
	v_mfma_f32_16x16x32_bf16 v[24:27], v[140:143], v[210:213], v[24:27]
	v_mfma_f32_16x16x32_bf16 v[12:15], v[132:135], v[218:221], v[12:15]
	v_mfma_f32_16x16x32_bf16 v[8:11], v[140:143], v[218:221], v[8:11]
	v_mfma_f32_16x16x32_bf16 v[52:55], v[144:147], v[180:183], v[52:55]
	v_mfma_f32_16x16x32_bf16 v[48:51], v[172:175], v[180:183], v[48:51]
	v_mfma_f32_16x16x32_bf16 v[36:39], v[144:147], v[198:201], v[36:39]
	v_mfma_f32_16x16x32_bf16 v[32:35], v[172:175], v[198:201], v[32:35]
	v_mfma_f32_16x16x32_bf16 v[20:23], v[144:147], v[206:209], v[20:23]
	v_mfma_f32_16x16x32_bf16 v[16:19], v[172:175], v[206:209], v[16:19]
	v_mfma_f32_16x16x32_bf16 v[4:7], v[144:147], v[214:217], v[4:7]
	v_mfma_f32_16x16x32_bf16 v[0:3], v[172:175], v[214:217], v[0:3]
	v_mfma_f32_16x16x32_bf16 v[52:55], v[148:151], v[194:197], v[52:55]
	v_mfma_f32_16x16x32_bf16 v[48:51], v[176:179], v[194:197], v[48:51]
	v_mfma_f32_16x16x32_bf16 v[36:39], v[148:151], v[202:205], v[36:39]
	v_mfma_f32_16x16x32_bf16 v[32:35], v[176:179], v[202:205], v[32:35]
	v_mfma_f32_16x16x32_bf16 v[20:23], v[148:151], v[210:213], v[20:23]
	v_mfma_f32_16x16x32_bf16 v[16:19], v[176:179], v[210:213], v[16:19]
	v_mfma_f32_16x16x32_bf16 v[4:7], v[148:151], v[218:221], v[4:7]
	v_mfma_f32_16x16x32_bf16 v[0:3], v[176:179], v[218:221], v[0:3]
	s_barrier
	s_add_i32 s72, s72, 2
	s_add_u32 s40, s40, 0x100
	s_addc_u32 s41, s41, 0
	s_add_u32 s70, s70, 0x100
	s_addc_u32 s71, s71, 0
	s_cmp_gt_u32 s72, 13
	s_cbranch_scc0 .LBB0_1026
	s_and_b64 vcc, exec, s[24:25]
	s_cbranch_vccz .LBB0_1029
	s_barrier

.LBB0_1115:
	ds_read_b128 v[144:147], v155
	ds_read_b128 v[160:163], v155 offset:1024
	ds_read_b128 v[164:167], v155 offset:2048
	ds_read_b128 v[168:171], v155 offset:3072
	ds_read_b128 v[172:175], v157
	ds_read_b128 v[176:179], v157 offset:1024
	ds_read_b128 v[180:183], v157 offset:2048
	ds_read_b128 v[186:189], v157 offset:3072
	s_add_u32 s40, s38, 0xfffc0080
	s_addc_u32 s41, s39, -1
	s_cmp_eq_u32 s70, 12
	s_cselect_b32 s43, s27, s41
	s_cselect_b32 s42, s64, s40
	s_cselect_b32 s41, s29, s67
	s_cselect_b32 s40, s65, s66
	v_lshl_add_u64 v[222:223], s[38:39], 0, v[136:137]
	s_add_i32 m0, s16, 0xc000
	ds_read_b128 v[190:193], v158
	ds_read_b128 v[194:197], v158 offset:1024
	ds_read_b128 v[198:201], v158 offset:2048
	ds_read_b128 v[202:205], v158 offset:3072
	ds_read_b128 v[206:209], v158 offset:4096
	ds_read_b128 v[210:213], v158 offset:5120
	ds_read_b128 v[214:217], v158 offset:6144
	ds_read_b128 v[218:221], v158 offset:7168
	global_load_lds_dwordx4 v[222:223], off
	v_lshl_add_u64 v[222:223], s[38:39], 0, v[138:139]
	s_add_i32 m0, s16, 0xe000
	s_nop 0
	global_load_lds_dwordx4 v[222:223], off
	s_waitcnt vmcnt(8)
	s_waitcnt lgkmcnt(0)
	s_barrier
	s_waitcnt lgkmcnt(0)
	v_mfma_f32_16x16x32_bf16 v[124:127], v[144:147], v[190:193], v[124:127]
	v_mfma_f32_16x16x32_bf16 v[120:123], v[164:167], v[190:193], v[120:123]
	v_mfma_f32_16x16x32_bf16 v[116:119], v[144:147], v[198:201], v[116:119]
	v_mfma_f32_16x16x32_bf16 v[104:107], v[164:167], v[198:201], v[104:107]
	v_mfma_f32_16x16x32_bf16 v[92:95], v[144:147], v[206:209], v[92:95]
	v_mfma_f32_16x16x32_bf16 v[88:91], v[164:167], v[206:209], v[88:91]
	v_mfma_f32_16x16x32_bf16 v[76:79], v[144:147], v[214:217], v[76:79]
	v_mfma_f32_16x16x32_bf16 v[72:75], v[164:167], v[214:217], v[72:75]
	v_mfma_f32_16x16x32_bf16 v[124:127], v[160:163], v[194:197], v[124:127]
	v_mfma_f32_16x16x32_bf16 v[120:123], v[168:171], v[194:197], v[120:123]
	v_mfma_f32_16x16x32_bf16 v[116:119], v[160:163], v[202:205], v[116:119]
	v_mfma_f32_16x16x32_bf16 v[104:107], v[168:171], v[202:205], v[104:107]
	v_mfma_f32_16x16x32_bf16 v[92:95], v[160:163], v[210:213], v[92:95]
	v_mfma_f32_16x16x32_bf16 v[88:91], v[168:171], v[210:213], v[88:91]
	v_mfma_f32_16x16x32_bf16 v[76:79], v[160:163], v[218:221], v[76:79]
	v_mfma_f32_16x16x32_bf16 v[72:75], v[168:171], v[218:221], v[72:75]
	v_mfma_f32_16x16x32_bf16 v[112:115], v[172:175], v[190:193], v[112:115]
	v_mfma_f32_16x16x32_bf16 v[108:111], v[180:183], v[190:193], v[108:111]
	v_mfma_f32_16x16x32_bf16 v[100:103], v[172:175], v[198:201], v[100:103]
	v_mfma_f32_16x16x32_bf16 v[96:99], v[180:183], v[198:201], v[96:99]
	v_mfma_f32_16x16x32_bf16 v[84:87], v[172:175], v[206:209], v[84:87]
	v_mfma_f32_16x16x32_bf16 v[80:83], v[180:183], v[206:209], v[80:83]
	v_mfma_f32_16x16x32_bf16 v[68:71], v[172:175], v[214:217], v[68:71]
	v_mfma_f32_16x16x32_bf16 v[64:67], v[180:183], v[214:217], v[64:67]
	v_mfma_f32_16x16x32_bf16 v[112:115], v[176:179], v[194:197], v[112:115]
	v_mfma_f32_16x16x32_bf16 v[108:111], v[186:189], v[194:197], v[108:111]
	v_mfma_f32_16x16x32_bf16 v[100:103], v[176:179], v[202:205], v[100:103]
	v_mfma_f32_16x16x32_bf16 v[96:99], v[186:189], v[202:205], v[96:99]
	v_mfma_f32_16x16x32_bf16 v[84:87], v[176:179], v[210:213], v[84:87]
	v_mfma_f32_16x16x32_bf16 v[80:83], v[186:189], v[210:213], v[80:83]
	v_mfma_f32_16x16x32_bf16 v[68:71], v[176:179], v[218:221], v[68:71]
	v_mfma_f32_16x16x32_bf16 v[64:67], v[186:189], v[218:221], v[64:67]
	s_barrier
	s_add_i32 s71, s60, s3
	v_lshl_add_u64 v[222:223], s[40:41], 0, v[132:133]
	s_mov_b32 m0, s71
	ds_read_b128 v[190:193], v158 offset:16384
	ds_read_b128 v[194:197], v158 offset:17408
	ds_read_b128 v[198:201], v158 offset:18432
	ds_read_b128 v[202:205], v158 offset:19456
	ds_read_b128 v[206:209], v158 offset:20480
	ds_read_b128 v[210:213], v158 offset:21504
	ds_read_b128 v[214:217], v158 offset:22528
	ds_read_b128 v[218:221], v158 offset:23552
	global_load_lds_dwordx4 v[222:223], off
	s_add_i32 m0, s71, 0x2000
	s_add_u32 s72, s40, 0x40000
	v_lshl_add_u64 v[224:225], s[40:41], 0, v[128:129]
	s_addc_u32 s73, s41, 0
	s_add_i32 s71, s61, s3
	global_load_lds_dwordx4 v[224:225], off
	v_lshl_add_u64 v[226:227], s[72:73], 0, v[132:133]
	s_mov_b32 m0, s71
	v_lshl_add_u64 v[228:229], s[42:43], 0, v[130:131]
	global_load_lds_dwordx4 v[226:227], off
	v_lshl_add_u64 v[226:227], s[72:73], 0, v[128:129]
	s_add_i32 m0, s71, 0x2000
	s_nop 0
	global_load_lds_dwordx4 v[226:227], off
	v_lshl_add_u64 v[226:227], s[42:43], 0, v[134:135]
	s_mov_b32 m0, s16
	s_nop 0
	global_load_lds_dwordx4 v[226:227], off
	s_mov_b32 m0, s17
	s_nop 0
	global_load_lds_dwordx4 v[228:229], off
	s_waitcnt vmcnt(8)
	s_waitcnt lgkmcnt(0)
	s_barrier
	s_waitcnt lgkmcnt(0)
	v_mfma_f32_16x16x32_bf16 v[60:63], v[144:147], v[190:193], v[60:63]
	v_mfma_f32_16x16x32_bf16 v[56:59], v[164:167], v[190:193], v[56:59]
	v_mfma_f32_16x16x32_bf16 v[44:47], v[144:147], v[198:201], v[44:47]
	v_mfma_f32_16x16x32_bf16 v[40:43], v[164:167], v[198:201], v[40:43]
	v_mfma_f32_16x16x32_bf16 v[28:31], v[144:147], v[206:209], v[28:31]
	v_mfma_f32_16x16x32_bf16 v[24:27], v[164:167], v[206:209], v[24:27]
	v_mfma_f32_16x16x32_bf16 v[12:15], v[144:147], v[214:217], v[12:15]
	v_mfma_f32_16x16x32_bf16 v[8:11], v[164:167], v[214:217], v[8:11]
	v_mfma_f32_16x16x32_bf16 v[60:63], v[160:163], v[194:197], v[60:63]
	v_mfma_f32_16x16x32_bf16 v[56:59], v[168:171], v[194:197], v[56:59]
	v_mfma_f32_16x16x32_bf16 v[44:47], v[160:163], v[202:205], v[44:47]
	v_mfma_f32_16x16x32_bf16 v[40:43], v[168:171], v[202:205], v[40:43]
	v_mfma_f32_16x16x32_bf16 v[28:31], v[160:163], v[210:213], v[28:31]
	v_mfma_f32_16x16x32_bf16 v[24:27], v[168:171], v[210:213], v[24:27]
	v_mfma_f32_16x16x32_bf16 v[12:15], v[160:163], v[218:221], v[12:15]
	v_mfma_f32_16x16x32_bf16 v[8:11], v[168:171], v[218:221], v[8:11]
	v_mfma_f32_16x16x32_bf16 v[52:55], v[172:175], v[190:193], v[52:55]
	v_mfma_f32_16x16x32_bf16 v[48:51], v[180:183], v[190:193], v[48:51]
	v_mfma_f32_16x16x32_bf16 v[36:39], v[172:175], v[198:201], v[36:39]
	v_mfma_f32_16x16x32_bf16 v[32:35], v[180:183], v[198:201], v[32:35]
	v_mfma_f32_16x16x32_bf16 v[20:23], v[172:175], v[206:209], v[20:23]
	v_mfma_f32_16x16x32_bf16 v[16:19], v[180:183], v[206:209], v[16:19]
	v_mfma_f32_16x16x32_bf16 v[4:7], v[172:175], v[214:217], v[4:7]
	v_mfma_f32_16x16x32_bf16 v[0:3], v[180:183], v[214:217], v[0:3]
	v_mfma_f32_16x16x32_bf16 v[52:55], v[176:179], v[194:197], v[52:55]
	v_mfma_f32_16x16x32_bf16 v[48:51], v[186:189], v[194:197], v[48:51]
	v_mfma_f32_16x16x32_bf16 v[36:39], v[176:179], v[202:205], v[36:39]
	v_mfma_f32_16x16x32_bf16 v[32:35], v[186:189], v[202:205], v[32:35]
	v_mfma_f32_16x16x32_bf16 v[20:23], v[176:179], v[210:213], v[20:23]
	v_mfma_f32_16x16x32_bf16 v[16:19], v[186:189], v[210:213], v[16:19]
	v_mfma_f32_16x16x32_bf16 v[4:7], v[176:179], v[218:221], v[4:7]
	v_mfma_f32_16x16x32_bf16 v[0:3], v[186:189], v[218:221], v[0:3]
	s_barrier
	s_add_i32 s71, 0, 0x18000
	v_add_u32_e32 v148, s71, v151
	s_add_i32 s72, 0, 0x1c000
	ds_read_b128 v[144:147], v148
	ds_read_b128 v[160:163], v148 offset:1024
	ds_read_b128 v[164:167], v148 offset:2048
	ds_read_b128 v[168:171], v148 offset:3072
	v_add_u32_e32 v148, s72, v151
	ds_read_b128 v[172:175], v148
	ds_read_b128 v[176:179], v148 offset:1024
	ds_read_b128 v[180:183], v148 offset:2048
	ds_read_b128 v[186:189], v148 offset:3072
	s_add_u32 s42, s42, 0x40000
	s_addc_u32 s43, s43, 0
	s_mov_b32 m0, s18
	v_lshl_add_u64 v[230:231], s[42:43], 0, v[134:135]
	ds_read_b128 v[190:193], v158 offset:32768
	ds_read_b128 v[194:197], v158 offset:33792
	ds_read_b128 v[198:201], v158 offset:34816
	ds_read_b128 v[202:205], v158 offset:35840
	ds_read_b128 v[206:209], v158 offset:36864
	ds_read_b128 v[210:213], v158 offset:37888
	ds_read_b128 v[214:217], v158 offset:38912
	ds_read_b128 v[218:221], v158 offset:39936
	global_load_lds_dwordx4 v[230:231], off
	v_lshl_add_u64 v[230:231], s[42:43], 0, v[130:131]
	s_mov_b32 m0, s19
	s_nop 0
	global_load_lds_dwordx4 v[230:231], off
	s_waitcnt vmcnt(8)
	s_waitcnt lgkmcnt(0)
	s_barrier
	s_waitcnt lgkmcnt(0)
	v_mfma_f32_16x16x32_bf16 v[124:127], v[144:147], v[190:193], v[124:127]
	v_mfma_f32_16x16x32_bf16 v[120:123], v[164:167], v[190:193], v[120:123]
	v_mfma_f32_16x16x32_bf16 v[116:119], v[144:147], v[198:201], v[116:119]
	v_mfma_f32_16x16x32_bf16 v[104:107], v[164:167], v[198:201], v[104:107]
	v_mfma_f32_16x16x32_bf16 v[92:95], v[144:147], v[206:209], v[92:95]
	v_mfma_f32_16x16x32_bf16 v[88:91], v[164:167], v[206:209], v[88:91]
	v_mfma_f32_16x16x32_bf16 v[76:79], v[144:147], v[214:217], v[76:79]
	v_mfma_f32_16x16x32_bf16 v[72:75], v[164:167], v[214:217], v[72:75]
	v_mfma_f32_16x16x32_bf16 v[124:127], v[160:163], v[194:197], v[124:127]
	v_mfma_f32_16x16x32_bf16 v[120:123], v[168:171], v[194:197], v[120:123]
	v_mfma_f32_16x16x32_bf16 v[116:119], v[160:163], v[202:205], v[116:119]
	v_mfma_f32_16x16x32_bf16 v[104:107], v[168:171], v[202:205], v[104:107]
	v_mfma_f32_16x16x32_bf16 v[92:95], v[160:163], v[210:213], v[92:95]
	v_mfma_f32_16x16x32_bf16 v[88:91], v[168:171], v[210:213], v[88:91]
	v_mfma_f32_16x16x32_bf16 v[76:79], v[160:163], v[218:221], v[76:79]
	v_mfma_f32_16x16x32_bf16 v[72:75], v[168:171], v[218:221], v[72:75]
	v_mfma_f32_16x16x32_bf16 v[112:115], v[172:175], v[190:193], v[112:115]
	v_mfma_f32_16x16x32_bf16 v[108:111], v[180:183], v[190:193], v[108:111]
	v_mfma_f32_16x16x32_bf16 v[100:103], v[172:175], v[198:201], v[100:103]
	v_mfma_f32_16x16x32_bf16 v[96:99], v[180:183], v[198:201], v[96:99]
	v_mfma_f32_16x16x32_bf16 v[84:87], v[172:175], v[206:209], v[84:87]
	v_mfma_f32_16x16x32_bf16 v[80:83], v[180:183], v[206:209], v[80:83]
	v_mfma_f32_16x16x32_bf16 v[68:71], v[172:175], v[214:217], v[68:71]
	v_mfma_f32_16x16x32_bf16 v[64:67], v[180:183], v[214:217], v[64:67]
	v_mfma_f32_16x16x32_bf16 v[112:115], v[176:179], v[194:197], v[112:115]
	v_mfma_f32_16x16x32_bf16 v[108:111], v[186:189], v[194:197], v[108:111]
	v_mfma_f32_16x16x32_bf16 v[100:103], v[176:179], v[202:205], v[100:103]
	v_mfma_f32_16x16x32_bf16 v[96:99], v[186:189], v[202:205], v[96:99]
	v_mfma_f32_16x16x32_bf16 v[84:87], v[176:179], v[210:213], v[84:87]
	v_mfma_f32_16x16x32_bf16 v[80:83], v[186:189], v[210:213], v[80:83]
	v_mfma_f32_16x16x32_bf16 v[68:71], v[176:179], v[218:221], v[68:71]
	v_mfma_f32_16x16x32_bf16 v[64:67], v[186:189], v[218:221], v[64:67]
	s_barrier
	s_add_i32 s42, s71, s3
	v_lshl_add_u64 v[222:223], v[222:223], 0, s[12:13]
	s_mov_b32 m0, s42
	ds_read_b128 v[190:193], v158 offset:49152
	ds_read_b128 v[194:197], v158 offset:50176
	ds_read_b128 v[198:201], v158 offset:51200
	ds_read_b128 v[202:205], v158 offset:52224
	ds_read_b128 v[206:209], v158 offset:53248
	ds_read_b128 v[210:213], v158 offset:54272
	ds_read_b128 v[214:217], v158 offset:55296
	ds_read_b128 v[218:221], v158 offset:56320
	global_load_lds_dwordx4 v[222:223], off
	s_add_i32 m0, s42, 0x2000
	s_add_u32 s40, s40, 0x40080
	v_lshl_add_u64 v[222:223], v[224:225], 0, s[12:13]
	s_addc_u32 s41, s41, 0
	s_add_i32 s42, s72, s3
	global_load_lds_dwordx4 v[222:223], off
	v_lshl_add_u64 v[222:223], s[40:41], 0, v[132:133]
	s_mov_b32 m0, s42
	s_nop 0
	global_load_lds_dwordx4 v[222:223], off
	v_lshl_add_u64 v[222:223], s[40:41], 0, v[128:129]
	s_add_i32 m0, s42, 0x2000
	s_nop 0
	global_load_lds_dwordx4 v[222:223], off
	v_lshl_add_u64 v[222:223], v[226:227], 0, s[12:13]
	s_mov_b32 m0, s21
	s_nop 0
	global_load_lds_dwordx4 v[222:223], off
	v_lshl_add_u64 v[222:223], v[228:229], 0, s[12:13]
	s_mov_b32 m0, s22
	s_nop 0
	global_load_lds_dwordx4 v[222:223], off
	s_waitcnt vmcnt(8)
	s_waitcnt lgkmcnt(0)
	s_barrier
	s_waitcnt lgkmcnt(0)
	v_mfma_f32_16x16x32_bf16 v[60:63], v[144:147], v[190:193], v[60:63]
	v_mfma_f32_16x16x32_bf16 v[56:59], v[164:167], v[190:193], v[56:59]
	v_mfma_f32_16x16x32_bf16 v[44:47], v[144:147], v[198:201], v[44:47]
	v_mfma_f32_16x16x32_bf16 v[40:43], v[164:167], v[198:201], v[40:43]
	v_mfma_f32_16x16x32_bf16 v[28:31], v[144:147], v[206:209], v[28:31]
	v_mfma_f32_16x16x32_bf16 v[24:27], v[164:167], v[206:209], v[24:27]
	v_mfma_f32_16x16x32_bf16 v[12:15], v[144:147], v[214:217], v[12:15]
	v_mfma_f32_16x16x32_bf16 v[8:11], v[164:167], v[214:217], v[8:11]
	v_mfma_f32_16x16x32_bf16 v[60:63], v[160:163], v[194:197], v[60:63]
	v_mfma_f32_16x16x32_bf16 v[56:59], v[168:171], v[194:197], v[56:59]
	v_mfma_f32_16x16x32_bf16 v[44:47], v[160:163], v[202:205], v[44:47]
	v_mfma_f32_16x16x32_bf16 v[40:43], v[168:171], v[202:205], v[40:43]
	v_mfma_f32_16x16x32_bf16 v[28:31], v[160:163], v[210:213], v[28:31]
	v_mfma_f32_16x16x32_bf16 v[24:27], v[168:171], v[210:213], v[24:27]
	v_mfma_f32_16x16x32_bf16 v[12:15], v[160:163], v[218:221], v[12:15]
	v_mfma_f32_16x16x32_bf16 v[8:11], v[168:171], v[218:221], v[8:11]
	v_mfma_f32_16x16x32_bf16 v[52:55], v[172:175], v[190:193], v[52:55]
	v_mfma_f32_16x16x32_bf16 v[48:51], v[180:183], v[190:193], v[48:51]
	v_mfma_f32_16x16x32_bf16 v[36:39], v[172:175], v[198:201], v[36:39]
	v_mfma_f32_16x16x32_bf16 v[32:35], v[180:183], v[198:201], v[32:35]
	v_mfma_f32_16x16x32_bf16 v[20:23], v[172:175], v[206:209], v[20:23]
	v_mfma_f32_16x16x32_bf16 v[16:19], v[180:183], v[206:209], v[16:19]
	v_mfma_f32_16x16x32_bf16 v[4:7], v[172:175], v[214:217], v[4:7]
	v_mfma_f32_16x16x32_bf16 v[0:3], v[180:183], v[214:217], v[0:3]
	v_mfma_f32_16x16x32_bf16 v[52:55], v[176:179], v[194:197], v[52:55]
	v_mfma_f32_16x16x32_bf16 v[48:51], v[186:189], v[194:197], v[48:51]
	v_mfma_f32_16x16x32_bf16 v[36:39], v[176:179], v[202:205], v[36:39]
	v_mfma_f32_16x16x32_bf16 v[32:35], v[186:189], v[202:205], v[32:35]
	v_mfma_f32_16x16x32_bf16 v[20:23], v[176:179], v[210:213], v[20:23]
	v_mfma_f32_16x16x32_bf16 v[16:19], v[186:189], v[210:213], v[16:19]
	v_mfma_f32_16x16x32_bf16 v[4:7], v[176:179], v[218:221], v[4:7]
	v_mfma_f32_16x16x32_bf16 v[0:3], v[186:189], v[218:221], v[0:3]
	s_barrier
	s_add_i32 s70, s70, 2
	s_add_u32 s38, s38, 0x100
	s_addc_u32 s39, s39, 0
	s_add_u32 s66, s66, 0x100
	s_addc_u32 s67, s67, 0
	s_cmp_gt_u32 s70, 13
	s_cbranch_scc0 .LBB0_1115
	s_and_b64 vcc, exec, s[24:25]
	s_cbranch_vccz .LBB0_1118
	s_barrier

.LBB0_1324:
	ds_read_b128 v[128:131], v189
	ds_read_b128 v[132:135], v189 offset:1024
	ds_read_b128 v[136:139], v189 offset:2048
	ds_read_b128 v[140:143], v189 offset:3072
	ds_read_b128 v[144:147], v190
	ds_read_b128 v[148:151], v190 offset:1024
	ds_read_b128 v[172:175], v190 offset:2048
	ds_read_b128 v[176:179], v190 offset:3072
	s_add_u32 s36, s34, 0xfff50080
	s_addc_u32 s37, s35, -1
	s_cmp_eq_u32 s64, 40
	s_cselect_b32 s39, s1, s37
	s_cselect_b32 s38, s0, s36
	s_cselect_b32 s37, s29, s63
	s_cselect_b32 s36, s28, s31
	v_lshl_add_u64 v[222:223], s[34:35], 0, v[164:165]
	s_add_i32 m0, s16, 0xc000
	ds_read_b128 v[180:183], v191
	ds_read_b128 v[194:197], v191 offset:1024
	ds_read_b128 v[198:201], v191 offset:2048
	ds_read_b128 v[202:205], v191 offset:3072
	ds_read_b128 v[206:209], v191 offset:4096
	ds_read_b128 v[210:213], v191 offset:5120
	ds_read_b128 v[214:217], v191 offset:6144
	ds_read_b128 v[218:221], v191 offset:7168
	global_load_lds_dwordx4 v[222:223], off
	v_lshl_add_u64 v[222:223], s[34:35], 0, v[166:167]
	s_add_i32 m0, s16, 0xe000
	s_nop 0
	global_load_lds_dwordx4 v[222:223], off
	s_waitcnt vmcnt(8)
	s_waitcnt lgkmcnt(0)
	s_barrier
	s_waitcnt lgkmcnt(0)
	v_mfma_f32_16x16x32_bf16 v[124:127], v[128:131], v[180:183], v[124:127]
	v_mfma_f32_16x16x32_bf16 v[120:123], v[136:139], v[180:183], v[120:123]
	v_mfma_f32_16x16x32_bf16 v[108:111], v[128:131], v[198:201], v[108:111]
	v_mfma_f32_16x16x32_bf16 v[104:107], v[136:139], v[198:201], v[104:107]
	v_mfma_f32_16x16x32_bf16 v[92:95], v[128:131], v[206:209], v[92:95]
	v_mfma_f32_16x16x32_bf16 v[88:91], v[136:139], v[206:209], v[88:91]
	v_mfma_f32_16x16x32_bf16 v[76:79], v[128:131], v[214:217], v[76:79]
	v_mfma_f32_16x16x32_bf16 v[72:75], v[136:139], v[214:217], v[72:75]
	v_mfma_f32_16x16x32_bf16 v[124:127], v[132:135], v[194:197], v[124:127]
	v_mfma_f32_16x16x32_bf16 v[120:123], v[140:143], v[194:197], v[120:123]
	v_mfma_f32_16x16x32_bf16 v[108:111], v[132:135], v[202:205], v[108:111]
	v_mfma_f32_16x16x32_bf16 v[104:107], v[140:143], v[202:205], v[104:107]
	v_mfma_f32_16x16x32_bf16 v[92:95], v[132:135], v[210:213], v[92:95]
	v_mfma_f32_16x16x32_bf16 v[88:91], v[140:143], v[210:213], v[88:91]
	v_mfma_f32_16x16x32_bf16 v[76:79], v[132:135], v[218:221], v[76:79]
	v_mfma_f32_16x16x32_bf16 v[72:75], v[140:143], v[218:221], v[72:75]
	v_mfma_f32_16x16x32_bf16 v[116:119], v[144:147], v[180:183], v[116:119]
	v_mfma_f32_16x16x32_bf16 v[112:115], v[172:175], v[180:183], v[112:115]
	v_mfma_f32_16x16x32_bf16 v[100:103], v[144:147], v[198:201], v[100:103]
	v_mfma_f32_16x16x32_bf16 v[96:99], v[172:175], v[198:201], v[96:99]
	v_mfma_f32_16x16x32_bf16 v[84:87], v[144:147], v[206:209], v[84:87]
	v_mfma_f32_16x16x32_bf16 v[80:83], v[172:175], v[206:209], v[80:83]
	v_mfma_f32_16x16x32_bf16 v[68:71], v[144:147], v[214:217], v[68:71]
	v_mfma_f32_16x16x32_bf16 v[64:67], v[172:175], v[214:217], v[64:67]
	v_mfma_f32_16x16x32_bf16 v[116:119], v[148:151], v[194:197], v[116:119]
	v_mfma_f32_16x16x32_bf16 v[112:115], v[176:179], v[194:197], v[112:115]
	v_mfma_f32_16x16x32_bf16 v[100:103], v[148:151], v[202:205], v[100:103]
	v_mfma_f32_16x16x32_bf16 v[96:99], v[176:179], v[202:205], v[96:99]
	v_mfma_f32_16x16x32_bf16 v[84:87], v[148:151], v[210:213], v[84:87]
	v_mfma_f32_16x16x32_bf16 v[80:83], v[176:179], v[210:213], v[80:83]
	v_mfma_f32_16x16x32_bf16 v[68:71], v[148:151], v[218:221], v[68:71]
	v_mfma_f32_16x16x32_bf16 v[64:67], v[176:179], v[218:221], v[64:67]
	s_barrier
	s_add_i32 s65, s42, s15
	v_lshl_add_u64 v[222:223], s[36:37], 0, v[154:155]
	s_mov_b32 m0, s65
	ds_read_b128 v[180:183], v191 offset:16384
	ds_read_b128 v[194:197], v191 offset:17408
	ds_read_b128 v[198:201], v191 offset:18432
	ds_read_b128 v[202:205], v191 offset:19456
	ds_read_b128 v[206:209], v191 offset:20480
	ds_read_b128 v[210:213], v191 offset:21504
	ds_read_b128 v[214:217], v191 offset:22528
	ds_read_b128 v[218:221], v191 offset:23552
	global_load_lds_dwordx4 v[222:223], off
	s_add_i32 m0, s65, 0x2000
	s_add_u32 s66, s36, 0xb0000
	v_lshl_add_u64 v[224:225], s[36:37], 0, v[158:159]
	s_addc_u32 s67, s37, 0
	s_add_i32 s65, s43, s15
	global_load_lds_dwordx4 v[224:225], off
	v_lshl_add_u64 v[226:227], s[66:67], 0, v[154:155]
	s_mov_b32 m0, s65
	v_lshl_add_u64 v[228:229], s[38:39], 0, v[156:157]
	global_load_lds_dwordx4 v[226:227], off
	v_lshl_add_u64 v[226:227], s[66:67], 0, v[158:159]
	s_add_i32 m0, s65, 0x2000
	s_nop 0
	global_load_lds_dwordx4 v[226:227], off
	v_lshl_add_u64 v[226:227], s[38:39], 0, v[152:153]
	s_mov_b32 m0, s16
	s_nop 0
	global_load_lds_dwordx4 v[226:227], off
	s_mov_b32 m0, s17
	s_nop 0
	global_load_lds_dwordx4 v[228:229], off
	s_waitcnt vmcnt(8)
	s_waitcnt lgkmcnt(0)
	s_barrier
	s_waitcnt lgkmcnt(0)
	v_mfma_f32_16x16x32_bf16 v[60:63], v[128:131], v[180:183], v[60:63]
	v_mfma_f32_16x16x32_bf16 v[56:59], v[136:139], v[180:183], v[56:59]
	v_mfma_f32_16x16x32_bf16 v[44:47], v[128:131], v[198:201], v[44:47]
	v_mfma_f32_16x16x32_bf16 v[40:43], v[136:139], v[198:201], v[40:43]
	v_mfma_f32_16x16x32_bf16 v[28:31], v[128:131], v[206:209], v[28:31]
	v_mfma_f32_16x16x32_bf16 v[24:27], v[136:139], v[206:209], v[24:27]
	v_mfma_f32_16x16x32_bf16 v[12:15], v[128:131], v[214:217], v[12:15]
	v_mfma_f32_16x16x32_bf16 v[8:11], v[136:139], v[214:217], v[8:11]
	v_mfma_f32_16x16x32_bf16 v[60:63], v[132:135], v[194:197], v[60:63]
	v_mfma_f32_16x16x32_bf16 v[56:59], v[140:143], v[194:197], v[56:59]
	v_mfma_f32_16x16x32_bf16 v[44:47], v[132:135], v[202:205], v[44:47]
	v_mfma_f32_16x16x32_bf16 v[40:43], v[140:143], v[202:205], v[40:43]
	v_mfma_f32_16x16x32_bf16 v[28:31], v[132:135], v[210:213], v[28:31]
	v_mfma_f32_16x16x32_bf16 v[24:27], v[140:143], v[210:213], v[24:27]
	v_mfma_f32_16x16x32_bf16 v[12:15], v[132:135], v[218:221], v[12:15]
	v_mfma_f32_16x16x32_bf16 v[8:11], v[140:143], v[218:221], v[8:11]
	v_mfma_f32_16x16x32_bf16 v[52:55], v[144:147], v[180:183], v[52:55]
	v_mfma_f32_16x16x32_bf16 v[48:51], v[172:175], v[180:183], v[48:51]
	v_mfma_f32_16x16x32_bf16 v[36:39], v[144:147], v[198:201], v[36:39]
	v_mfma_f32_16x16x32_bf16 v[32:35], v[172:175], v[198:201], v[32:35]
	v_mfma_f32_16x16x32_bf16 v[20:23], v[144:147], v[206:209], v[20:23]
	v_mfma_f32_16x16x32_bf16 v[16:19], v[172:175], v[206:209], v[16:19]
	v_mfma_f32_16x16x32_bf16 v[4:7], v[144:147], v[214:217], v[4:7]
	v_mfma_f32_16x16x32_bf16 v[0:3], v[172:175], v[214:217], v[0:3]
	v_mfma_f32_16x16x32_bf16 v[52:55], v[148:151], v[194:197], v[52:55]
	v_mfma_f32_16x16x32_bf16 v[48:51], v[176:179], v[194:197], v[48:51]
	v_mfma_f32_16x16x32_bf16 v[36:39], v[148:151], v[202:205], v[36:39]
	v_mfma_f32_16x16x32_bf16 v[32:35], v[176:179], v[202:205], v[32:35]
	v_mfma_f32_16x16x32_bf16 v[20:23], v[148:151], v[210:213], v[20:23]
	v_mfma_f32_16x16x32_bf16 v[16:19], v[176:179], v[210:213], v[16:19]
	v_mfma_f32_16x16x32_bf16 v[4:7], v[148:151], v[218:221], v[4:7]
	v_mfma_f32_16x16x32_bf16 v[0:3], v[176:179], v[218:221], v[0:3]
	s_barrier
	s_add_i32 s65, 0, 0x18000
	s_add_i32 s66, 0, 0x1c000
	v_add_u32_e32 v140, s65, v186
	v_add_u32_e32 v176, s66, v186
	ds_read_b128 v[128:131], v140
	ds_read_b128 v[132:135], v140 offset:1024
	ds_read_b128 v[136:139], v140 offset:2048
	ds_read_b128 v[140:143], v140 offset:3072
	ds_read_b128 v[144:147], v176
	ds_read_b128 v[148:151], v176 offset:1024
	ds_read_b128 v[172:175], v176 offset:2048
	ds_read_b128 v[176:179], v176 offset:3072
	s_add_u32 s38, s38, 0xb0000
	s_addc_u32 s39, s39, 0
	s_mov_b32 m0, s18
	v_lshl_add_u64 v[230:231], s[38:39], 0, v[152:153]
	ds_read_b128 v[180:183], v191 offset:32768
	ds_read_b128 v[194:197], v191 offset:33792
	ds_read_b128 v[198:201], v191 offset:34816
	ds_read_b128 v[202:205], v191 offset:35840
	ds_read_b128 v[206:209], v191 offset:36864
	ds_read_b128 v[210:213], v191 offset:37888
	ds_read_b128 v[214:217], v191 offset:38912
	ds_read_b128 v[218:221], v191 offset:39936
	global_load_lds_dwordx4 v[230:231], off
	v_lshl_add_u64 v[230:231], s[38:39], 0, v[156:157]
	s_mov_b32 m0, s19
	s_nop 0
	global_load_lds_dwordx4 v[230:231], off
	s_waitcnt vmcnt(8)
	s_waitcnt lgkmcnt(0)
	s_barrier
	s_waitcnt lgkmcnt(0)
	v_mfma_f32_16x16x32_bf16 v[124:127], v[128:131], v[180:183], v[124:127]
	v_mfma_f32_16x16x32_bf16 v[120:123], v[136:139], v[180:183], v[120:123]
	v_mfma_f32_16x16x32_bf16 v[108:111], v[128:131], v[198:201], v[108:111]
	v_mfma_f32_16x16x32_bf16 v[104:107], v[136:139], v[198:201], v[104:107]
	v_mfma_f32_16x16x32_bf16 v[92:95], v[128:131], v[206:209], v[92:95]
	v_mfma_f32_16x16x32_bf16 v[88:91], v[136:139], v[206:209], v[88:91]
	v_mfma_f32_16x16x32_bf16 v[76:79], v[128:131], v[214:217], v[76:79]
	v_mfma_f32_16x16x32_bf16 v[72:75], v[136:139], v[214:217], v[72:75]
	v_mfma_f32_16x16x32_bf16 v[124:127], v[132:135], v[194:197], v[124:127]
	v_mfma_f32_16x16x32_bf16 v[120:123], v[140:143], v[194:197], v[120:123]
	v_mfma_f32_16x16x32_bf16 v[108:111], v[132:135], v[202:205], v[108:111]
	v_mfma_f32_16x16x32_bf16 v[104:107], v[140:143], v[202:205], v[104:107]
	v_mfma_f32_16x16x32_bf16 v[92:95], v[132:135], v[210:213], v[92:95]
	v_mfma_f32_16x16x32_bf16 v[88:91], v[140:143], v[210:213], v[88:91]
	v_mfma_f32_16x16x32_bf16 v[76:79], v[132:135], v[218:221], v[76:79]
	v_mfma_f32_16x16x32_bf16 v[72:75], v[140:143], v[218:221], v[72:75]
	v_mfma_f32_16x16x32_bf16 v[116:119], v[144:147], v[180:183], v[116:119]
	v_mfma_f32_16x16x32_bf16 v[112:115], v[172:175], v[180:183], v[112:115]
	v_mfma_f32_16x16x32_bf16 v[100:103], v[144:147], v[198:201], v[100:103]
	v_mfma_f32_16x16x32_bf16 v[96:99], v[172:175], v[198:201], v[96:99]
	v_mfma_f32_16x16x32_bf16 v[84:87], v[144:147], v[206:209], v[84:87]
	v_mfma_f32_16x16x32_bf16 v[80:83], v[172:175], v[206:209], v[80:83]
	v_mfma_f32_16x16x32_bf16 v[68:71], v[144:147], v[214:217], v[68:71]
	v_mfma_f32_16x16x32_bf16 v[64:67], v[172:175], v[214:217], v[64:67]
	v_mfma_f32_16x16x32_bf16 v[116:119], v[148:151], v[194:197], v[116:119]
	v_mfma_f32_16x16x32_bf16 v[112:115], v[176:179], v[194:197], v[112:115]
	v_mfma_f32_16x16x32_bf16 v[100:103], v[148:151], v[202:205], v[100:103]
	v_mfma_f32_16x16x32_bf16 v[96:99], v[176:179], v[202:205], v[96:99]
	v_mfma_f32_16x16x32_bf16 v[84:87], v[148:151], v[210:213], v[84:87]
	v_mfma_f32_16x16x32_bf16 v[80:83], v[176:179], v[210:213], v[80:83]
	v_mfma_f32_16x16x32_bf16 v[68:71], v[148:151], v[218:221], v[68:71]
	v_mfma_f32_16x16x32_bf16 v[64:67], v[176:179], v[218:221], v[64:67]
	s_barrier
	s_add_i32 s38, s65, s15
	v_lshl_add_u64 v[222:223], v[222:223], 0, s[24:25]
	s_mov_b32 m0, s38
	ds_read_b128 v[180:183], v191 offset:49152
	ds_read_b128 v[194:197], v191 offset:50176
	ds_read_b128 v[198:201], v191 offset:51200
	ds_read_b128 v[202:205], v191 offset:52224
	ds_read_b128 v[206:209], v191 offset:53248
	ds_read_b128 v[210:213], v191 offset:54272
	ds_read_b128 v[214:217], v191 offset:55296
	ds_read_b128 v[218:221], v191 offset:56320
	global_load_lds_dwordx4 v[222:223], off
	s_add_i32 m0, s38, 0x2000
	s_add_u32 s36, s36, 0xb0080
	v_lshl_add_u64 v[222:223], v[224:225], 0, s[24:25]
	s_addc_u32 s37, s37, 0
	s_add_i32 s38, s66, s15
	global_load_lds_dwordx4 v[222:223], off
	v_lshl_add_u64 v[222:223], s[36:37], 0, v[154:155]
	s_mov_b32 m0, s38
	s_nop 0
	global_load_lds_dwordx4 v[222:223], off
	v_lshl_add_u64 v[222:223], s[36:37], 0, v[158:159]
	s_add_i32 m0, s38, 0x2000
	s_nop 0
	global_load_lds_dwordx4 v[222:223], off
	v_lshl_add_u64 v[222:223], v[226:227], 0, s[24:25]
	s_mov_b32 m0, s21
	s_nop 0
	global_load_lds_dwordx4 v[222:223], off
	v_lshl_add_u64 v[222:223], v[228:229], 0, s[24:25]
	s_mov_b32 m0, s22
	s_nop 0
	global_load_lds_dwordx4 v[222:223], off
	s_waitcnt vmcnt(8)
	s_waitcnt lgkmcnt(0)
	s_barrier
	s_waitcnt lgkmcnt(0)
	v_mfma_f32_16x16x32_bf16 v[60:63], v[128:131], v[180:183], v[60:63]
	v_mfma_f32_16x16x32_bf16 v[56:59], v[136:139], v[180:183], v[56:59]
	v_mfma_f32_16x16x32_bf16 v[44:47], v[128:131], v[198:201], v[44:47]
	v_mfma_f32_16x16x32_bf16 v[40:43], v[136:139], v[198:201], v[40:43]
	v_mfma_f32_16x16x32_bf16 v[28:31], v[128:131], v[206:209], v[28:31]
	v_mfma_f32_16x16x32_bf16 v[24:27], v[136:139], v[206:209], v[24:27]
	v_mfma_f32_16x16x32_bf16 v[12:15], v[128:131], v[214:217], v[12:15]
	v_mfma_f32_16x16x32_bf16 v[8:11], v[136:139], v[214:217], v[8:11]
	v_mfma_f32_16x16x32_bf16 v[60:63], v[132:135], v[194:197], v[60:63]
	v_mfma_f32_16x16x32_bf16 v[56:59], v[140:143], v[194:197], v[56:59]
	v_mfma_f32_16x16x32_bf16 v[44:47], v[132:135], v[202:205], v[44:47]
	v_mfma_f32_16x16x32_bf16 v[40:43], v[140:143], v[202:205], v[40:43]
	v_mfma_f32_16x16x32_bf16 v[28:31], v[132:135], v[210:213], v[28:31]
	v_mfma_f32_16x16x32_bf16 v[24:27], v[140:143], v[210:213], v[24:27]
	v_mfma_f32_16x16x32_bf16 v[12:15], v[132:135], v[218:221], v[12:15]
	v_mfma_f32_16x16x32_bf16 v[8:11], v[140:143], v[218:221], v[8:11]
	v_mfma_f32_16x16x32_bf16 v[52:55], v[144:147], v[180:183], v[52:55]
	v_mfma_f32_16x16x32_bf16 v[48:51], v[172:175], v[180:183], v[48:51]
	v_mfma_f32_16x16x32_bf16 v[36:39], v[144:147], v[198:201], v[36:39]
	v_mfma_f32_16x16x32_bf16 v[32:35], v[172:175], v[198:201], v[32:35]
	v_mfma_f32_16x16x32_bf16 v[20:23], v[144:147], v[206:209], v[20:23]
	v_mfma_f32_16x16x32_bf16 v[16:19], v[172:175], v[206:209], v[16:19]
	v_mfma_f32_16x16x32_bf16 v[4:7], v[144:147], v[214:217], v[4:7]
	v_mfma_f32_16x16x32_bf16 v[0:3], v[172:175], v[214:217], v[0:3]
	v_mfma_f32_16x16x32_bf16 v[52:55], v[148:151], v[194:197], v[52:55]
	v_mfma_f32_16x16x32_bf16 v[48:51], v[176:179], v[194:197], v[48:51]
	v_mfma_f32_16x16x32_bf16 v[36:39], v[148:151], v[202:205], v[36:39]
	v_mfma_f32_16x16x32_bf16 v[32:35], v[176:179], v[202:205], v[32:35]
	v_mfma_f32_16x16x32_bf16 v[20:23], v[148:151], v[210:213], v[20:23]
	v_mfma_f32_16x16x32_bf16 v[16:19], v[176:179], v[210:213], v[16:19]
	v_mfma_f32_16x16x32_bf16 v[4:7], v[148:151], v[218:221], v[4:7]
	v_mfma_f32_16x16x32_bf16 v[0:3], v[176:179], v[218:221], v[0:3]
	s_barrier
	s_add_i32 s64, s64, 2
	s_add_u32 s34, s34, 0x100
	s_addc_u32 s35, s35, 0
	s_add_u32 s31, s31, 0x100
	s_addc_u32 s63, s63, 0
	s_cmp_gt_u32 s64, 41
	s_cbranch_scc0 .LBB0_1324
	s_and_b64 vcc, exec, s[26:27]
	s_cbranch_vccz .LBB0_1327
	s_barrier

.LBB0_1413:
	ds_read_b128 v[128:131], v171
	ds_read_b128 v[132:135], v171 offset:1024
	ds_read_b128 v[178:181], v171 offset:2048
	ds_read_b128 v[186:189], v171 offset:3072
	ds_read_b128 v[190:193], v173
	ds_read_b128 v[194:197], v173 offset:1024
	ds_read_b128 v[198:201], v173 offset:2048
	ds_read_b128 v[202:205], v173 offset:3072
	s_add_u32 s21, s38, 0xfffc0080
	s_addc_u32 s22, s39, -1
	s_cmp_eq_u32 s20, 12
	s_cselect_b32 s43, s14, s22
	s_cselect_b32 s42, s15, s21
	s_cselect_b32 s41, s16, s19
	s_cselect_b32 s40, s17, s18
	v_lshl_add_u64 v[160:161], s[38:39], 0, v[152:153]
	s_add_i32 m0, s37, 0xc000
	ds_read_b128 v[206:209], v175
	ds_read_b128 v[210:213], v175 offset:1024
	ds_read_b128 v[214:217], v175 offset:2048
	ds_read_b128 v[218:221], v175 offset:3072
	ds_read_b128 v[222:225], v175 offset:4096
	ds_read_b128 v[226:229], v175 offset:5120
	ds_read_b128 v[230:233], v175 offset:6144
	ds_read_b128 v[234:237], v175 offset:7168
	global_load_lds_dwordx4 v[160:161], off
	v_lshl_add_u64 v[160:161], s[38:39], 0, v[154:155]
	s_add_i32 m0, s37, 0xe000
	s_nop 0
	global_load_lds_dwordx4 v[160:161], off
	s_waitcnt vmcnt(8)
	s_waitcnt lgkmcnt(0)
	s_barrier
	s_waitcnt lgkmcnt(0)
	v_mfma_f32_16x16x32_bf16 v[124:127], v[128:131], v[206:209], v[124:127]
	v_mfma_f32_16x16x32_bf16 v[120:123], v[178:181], v[206:209], v[120:123]
	v_mfma_f32_16x16x32_bf16 v[108:111], v[128:131], v[214:217], v[108:111]
	v_mfma_f32_16x16x32_bf16 v[100:103], v[178:181], v[214:217], v[100:103]
	v_mfma_f32_16x16x32_bf16 v[92:95], v[128:131], v[222:225], v[92:95]
	v_mfma_f32_16x16x32_bf16 v[84:87], v[178:181], v[222:225], v[84:87]
	v_mfma_f32_16x16x32_bf16 v[76:79], v[128:131], v[230:233], v[76:79]
	v_mfma_f32_16x16x32_bf16 v[68:71], v[178:181], v[230:233], v[68:71]
	v_mfma_f32_16x16x32_bf16 v[124:127], v[132:135], v[210:213], v[124:127]
	v_mfma_f32_16x16x32_bf16 v[120:123], v[186:189], v[210:213], v[120:123]
	v_mfma_f32_16x16x32_bf16 v[108:111], v[132:135], v[218:221], v[108:111]
	v_mfma_f32_16x16x32_bf16 v[100:103], v[186:189], v[218:221], v[100:103]
	v_mfma_f32_16x16x32_bf16 v[92:95], v[132:135], v[226:229], v[92:95]
	v_mfma_f32_16x16x32_bf16 v[84:87], v[186:189], v[226:229], v[84:87]
	v_mfma_f32_16x16x32_bf16 v[76:79], v[132:135], v[234:237], v[76:79]
	v_mfma_f32_16x16x32_bf16 v[68:71], v[186:189], v[234:237], v[68:71]
	v_mfma_f32_16x16x32_bf16 v[116:119], v[190:193], v[206:209], v[116:119]
	v_mfma_f32_16x16x32_bf16 v[112:115], v[198:201], v[206:209], v[112:115]
	v_mfma_f32_16x16x32_bf16 v[104:107], v[190:193], v[214:217], v[104:107]
	v_mfma_f32_16x16x32_bf16 v[96:99], v[198:201], v[214:217], v[96:99]
	v_mfma_f32_16x16x32_bf16 v[88:91], v[190:193], v[222:225], v[88:91]
	v_mfma_f32_16x16x32_bf16 v[80:83], v[198:201], v[222:225], v[80:83]
	v_mfma_f32_16x16x32_bf16 v[72:75], v[190:193], v[230:233], v[72:75]
	v_mfma_f32_16x16x32_bf16 v[64:67], v[198:201], v[230:233], v[64:67]
	v_mfma_f32_16x16x32_bf16 v[116:119], v[194:197], v[210:213], v[116:119]
	v_mfma_f32_16x16x32_bf16 v[112:115], v[202:205], v[210:213], v[112:115]
	v_mfma_f32_16x16x32_bf16 v[104:107], v[194:197], v[218:221], v[104:107]
	v_mfma_f32_16x16x32_bf16 v[96:99], v[202:205], v[218:221], v[96:99]
	v_mfma_f32_16x16x32_bf16 v[88:91], v[194:197], v[226:229], v[88:91]
	v_mfma_f32_16x16x32_bf16 v[80:83], v[202:205], v[226:229], v[80:83]
	v_mfma_f32_16x16x32_bf16 v[72:75], v[194:197], v[234:237], v[72:75]
	v_mfma_f32_16x16x32_bf16 v[64:67], v[202:205], v[234:237], v[64:67]
	s_barrier
	s_add_i32 s21, s44, s60
	v_lshl_add_u64 v[160:161], s[40:41], 0, v[140:141]
	s_mov_b32 m0, s21
	ds_read_b128 v[206:209], v175 offset:16384
	ds_read_b128 v[210:213], v175 offset:17408
	ds_read_b128 v[214:217], v175 offset:18432
	ds_read_b128 v[218:221], v175 offset:19456
	ds_read_b128 v[222:225], v175 offset:20480
	ds_read_b128 v[226:229], v175 offset:21504
	ds_read_b128 v[230:233], v175 offset:22528
	ds_read_b128 v[234:237], v175 offset:23552
	global_load_lds_dwordx4 v[160:161], off
	s_add_i32 m0, s21, 0x2000
	s_add_u32 s22, s40, 0x40000
	v_lshl_add_u64 v[168:169], s[40:41], 0, v[136:137]
	s_addc_u32 s23, s41, 0
	s_add_i32 s21, s45, s60
	global_load_lds_dwordx4 v[168:169], off
	v_lshl_add_u64 v[182:183], s[22:23], 0, v[140:141]
	s_mov_b32 m0, s21
	v_lshl_add_u64 v[238:239], s[42:43], 0, v[138:139]
	global_load_lds_dwordx4 v[182:183], off
	v_lshl_add_u64 v[182:183], s[22:23], 0, v[136:137]
	s_add_i32 m0, s21, 0x2000
	s_nop 0
	global_load_lds_dwordx4 v[182:183], off
	v_lshl_add_u64 v[182:183], s[42:43], 0, v[142:143]
	s_mov_b32 m0, s37
	s_nop 0
	global_load_lds_dwordx4 v[182:183], off
	s_mov_b32 m0, s63
	s_nop 0
	global_load_lds_dwordx4 v[238:239], off
	s_waitcnt vmcnt(8)
	s_waitcnt lgkmcnt(0)
	s_barrier
	s_waitcnt lgkmcnt(0)
	v_mfma_f32_16x16x32_bf16 v[60:63], v[128:131], v[206:209], v[60:63]
	v_mfma_f32_16x16x32_bf16 v[52:55], v[178:181], v[206:209], v[52:55]
	v_mfma_f32_16x16x32_bf16 v[44:47], v[128:131], v[214:217], v[44:47]
	v_mfma_f32_16x16x32_bf16 v[36:39], v[178:181], v[214:217], v[36:39]
	v_mfma_f32_16x16x32_bf16 v[28:31], v[128:131], v[222:225], v[28:31]
	v_mfma_f32_16x16x32_bf16 v[20:23], v[178:181], v[222:225], v[20:23]
	v_mfma_f32_16x16x32_bf16 v[12:15], v[128:131], v[230:233], v[12:15]
	v_mfma_f32_16x16x32_bf16 v[4:7], v[178:181], v[230:233], v[4:7]
	v_mfma_f32_16x16x32_bf16 v[60:63], v[132:135], v[210:213], v[60:63]
	v_mfma_f32_16x16x32_bf16 v[52:55], v[186:189], v[210:213], v[52:55]
	v_mfma_f32_16x16x32_bf16 v[44:47], v[132:135], v[218:221], v[44:47]
	v_mfma_f32_16x16x32_bf16 v[36:39], v[186:189], v[218:221], v[36:39]
	v_mfma_f32_16x16x32_bf16 v[28:31], v[132:135], v[226:229], v[28:31]
	v_mfma_f32_16x16x32_bf16 v[20:23], v[186:189], v[226:229], v[20:23]
	v_mfma_f32_16x16x32_bf16 v[12:15], v[132:135], v[234:237], v[12:15]
	v_mfma_f32_16x16x32_bf16 v[4:7], v[186:189], v[234:237], v[4:7]
	v_mfma_f32_16x16x32_bf16 v[56:59], v[190:193], v[206:209], v[56:59]
	v_mfma_f32_16x16x32_bf16 v[48:51], v[198:201], v[206:209], v[48:51]
	v_mfma_f32_16x16x32_bf16 v[40:43], v[190:193], v[214:217], v[40:43]
	v_mfma_f32_16x16x32_bf16 v[32:35], v[198:201], v[214:217], v[32:35]
	v_mfma_f32_16x16x32_bf16 v[24:27], v[190:193], v[222:225], v[24:27]
	v_mfma_f32_16x16x32_bf16 v[16:19], v[198:201], v[222:225], v[16:19]
	v_mfma_f32_16x16x32_bf16 v[8:11], v[190:193], v[230:233], v[8:11]
	v_mfma_f32_16x16x32_bf16 v[0:3], v[198:201], v[230:233], v[0:3]
	v_mfma_f32_16x16x32_bf16 v[56:59], v[194:197], v[210:213], v[56:59]
	v_mfma_f32_16x16x32_bf16 v[48:51], v[202:205], v[210:213], v[48:51]
	v_mfma_f32_16x16x32_bf16 v[40:43], v[194:197], v[218:221], v[40:43]
	v_mfma_f32_16x16x32_bf16 v[32:35], v[202:205], v[218:221], v[32:35]
	v_mfma_f32_16x16x32_bf16 v[24:27], v[194:197], v[226:229], v[24:27]
	v_mfma_f32_16x16x32_bf16 v[16:19], v[202:205], v[226:229], v[16:19]
	v_mfma_f32_16x16x32_bf16 v[8:11], v[194:197], v[234:237], v[8:11]
	v_mfma_f32_16x16x32_bf16 v[0:3], v[202:205], v[234:237], v[0:3]
	s_barrier
	s_add_i32 s21, 0, 0x18000
	v_add_u32_e32 v144, s21, v165
	s_add_i32 s27, 0, 0x1c000
	ds_read_b128 v[128:131], v144
	ds_read_b128 v[132:135], v144 offset:1024
	ds_read_b128 v[178:181], v144 offset:2048
	ds_read_b128 v[186:189], v144 offset:3072
	v_add_u32_e32 v144, s27, v165
	ds_read_b128 v[190:193], v144
	ds_read_b128 v[194:197], v144 offset:1024
	ds_read_b128 v[198:201], v144 offset:2048
	ds_read_b128 v[202:205], v144 offset:3072
	s_add_u32 s22, s42, 0x40000
	s_addc_u32 s23, s43, 0
	s_mov_b32 m0, s64
	v_lshl_add_u64 v[240:241], s[22:23], 0, v[142:143]
	ds_read_b128 v[206:209], v175 offset:32768
	ds_read_b128 v[210:213], v175 offset:33792
	ds_read_b128 v[214:217], v175 offset:34816
	ds_read_b128 v[218:221], v175 offset:35840
	ds_read_b128 v[222:225], v175 offset:36864
	ds_read_b128 v[226:229], v175 offset:37888
	ds_read_b128 v[230:233], v175 offset:38912
	ds_read_b128 v[234:237], v175 offset:39936
	global_load_lds_dwordx4 v[240:241], off
	v_lshl_add_u64 v[240:241], s[22:23], 0, v[138:139]
	s_mov_b32 m0, s65
	s_nop 0
	global_load_lds_dwordx4 v[240:241], off
	s_waitcnt vmcnt(8)
	s_waitcnt lgkmcnt(0)
	s_barrier
	s_waitcnt lgkmcnt(0)
	v_mfma_f32_16x16x32_bf16 v[124:127], v[128:131], v[206:209], v[124:127]
	v_mfma_f32_16x16x32_bf16 v[120:123], v[178:181], v[206:209], v[120:123]
	v_mfma_f32_16x16x32_bf16 v[108:111], v[128:131], v[214:217], v[108:111]
	v_mfma_f32_16x16x32_bf16 v[100:103], v[178:181], v[214:217], v[100:103]
	v_mfma_f32_16x16x32_bf16 v[92:95], v[128:131], v[222:225], v[92:95]
	v_mfma_f32_16x16x32_bf16 v[84:87], v[178:181], v[222:225], v[84:87]
	v_mfma_f32_16x16x32_bf16 v[76:79], v[128:131], v[230:233], v[76:79]
	v_mfma_f32_16x16x32_bf16 v[68:71], v[178:181], v[230:233], v[68:71]
	v_mfma_f32_16x16x32_bf16 v[124:127], v[132:135], v[210:213], v[124:127]
	v_mfma_f32_16x16x32_bf16 v[120:123], v[186:189], v[210:213], v[120:123]
	v_mfma_f32_16x16x32_bf16 v[108:111], v[132:135], v[218:221], v[108:111]
	v_mfma_f32_16x16x32_bf16 v[100:103], v[186:189], v[218:221], v[100:103]
	v_mfma_f32_16x16x32_bf16 v[92:95], v[132:135], v[226:229], v[92:95]
	v_mfma_f32_16x16x32_bf16 v[84:87], v[186:189], v[226:229], v[84:87]
	v_mfma_f32_16x16x32_bf16 v[76:79], v[132:135], v[234:237], v[76:79]
	v_mfma_f32_16x16x32_bf16 v[68:71], v[186:189], v[234:237], v[68:71]
	v_mfma_f32_16x16x32_bf16 v[116:119], v[190:193], v[206:209], v[116:119]
	v_mfma_f32_16x16x32_bf16 v[112:115], v[198:201], v[206:209], v[112:115]
	v_mfma_f32_16x16x32_bf16 v[104:107], v[190:193], v[214:217], v[104:107]
	v_mfma_f32_16x16x32_bf16 v[96:99], v[198:201], v[214:217], v[96:99]
	v_mfma_f32_16x16x32_bf16 v[88:91], v[190:193], v[222:225], v[88:91]
	v_mfma_f32_16x16x32_bf16 v[80:83], v[198:201], v[222:225], v[80:83]
	v_mfma_f32_16x16x32_bf16 v[72:75], v[190:193], v[230:233], v[72:75]
	v_mfma_f32_16x16x32_bf16 v[64:67], v[198:201], v[230:233], v[64:67]
	v_mfma_f32_16x16x32_bf16 v[116:119], v[194:197], v[210:213], v[116:119]
	v_mfma_f32_16x16x32_bf16 v[112:115], v[202:205], v[210:213], v[112:115]
	v_mfma_f32_16x16x32_bf16 v[104:107], v[194:197], v[218:221], v[104:107]
	v_mfma_f32_16x16x32_bf16 v[96:99], v[202:205], v[218:221], v[96:99]
	v_mfma_f32_16x16x32_bf16 v[88:91], v[194:197], v[226:229], v[88:91]
	v_mfma_f32_16x16x32_bf16 v[80:83], v[202:205], v[226:229], v[80:83]
	v_mfma_f32_16x16x32_bf16 v[72:75], v[194:197], v[234:237], v[72:75]
	v_mfma_f32_16x16x32_bf16 v[64:67], v[202:205], v[234:237], v[64:67]
	s_barrier
	s_add_i32 s21, s21, s60
	v_lshl_add_u64 v[160:161], v[160:161], 0, s[12:13]
	s_mov_b32 m0, s21
	ds_read_b128 v[206:209], v175 offset:49152
	ds_read_b128 v[210:213], v175 offset:50176
	ds_read_b128 v[214:217], v175 offset:51200
	ds_read_b128 v[218:221], v175 offset:52224
	ds_read_b128 v[222:225], v175 offset:53248
	ds_read_b128 v[226:229], v175 offset:54272
	ds_read_b128 v[230:233], v175 offset:55296
	ds_read_b128 v[234:237], v175 offset:56320
	global_load_lds_dwordx4 v[160:161], off
	s_add_i32 m0, s21, 0x2000
	s_add_u32 s22, s40, 0x40080
	v_lshl_add_u64 v[160:161], v[168:169], 0, s[12:13]
	s_addc_u32 s23, s41, 0
	s_add_i32 s21, s27, s60
	global_load_lds_dwordx4 v[160:161], off
	v_lshl_add_u64 v[160:161], s[22:23], 0, v[140:141]
	s_mov_b32 m0, s21
	s_nop 0
	global_load_lds_dwordx4 v[160:161], off
	v_lshl_add_u64 v[160:161], s[22:23], 0, v[136:137]
	s_add_i32 m0, s21, 0x2000
	s_nop 0
	global_load_lds_dwordx4 v[160:161], off
	v_lshl_add_u64 v[160:161], v[182:183], 0, s[12:13]
	s_mov_b32 m0, s67
	s_nop 0
	global_load_lds_dwordx4 v[160:161], off
	v_lshl_add_u64 v[160:161], v[238:239], 0, s[12:13]
	s_mov_b32 m0, s70
	s_nop 0
	global_load_lds_dwordx4 v[160:161], off
	s_waitcnt vmcnt(8)
	s_waitcnt lgkmcnt(0)
	s_barrier
	s_waitcnt lgkmcnt(0)
	v_mfma_f32_16x16x32_bf16 v[60:63], v[128:131], v[206:209], v[60:63]
	v_mfma_f32_16x16x32_bf16 v[52:55], v[178:181], v[206:209], v[52:55]
	v_mfma_f32_16x16x32_bf16 v[44:47], v[128:131], v[214:217], v[44:47]
	v_mfma_f32_16x16x32_bf16 v[36:39], v[178:181], v[214:217], v[36:39]
	v_mfma_f32_16x16x32_bf16 v[28:31], v[128:131], v[222:225], v[28:31]
	v_mfma_f32_16x16x32_bf16 v[20:23], v[178:181], v[222:225], v[20:23]
	v_mfma_f32_16x16x32_bf16 v[12:15], v[128:131], v[230:233], v[12:15]
	v_mfma_f32_16x16x32_bf16 v[4:7], v[178:181], v[230:233], v[4:7]
	v_mfma_f32_16x16x32_bf16 v[60:63], v[132:135], v[210:213], v[60:63]
	v_mfma_f32_16x16x32_bf16 v[52:55], v[186:189], v[210:213], v[52:55]
	v_mfma_f32_16x16x32_bf16 v[44:47], v[132:135], v[218:221], v[44:47]
	v_mfma_f32_16x16x32_bf16 v[36:39], v[186:189], v[218:221], v[36:39]
	v_mfma_f32_16x16x32_bf16 v[28:31], v[132:135], v[226:229], v[28:31]
	v_mfma_f32_16x16x32_bf16 v[20:23], v[186:189], v[226:229], v[20:23]
	v_mfma_f32_16x16x32_bf16 v[12:15], v[132:135], v[234:237], v[12:15]
	v_mfma_f32_16x16x32_bf16 v[4:7], v[186:189], v[234:237], v[4:7]
	v_mfma_f32_16x16x32_bf16 v[56:59], v[190:193], v[206:209], v[56:59]
	v_mfma_f32_16x16x32_bf16 v[48:51], v[198:201], v[206:209], v[48:51]
	v_mfma_f32_16x16x32_bf16 v[40:43], v[190:193], v[214:217], v[40:43]
	v_mfma_f32_16x16x32_bf16 v[32:35], v[198:201], v[214:217], v[32:35]
	v_mfma_f32_16x16x32_bf16 v[24:27], v[190:193], v[222:225], v[24:27]
	v_mfma_f32_16x16x32_bf16 v[16:19], v[198:201], v[222:225], v[16:19]
	v_mfma_f32_16x16x32_bf16 v[8:11], v[190:193], v[230:233], v[8:11]
	v_mfma_f32_16x16x32_bf16 v[0:3], v[198:201], v[230:233], v[0:3]
	v_mfma_f32_16x16x32_bf16 v[56:59], v[194:197], v[210:213], v[56:59]
	v_mfma_f32_16x16x32_bf16 v[48:51], v[202:205], v[210:213], v[48:51]
	v_mfma_f32_16x16x32_bf16 v[40:43], v[194:197], v[218:221], v[40:43]
	v_mfma_f32_16x16x32_bf16 v[32:35], v[202:205], v[218:221], v[32:35]
	v_mfma_f32_16x16x32_bf16 v[24:27], v[194:197], v[226:229], v[24:27]
	v_mfma_f32_16x16x32_bf16 v[16:19], v[202:205], v[226:229], v[16:19]
	v_mfma_f32_16x16x32_bf16 v[8:11], v[194:197], v[234:237], v[8:11]
	v_mfma_f32_16x16x32_bf16 v[0:3], v[202:205], v[234:237], v[0:3]
	s_barrier
	s_add_i32 s20, s20, 2
	s_add_u32 s38, s38, 0x100
	s_addc_u32 s39, s39, 0
	s_add_u32 s18, s18, 0x100
	s_addc_u32 s19, s19, 0
	s_cmp_gt_u32 s20, 13
	s_cbranch_scc0 .LBB0_1413
	s_and_b64 vcc, exec, s[24:25]
	s_cbranch_vccz .LBB0_1418
	s_barrier
	s_cmp_lt_i32 s80, 8
	s_mov_b64 s[38:39], -1
	s_cbranch_scc1 .LBB0_1419

.LBB0_1630:
	ds_read_b128 v[128:131], v189
	ds_read_b128 v[132:135], v189 offset:1024
	ds_read_b128 v[136:139], v189 offset:2048
	ds_read_b128 v[140:143], v189 offset:3072
	ds_read_b128 v[144:147], v190
	ds_read_b128 v[148:151], v190 offset:1024
	ds_read_b128 v[172:175], v190 offset:2048
	ds_read_b128 v[176:179], v190 offset:3072
	s_add_u32 s24, s22, 0xfff50080
	s_addc_u32 s25, s23, -1
	s_cmp_eq_u32 s50, 40
	s_cselect_b32 s27, s1, s25
	s_cselect_b32 s26, s0, s24
	s_cselect_b32 s25, s19, s47
	s_cselect_b32 s24, s18, s21
	v_lshl_add_u64 v[222:223], s[22:23], 0, v[164:165]
	s_add_i32 m0, s30, 0xc000
	ds_read_b128 v[180:183], v191
	ds_read_b128 v[194:197], v191 offset:1024
	ds_read_b128 v[198:201], v191 offset:2048
	ds_read_b128 v[202:205], v191 offset:3072
	ds_read_b128 v[206:209], v191 offset:4096
	ds_read_b128 v[210:213], v191 offset:5120
	ds_read_b128 v[214:217], v191 offset:6144
	ds_read_b128 v[218:221], v191 offset:7168
	global_load_lds_dwordx4 v[222:223], off
	v_lshl_add_u64 v[222:223], s[22:23], 0, v[166:167]
	s_add_i32 m0, s30, 0xe000
	s_nop 0
	global_load_lds_dwordx4 v[222:223], off
	s_waitcnt vmcnt(8)
	s_waitcnt lgkmcnt(0)
	s_barrier
	s_waitcnt lgkmcnt(0)
	v_mfma_f32_16x16x32_bf16 v[124:127], v[128:131], v[180:183], v[124:127]
	v_mfma_f32_16x16x32_bf16 v[120:123], v[136:139], v[180:183], v[120:123]
	v_mfma_f32_16x16x32_bf16 v[108:111], v[128:131], v[198:201], v[108:111]
	v_mfma_f32_16x16x32_bf16 v[104:107], v[136:139], v[198:201], v[104:107]
	v_mfma_f32_16x16x32_bf16 v[92:95], v[128:131], v[206:209], v[92:95]
	v_mfma_f32_16x16x32_bf16 v[88:91], v[136:139], v[206:209], v[88:91]
	v_mfma_f32_16x16x32_bf16 v[76:79], v[128:131], v[214:217], v[76:79]
	v_mfma_f32_16x16x32_bf16 v[72:75], v[136:139], v[214:217], v[72:75]
	v_mfma_f32_16x16x32_bf16 v[124:127], v[132:135], v[194:197], v[124:127]
	v_mfma_f32_16x16x32_bf16 v[120:123], v[140:143], v[194:197], v[120:123]
	v_mfma_f32_16x16x32_bf16 v[108:111], v[132:135], v[202:205], v[108:111]
	v_mfma_f32_16x16x32_bf16 v[104:107], v[140:143], v[202:205], v[104:107]
	v_mfma_f32_16x16x32_bf16 v[92:95], v[132:135], v[210:213], v[92:95]
	v_mfma_f32_16x16x32_bf16 v[88:91], v[140:143], v[210:213], v[88:91]
	v_mfma_f32_16x16x32_bf16 v[76:79], v[132:135], v[218:221], v[76:79]
	v_mfma_f32_16x16x32_bf16 v[72:75], v[140:143], v[218:221], v[72:75]
	v_mfma_f32_16x16x32_bf16 v[116:119], v[144:147], v[180:183], v[116:119]
	v_mfma_f32_16x16x32_bf16 v[112:115], v[172:175], v[180:183], v[112:115]
	v_mfma_f32_16x16x32_bf16 v[100:103], v[144:147], v[198:201], v[100:103]
	v_mfma_f32_16x16x32_bf16 v[96:99], v[172:175], v[198:201], v[96:99]
	v_mfma_f32_16x16x32_bf16 v[84:87], v[144:147], v[206:209], v[84:87]
	v_mfma_f32_16x16x32_bf16 v[80:83], v[172:175], v[206:209], v[80:83]
	v_mfma_f32_16x16x32_bf16 v[68:71], v[144:147], v[214:217], v[68:71]
	v_mfma_f32_16x16x32_bf16 v[64:67], v[172:175], v[214:217], v[64:67]
	v_mfma_f32_16x16x32_bf16 v[116:119], v[148:151], v[194:197], v[116:119]
	v_mfma_f32_16x16x32_bf16 v[112:115], v[176:179], v[194:197], v[112:115]
	v_mfma_f32_16x16x32_bf16 v[100:103], v[148:151], v[202:205], v[100:103]
	v_mfma_f32_16x16x32_bf16 v[96:99], v[176:179], v[202:205], v[96:99]
	v_mfma_f32_16x16x32_bf16 v[84:87], v[148:151], v[210:213], v[84:87]
	v_mfma_f32_16x16x32_bf16 v[80:83], v[176:179], v[210:213], v[80:83]
	v_mfma_f32_16x16x32_bf16 v[68:71], v[148:151], v[218:221], v[68:71]
	v_mfma_f32_16x16x32_bf16 v[64:67], v[176:179], v[218:221], v[64:67]
	s_barrier
	s_add_i32 s51, s42, s29
	v_lshl_add_u64 v[222:223], s[24:25], 0, v[154:155]
	s_mov_b32 m0, s51
	ds_read_b128 v[180:183], v191 offset:16384
	ds_read_b128 v[194:197], v191 offset:17408
	ds_read_b128 v[198:201], v191 offset:18432
	ds_read_b128 v[202:205], v191 offset:19456
	ds_read_b128 v[206:209], v191 offset:20480
	ds_read_b128 v[210:213], v191 offset:21504
	ds_read_b128 v[214:217], v191 offset:22528
	ds_read_b128 v[218:221], v191 offset:23552
	global_load_lds_dwordx4 v[222:223], off
	s_add_i32 m0, s51, 0x2000
	s_add_u32 s52, s24, 0xb0000
	v_lshl_add_u64 v[224:225], s[24:25], 0, v[158:159]
	s_addc_u32 s53, s25, 0
	s_add_i32 s51, s43, s29
	global_load_lds_dwordx4 v[224:225], off
	v_lshl_add_u64 v[226:227], s[52:53], 0, v[154:155]
	s_mov_b32 m0, s51
	v_lshl_add_u64 v[228:229], s[26:27], 0, v[156:157]
	global_load_lds_dwordx4 v[226:227], off
	v_lshl_add_u64 v[226:227], s[52:53], 0, v[158:159]
	s_add_i32 m0, s51, 0x2000
	s_nop 0
	global_load_lds_dwordx4 v[226:227], off
	v_lshl_add_u64 v[226:227], s[26:27], 0, v[152:153]
	s_mov_b32 m0, s30
	s_nop 0
	global_load_lds_dwordx4 v[226:227], off
	s_mov_b32 m0, s31
	s_nop 0
	global_load_lds_dwordx4 v[228:229], off
	s_waitcnt vmcnt(8)
	s_waitcnt lgkmcnt(0)
	s_barrier
	s_waitcnt lgkmcnt(0)
	v_mfma_f32_16x16x32_bf16 v[60:63], v[128:131], v[180:183], v[60:63]
	v_mfma_f32_16x16x32_bf16 v[56:59], v[136:139], v[180:183], v[56:59]
	v_mfma_f32_16x16x32_bf16 v[44:47], v[128:131], v[198:201], v[44:47]
	v_mfma_f32_16x16x32_bf16 v[40:43], v[136:139], v[198:201], v[40:43]
	v_mfma_f32_16x16x32_bf16 v[28:31], v[128:131], v[206:209], v[28:31]
	v_mfma_f32_16x16x32_bf16 v[24:27], v[136:139], v[206:209], v[24:27]
	v_mfma_f32_16x16x32_bf16 v[12:15], v[128:131], v[214:217], v[12:15]
	v_mfma_f32_16x16x32_bf16 v[8:11], v[136:139], v[214:217], v[8:11]
	v_mfma_f32_16x16x32_bf16 v[60:63], v[132:135], v[194:197], v[60:63]
	v_mfma_f32_16x16x32_bf16 v[56:59], v[140:143], v[194:197], v[56:59]
	v_mfma_f32_16x16x32_bf16 v[44:47], v[132:135], v[202:205], v[44:47]
	v_mfma_f32_16x16x32_bf16 v[40:43], v[140:143], v[202:205], v[40:43]
	v_mfma_f32_16x16x32_bf16 v[28:31], v[132:135], v[210:213], v[28:31]
	v_mfma_f32_16x16x32_bf16 v[24:27], v[140:143], v[210:213], v[24:27]
	v_mfma_f32_16x16x32_bf16 v[12:15], v[132:135], v[218:221], v[12:15]
	v_mfma_f32_16x16x32_bf16 v[8:11], v[140:143], v[218:221], v[8:11]
	v_mfma_f32_16x16x32_bf16 v[52:55], v[144:147], v[180:183], v[52:55]
	v_mfma_f32_16x16x32_bf16 v[48:51], v[172:175], v[180:183], v[48:51]
	v_mfma_f32_16x16x32_bf16 v[36:39], v[144:147], v[198:201], v[36:39]
	v_mfma_f32_16x16x32_bf16 v[32:35], v[172:175], v[198:201], v[32:35]
	v_mfma_f32_16x16x32_bf16 v[20:23], v[144:147], v[206:209], v[20:23]
	v_mfma_f32_16x16x32_bf16 v[16:19], v[172:175], v[206:209], v[16:19]
	v_mfma_f32_16x16x32_bf16 v[4:7], v[144:147], v[214:217], v[4:7]
	v_mfma_f32_16x16x32_bf16 v[0:3], v[172:175], v[214:217], v[0:3]
	v_mfma_f32_16x16x32_bf16 v[52:55], v[148:151], v[194:197], v[52:55]
	v_mfma_f32_16x16x32_bf16 v[48:51], v[176:179], v[194:197], v[48:51]
	v_mfma_f32_16x16x32_bf16 v[36:39], v[148:151], v[202:205], v[36:39]
	v_mfma_f32_16x16x32_bf16 v[32:35], v[176:179], v[202:205], v[32:35]
	v_mfma_f32_16x16x32_bf16 v[20:23], v[148:151], v[210:213], v[20:23]
	v_mfma_f32_16x16x32_bf16 v[16:19], v[176:179], v[210:213], v[16:19]
	v_mfma_f32_16x16x32_bf16 v[4:7], v[148:151], v[218:221], v[4:7]
	v_mfma_f32_16x16x32_bf16 v[0:3], v[176:179], v[218:221], v[0:3]
	s_barrier
	s_add_i32 s51, 0, 0x18000
	s_add_i32 s52, 0, 0x1c000
	v_add_u32_e32 v140, s51, v186
	v_add_u32_e32 v176, s52, v186
	ds_read_b128 v[128:131], v140
	ds_read_b128 v[132:135], v140 offset:1024
	ds_read_b128 v[136:139], v140 offset:2048
	ds_read_b128 v[140:143], v140 offset:3072
	ds_read_b128 v[144:147], v176
	ds_read_b128 v[148:151], v176 offset:1024
	ds_read_b128 v[172:175], v176 offset:2048
	ds_read_b128 v[176:179], v176 offset:3072
	s_add_u32 s26, s26, 0xb0000
	s_addc_u32 s27, s27, 0
	s_mov_b32 m0, s34
	v_lshl_add_u64 v[230:231], s[26:27], 0, v[152:153]
	ds_read_b128 v[180:183], v191 offset:32768
	ds_read_b128 v[194:197], v191 offset:33792
	ds_read_b128 v[198:201], v191 offset:34816
	ds_read_b128 v[202:205], v191 offset:35840
	ds_read_b128 v[206:209], v191 offset:36864
	ds_read_b128 v[210:213], v191 offset:37888
	ds_read_b128 v[214:217], v191 offset:38912
	ds_read_b128 v[218:221], v191 offset:39936
	global_load_lds_dwordx4 v[230:231], off
	v_lshl_add_u64 v[230:231], s[26:27], 0, v[156:157]
	s_mov_b32 m0, s35
	s_nop 0
	global_load_lds_dwordx4 v[230:231], off
	s_waitcnt vmcnt(8)
	s_waitcnt lgkmcnt(0)
	s_barrier
	s_waitcnt lgkmcnt(0)
	v_mfma_f32_16x16x32_bf16 v[124:127], v[128:131], v[180:183], v[124:127]
	v_mfma_f32_16x16x32_bf16 v[120:123], v[136:139], v[180:183], v[120:123]
	v_mfma_f32_16x16x32_bf16 v[108:111], v[128:131], v[198:201], v[108:111]
	v_mfma_f32_16x16x32_bf16 v[104:107], v[136:139], v[198:201], v[104:107]
	v_mfma_f32_16x16x32_bf16 v[92:95], v[128:131], v[206:209], v[92:95]
	v_mfma_f32_16x16x32_bf16 v[88:91], v[136:139], v[206:209], v[88:91]
	v_mfma_f32_16x16x32_bf16 v[76:79], v[128:131], v[214:217], v[76:79]
	v_mfma_f32_16x16x32_bf16 v[72:75], v[136:139], v[214:217], v[72:75]
	v_mfma_f32_16x16x32_bf16 v[124:127], v[132:135], v[194:197], v[124:127]
	v_mfma_f32_16x16x32_bf16 v[120:123], v[140:143], v[194:197], v[120:123]
	v_mfma_f32_16x16x32_bf16 v[108:111], v[132:135], v[202:205], v[108:111]
	v_mfma_f32_16x16x32_bf16 v[104:107], v[140:143], v[202:205], v[104:107]
	v_mfma_f32_16x16x32_bf16 v[92:95], v[132:135], v[210:213], v[92:95]
	v_mfma_f32_16x16x32_bf16 v[88:91], v[140:143], v[210:213], v[88:91]
	v_mfma_f32_16x16x32_bf16 v[76:79], v[132:135], v[218:221], v[76:79]
	v_mfma_f32_16x16x32_bf16 v[72:75], v[140:143], v[218:221], v[72:75]
	v_mfma_f32_16x16x32_bf16 v[116:119], v[144:147], v[180:183], v[116:119]
	v_mfma_f32_16x16x32_bf16 v[112:115], v[172:175], v[180:183], v[112:115]
	v_mfma_f32_16x16x32_bf16 v[100:103], v[144:147], v[198:201], v[100:103]
	v_mfma_f32_16x16x32_bf16 v[96:99], v[172:175], v[198:201], v[96:99]
	v_mfma_f32_16x16x32_bf16 v[84:87], v[144:147], v[206:209], v[84:87]
	v_mfma_f32_16x16x32_bf16 v[80:83], v[172:175], v[206:209], v[80:83]
	v_mfma_f32_16x16x32_bf16 v[68:71], v[144:147], v[214:217], v[68:71]
	v_mfma_f32_16x16x32_bf16 v[64:67], v[172:175], v[214:217], v[64:67]
	v_mfma_f32_16x16x32_bf16 v[116:119], v[148:151], v[194:197], v[116:119]
	v_mfma_f32_16x16x32_bf16 v[112:115], v[176:179], v[194:197], v[112:115]
	v_mfma_f32_16x16x32_bf16 v[100:103], v[148:151], v[202:205], v[100:103]
	v_mfma_f32_16x16x32_bf16 v[96:99], v[176:179], v[202:205], v[96:99]
	v_mfma_f32_16x16x32_bf16 v[84:87], v[148:151], v[210:213], v[84:87]
	v_mfma_f32_16x16x32_bf16 v[80:83], v[176:179], v[210:213], v[80:83]
	v_mfma_f32_16x16x32_bf16 v[68:71], v[148:151], v[218:221], v[68:71]
	v_mfma_f32_16x16x32_bf16 v[64:67], v[176:179], v[218:221], v[64:67]
	s_barrier
	s_add_i32 s26, s51, s29
	v_lshl_add_u64 v[222:223], v[222:223], 0, s[14:15]
	s_mov_b32 m0, s26
	ds_read_b128 v[180:183], v191 offset:49152
	ds_read_b128 v[194:197], v191 offset:50176
	ds_read_b128 v[198:201], v191 offset:51200
	ds_read_b128 v[202:205], v191 offset:52224
	ds_read_b128 v[206:209], v191 offset:53248
	ds_read_b128 v[210:213], v191 offset:54272
	ds_read_b128 v[214:217], v191 offset:55296
	ds_read_b128 v[218:221], v191 offset:56320
	global_load_lds_dwordx4 v[222:223], off
	s_add_i32 m0, s26, 0x2000
	s_add_u32 s24, s24, 0xb0080
	v_lshl_add_u64 v[222:223], v[224:225], 0, s[14:15]
	s_addc_u32 s25, s25, 0
	s_add_i32 s26, s52, s29
	global_load_lds_dwordx4 v[222:223], off
	v_lshl_add_u64 v[222:223], s[24:25], 0, v[154:155]
	s_mov_b32 m0, s26
	s_nop 0
	global_load_lds_dwordx4 v[222:223], off
	v_lshl_add_u64 v[222:223], s[24:25], 0, v[158:159]
	s_add_i32 m0, s26, 0x2000
	s_nop 0
	global_load_lds_dwordx4 v[222:223], off
	v_lshl_add_u64 v[222:223], v[226:227], 0, s[14:15]
	s_mov_b32 m0, s37
	s_nop 0
	global_load_lds_dwordx4 v[222:223], off
	v_lshl_add_u64 v[222:223], v[228:229], 0, s[14:15]
	s_mov_b32 m0, s38
	s_nop 0
	global_load_lds_dwordx4 v[222:223], off
	s_waitcnt vmcnt(8)
	s_waitcnt lgkmcnt(0)
	s_barrier
	s_waitcnt lgkmcnt(0)
	v_mfma_f32_16x16x32_bf16 v[60:63], v[128:131], v[180:183], v[60:63]
	v_mfma_f32_16x16x32_bf16 v[56:59], v[136:139], v[180:183], v[56:59]
	v_mfma_f32_16x16x32_bf16 v[44:47], v[128:131], v[198:201], v[44:47]
	v_mfma_f32_16x16x32_bf16 v[40:43], v[136:139], v[198:201], v[40:43]
	v_mfma_f32_16x16x32_bf16 v[28:31], v[128:131], v[206:209], v[28:31]
	v_mfma_f32_16x16x32_bf16 v[24:27], v[136:139], v[206:209], v[24:27]
	v_mfma_f32_16x16x32_bf16 v[12:15], v[128:131], v[214:217], v[12:15]
	v_mfma_f32_16x16x32_bf16 v[8:11], v[136:139], v[214:217], v[8:11]
	v_mfma_f32_16x16x32_bf16 v[60:63], v[132:135], v[194:197], v[60:63]
	v_mfma_f32_16x16x32_bf16 v[56:59], v[140:143], v[194:197], v[56:59]
	v_mfma_f32_16x16x32_bf16 v[44:47], v[132:135], v[202:205], v[44:47]
	v_mfma_f32_16x16x32_bf16 v[40:43], v[140:143], v[202:205], v[40:43]
	v_mfma_f32_16x16x32_bf16 v[28:31], v[132:135], v[210:213], v[28:31]
	v_mfma_f32_16x16x32_bf16 v[24:27], v[140:143], v[210:213], v[24:27]
	v_mfma_f32_16x16x32_bf16 v[12:15], v[132:135], v[218:221], v[12:15]
	v_mfma_f32_16x16x32_bf16 v[8:11], v[140:143], v[218:221], v[8:11]
	v_mfma_f32_16x16x32_bf16 v[52:55], v[144:147], v[180:183], v[52:55]
	v_mfma_f32_16x16x32_bf16 v[48:51], v[172:175], v[180:183], v[48:51]
	v_mfma_f32_16x16x32_bf16 v[36:39], v[144:147], v[198:201], v[36:39]
	v_mfma_f32_16x16x32_bf16 v[32:35], v[172:175], v[198:201], v[32:35]
	v_mfma_f32_16x16x32_bf16 v[20:23], v[144:147], v[206:209], v[20:23]
	v_mfma_f32_16x16x32_bf16 v[16:19], v[172:175], v[206:209], v[16:19]
	v_mfma_f32_16x16x32_bf16 v[4:7], v[144:147], v[214:217], v[4:7]
	v_mfma_f32_16x16x32_bf16 v[0:3], v[172:175], v[214:217], v[0:3]
	v_mfma_f32_16x16x32_bf16 v[52:55], v[148:151], v[194:197], v[52:55]
	v_mfma_f32_16x16x32_bf16 v[48:51], v[176:179], v[194:197], v[48:51]
	v_mfma_f32_16x16x32_bf16 v[36:39], v[148:151], v[202:205], v[36:39]
	v_mfma_f32_16x16x32_bf16 v[32:35], v[176:179], v[202:205], v[32:35]
	v_mfma_f32_16x16x32_bf16 v[20:23], v[148:151], v[210:213], v[20:23]
	v_mfma_f32_16x16x32_bf16 v[16:19], v[176:179], v[210:213], v[16:19]
	v_mfma_f32_16x16x32_bf16 v[4:7], v[148:151], v[218:221], v[4:7]
	v_mfma_f32_16x16x32_bf16 v[0:3], v[176:179], v[218:221], v[0:3]
	s_barrier
	s_add_i32 s50, s50, 2
	s_add_u32 s22, s22, 0x100
	s_addc_u32 s23, s23, 0
	s_add_u32 s21, s21, 0x100
	s_addc_u32 s47, s47, 0
	s_cmp_gt_u32 s50, 41
	s_cbranch_scc0 .LBB0_1630
	s_and_b64 vcc, exec, s[16:17]
	s_cbranch_vccz .LBB0_1633
	s_barrier

.LBB0_1727:
	ds_read_b128 v[128:131], v163
	ds_read_b128 v[132:135], v163 offset:1024
	ds_read_b128 v[172:175], v163 offset:2048
	ds_read_b128 v[176:179], v163 offset:3072
	ds_read_b128 v[180:183], v165
	ds_read_b128 v[186:189], v165 offset:1024
	ds_read_b128 v[190:193], v165 offset:2048
	ds_read_b128 v[194:197], v165 offset:3072
	s_add_u32 s26, s24, 0xfffc0080
	s_addc_u32 s27, s25, -1
	s_cmp_eq_u32 s51, 12
	s_cselect_b32 s29, s15, s27
	s_cselect_b32 s28, s47, s26
	s_cselect_b32 s27, s17, s50
	s_cselect_b32 s26, s48, s49
	v_lshl_add_u64 v[156:157], s[24:25], 0, v[148:149]
	s_add_i32 m0, s23, 0xc000
	ds_read_b128 v[198:201], v167
	ds_read_b128 v[202:205], v167 offset:1024
	ds_read_b128 v[206:209], v167 offset:2048
	ds_read_b128 v[210:213], v167 offset:3072
	ds_read_b128 v[214:217], v167 offset:4096
	ds_read_b128 v[218:221], v167 offset:5120
	ds_read_b128 v[222:225], v167 offset:6144
	ds_read_b128 v[226:229], v167 offset:7168
	global_load_lds_dwordx4 v[156:157], off
	v_lshl_add_u64 v[156:157], s[24:25], 0, v[150:151]
	s_add_i32 m0, s23, 0xe000
	s_nop 0
	global_load_lds_dwordx4 v[156:157], off
	s_waitcnt vmcnt(8)
	s_waitcnt lgkmcnt(0)
	s_barrier
	s_waitcnt lgkmcnt(0)
	v_mfma_f32_16x16x32_bf16 v[124:127], v[128:131], v[198:201], v[124:127]
	v_mfma_f32_16x16x32_bf16 v[120:123], v[172:175], v[198:201], v[120:123]
	v_mfma_f32_16x16x32_bf16 v[116:119], v[128:131], v[206:209], v[116:119]
	v_mfma_f32_16x16x32_bf16 v[112:115], v[172:175], v[206:209], v[112:115]
	v_mfma_f32_16x16x32_bf16 v[108:111], v[128:131], v[214:217], v[108:111]
	v_mfma_f32_16x16x32_bf16 v[104:107], v[172:175], v[214:217], v[104:107]
	v_mfma_f32_16x16x32_bf16 v[100:103], v[128:131], v[222:225], v[100:103]
	v_mfma_f32_16x16x32_bf16 v[96:99], v[172:175], v[222:225], v[96:99]
	v_mfma_f32_16x16x32_bf16 v[124:127], v[132:135], v[202:205], v[124:127]
	v_mfma_f32_16x16x32_bf16 v[120:123], v[176:179], v[202:205], v[120:123]
	v_mfma_f32_16x16x32_bf16 v[116:119], v[132:135], v[210:213], v[116:119]
	v_mfma_f32_16x16x32_bf16 v[112:115], v[176:179], v[210:213], v[112:115]
	v_mfma_f32_16x16x32_bf16 v[108:111], v[132:135], v[218:221], v[108:111]
	v_mfma_f32_16x16x32_bf16 v[104:107], v[176:179], v[218:221], v[104:107]
	v_mfma_f32_16x16x32_bf16 v[100:103], v[132:135], v[226:229], v[100:103]
	v_mfma_f32_16x16x32_bf16 v[96:99], v[176:179], v[226:229], v[96:99]
	v_mfma_f32_16x16x32_bf16 v[72:75], v[180:183], v[198:201], v[72:75]
	v_mfma_f32_16x16x32_bf16 v[64:67], v[190:193], v[198:201], v[64:67]
	v_mfma_f32_16x16x32_bf16 v[56:59], v[180:183], v[206:209], v[56:59]
	v_mfma_f32_16x16x32_bf16 v[48:51], v[190:193], v[206:209], v[48:51]
	v_mfma_f32_16x16x32_bf16 v[44:47], v[180:183], v[214:217], v[44:47]
	v_mfma_f32_16x16x32_bf16 v[40:43], v[190:193], v[214:217], v[40:43]
	v_mfma_f32_16x16x32_bf16 v[36:39], v[180:183], v[222:225], v[36:39]
	v_mfma_f32_16x16x32_bf16 v[32:35], v[190:193], v[222:225], v[32:35]
	v_mfma_f32_16x16x32_bf16 v[72:75], v[186:189], v[202:205], v[72:75]
	v_mfma_f32_16x16x32_bf16 v[64:67], v[194:197], v[202:205], v[64:67]
	v_mfma_f32_16x16x32_bf16 v[56:59], v[186:189], v[210:213], v[56:59]
	v_mfma_f32_16x16x32_bf16 v[48:51], v[194:197], v[210:213], v[48:51]
	v_mfma_f32_16x16x32_bf16 v[44:47], v[186:189], v[218:221], v[44:47]
	v_mfma_f32_16x16x32_bf16 v[40:43], v[194:197], v[218:221], v[40:43]
	v_mfma_f32_16x16x32_bf16 v[36:39], v[186:189], v[226:229], v[36:39]
	v_mfma_f32_16x16x32_bf16 v[32:35], v[194:197], v[226:229], v[32:35]
	s_barrier
	s_add_i32 s52, s44, s34
	v_lshl_add_u64 v[156:157], s[26:27], 0, v[138:139]
	s_mov_b32 m0, s52
	ds_read_b128 v[198:201], v167 offset:16384
	ds_read_b128 v[202:205], v167 offset:17408
	ds_read_b128 v[206:209], v167 offset:18432
	ds_read_b128 v[210:213], v167 offset:19456
	ds_read_b128 v[214:217], v167 offset:20480
	ds_read_b128 v[218:221], v167 offset:21504
	ds_read_b128 v[222:225], v167 offset:22528
	ds_read_b128 v[226:229], v167 offset:23552
	global_load_lds_dwordx4 v[156:157], off
	s_add_i32 m0, s52, 0x2000
	s_add_u32 s52, s26, 0x40000
	v_lshl_add_u64 v[230:231], s[26:27], 0, v[142:143]
	s_addc_u32 s53, s27, 0
	s_add_i32 s54, s45, s34
	global_load_lds_dwordx4 v[230:231], off
	v_lshl_add_u64 v[232:233], s[52:53], 0, v[138:139]
	s_mov_b32 m0, s54
	v_lshl_add_u64 v[234:235], s[28:29], 0, v[140:141]
	global_load_lds_dwordx4 v[232:233], off
	v_lshl_add_u64 v[232:233], s[52:53], 0, v[142:143]
	s_add_i32 m0, s54, 0x2000
	s_nop 0
	global_load_lds_dwordx4 v[232:233], off
	v_lshl_add_u64 v[232:233], s[28:29], 0, v[136:137]
	s_mov_b32 m0, s23
	s_nop 0
	global_load_lds_dwordx4 v[232:233], off
	s_mov_b32 m0, s35
	s_nop 0
	global_load_lds_dwordx4 v[234:235], off
	s_waitcnt vmcnt(8)
	s_waitcnt lgkmcnt(0)
	s_barrier
	s_waitcnt lgkmcnt(0)
	v_mfma_f32_16x16x32_bf16 v[92:95], v[128:131], v[198:201], v[92:95]
	v_mfma_f32_16x16x32_bf16 v[88:91], v[172:175], v[198:201], v[88:91]
	v_mfma_f32_16x16x32_bf16 v[84:87], v[128:131], v[206:209], v[84:87]
	v_mfma_f32_16x16x32_bf16 v[80:83], v[172:175], v[206:209], v[80:83]
	v_mfma_f32_16x16x32_bf16 v[76:79], v[128:131], v[214:217], v[76:79]
	v_mfma_f32_16x16x32_bf16 v[68:71], v[172:175], v[214:217], v[68:71]
	v_mfma_f32_16x16x32_bf16 v[60:63], v[128:131], v[222:225], v[60:63]
	v_mfma_f32_16x16x32_bf16 v[52:55], v[172:175], v[222:225], v[52:55]
	v_mfma_f32_16x16x32_bf16 v[92:95], v[132:135], v[202:205], v[92:95]
	v_mfma_f32_16x16x32_bf16 v[88:91], v[176:179], v[202:205], v[88:91]
	v_mfma_f32_16x16x32_bf16 v[84:87], v[132:135], v[210:213], v[84:87]
	v_mfma_f32_16x16x32_bf16 v[80:83], v[176:179], v[210:213], v[80:83]
	v_mfma_f32_16x16x32_bf16 v[76:79], v[132:135], v[218:221], v[76:79]
	v_mfma_f32_16x16x32_bf16 v[68:71], v[176:179], v[218:221], v[68:71]
	v_mfma_f32_16x16x32_bf16 v[60:63], v[132:135], v[226:229], v[60:63]
	v_mfma_f32_16x16x32_bf16 v[52:55], v[176:179], v[226:229], v[52:55]
	v_mfma_f32_16x16x32_bf16 v[28:31], v[180:183], v[198:201], v[28:31]
	v_mfma_f32_16x16x32_bf16 v[24:27], v[190:193], v[198:201], v[24:27]
	v_mfma_f32_16x16x32_bf16 v[20:23], v[180:183], v[206:209], v[20:23]
	v_mfma_f32_16x16x32_bf16 v[16:19], v[190:193], v[206:209], v[16:19]
	v_mfma_f32_16x16x32_bf16 v[12:15], v[180:183], v[214:217], v[12:15]
	v_mfma_f32_16x16x32_bf16 v[8:11], v[190:193], v[214:217], v[8:11]
	v_mfma_f32_16x16x32_bf16 v[4:7], v[180:183], v[222:225], v[4:7]
	v_mfma_f32_16x16x32_bf16 v[0:3], v[190:193], v[222:225], v[0:3]
	v_mfma_f32_16x16x32_bf16 v[28:31], v[186:189], v[202:205], v[28:31]
	v_mfma_f32_16x16x32_bf16 v[24:27], v[194:197], v[202:205], v[24:27]
	v_mfma_f32_16x16x32_bf16 v[20:23], v[186:189], v[210:213], v[20:23]
	v_mfma_f32_16x16x32_bf16 v[16:19], v[194:197], v[210:213], v[16:19]
	v_mfma_f32_16x16x32_bf16 v[12:15], v[186:189], v[218:221], v[12:15]
	v_mfma_f32_16x16x32_bf16 v[8:11], v[194:197], v[218:221], v[8:11]
	v_mfma_f32_16x16x32_bf16 v[4:7], v[186:189], v[226:229], v[4:7]
	v_mfma_f32_16x16x32_bf16 v[0:3], v[194:197], v[226:229], v[0:3]
	s_barrier
	s_add_i32 s52, 0, 0x18000
	v_add_u32_e32 v158, s52, v161
	s_add_i32 s53, 0, 0x1c000
	ds_read_b128 v[128:131], v158
	ds_read_b128 v[132:135], v158 offset:1024
	ds_read_b128 v[172:175], v158 offset:2048
	ds_read_b128 v[176:179], v158 offset:3072
	v_add_u32_e32 v158, s53, v161
	ds_read_b128 v[180:183], v158
	ds_read_b128 v[186:189], v158 offset:1024
	ds_read_b128 v[190:193], v158 offset:2048
	ds_read_b128 v[194:197], v158 offset:3072
	s_add_u32 s28, s28, 0x40000
	s_addc_u32 s29, s29, 0
	s_mov_b32 m0, s36
	v_lshl_add_u64 v[236:237], s[28:29], 0, v[136:137]
	ds_read_b128 v[198:201], v167 offset:32768
	ds_read_b128 v[202:205], v167 offset:33792
	ds_read_b128 v[206:209], v167 offset:34816
	ds_read_b128 v[210:213], v167 offset:35840
	ds_read_b128 v[214:217], v167 offset:36864
	ds_read_b128 v[218:221], v167 offset:37888
	ds_read_b128 v[222:225], v167 offset:38912
	ds_read_b128 v[226:229], v167 offset:39936
	global_load_lds_dwordx4 v[236:237], off
	v_lshl_add_u64 v[236:237], s[28:29], 0, v[140:141]
	s_mov_b32 m0, s37
	s_nop 0
	global_load_lds_dwordx4 v[236:237], off
	s_waitcnt vmcnt(8)
	s_waitcnt lgkmcnt(0)
	s_barrier
	s_waitcnt lgkmcnt(0)
	v_mfma_f32_16x16x32_bf16 v[124:127], v[128:131], v[198:201], v[124:127]
	v_mfma_f32_16x16x32_bf16 v[120:123], v[172:175], v[198:201], v[120:123]
	v_mfma_f32_16x16x32_bf16 v[116:119], v[128:131], v[206:209], v[116:119]
	v_mfma_f32_16x16x32_bf16 v[112:115], v[172:175], v[206:209], v[112:115]
	v_mfma_f32_16x16x32_bf16 v[108:111], v[128:131], v[214:217], v[108:111]
	v_mfma_f32_16x16x32_bf16 v[104:107], v[172:175], v[214:217], v[104:107]
	v_mfma_f32_16x16x32_bf16 v[100:103], v[128:131], v[222:225], v[100:103]
	v_mfma_f32_16x16x32_bf16 v[96:99], v[172:175], v[222:225], v[96:99]
	v_mfma_f32_16x16x32_bf16 v[124:127], v[132:135], v[202:205], v[124:127]
	v_mfma_f32_16x16x32_bf16 v[120:123], v[176:179], v[202:205], v[120:123]
	v_mfma_f32_16x16x32_bf16 v[116:119], v[132:135], v[210:213], v[116:119]
	v_mfma_f32_16x16x32_bf16 v[112:115], v[176:179], v[210:213], v[112:115]
	v_mfma_f32_16x16x32_bf16 v[108:111], v[132:135], v[218:221], v[108:111]
	v_mfma_f32_16x16x32_bf16 v[104:107], v[176:179], v[218:221], v[104:107]
	v_mfma_f32_16x16x32_bf16 v[100:103], v[132:135], v[226:229], v[100:103]
	v_mfma_f32_16x16x32_bf16 v[96:99], v[176:179], v[226:229], v[96:99]
	v_mfma_f32_16x16x32_bf16 v[72:75], v[180:183], v[198:201], v[72:75]
	v_mfma_f32_16x16x32_bf16 v[64:67], v[190:193], v[198:201], v[64:67]
	v_mfma_f32_16x16x32_bf16 v[56:59], v[180:183], v[206:209], v[56:59]
	v_mfma_f32_16x16x32_bf16 v[48:51], v[190:193], v[206:209], v[48:51]
	v_mfma_f32_16x16x32_bf16 v[44:47], v[180:183], v[214:217], v[44:47]
	v_mfma_f32_16x16x32_bf16 v[40:43], v[190:193], v[214:217], v[40:43]
	v_mfma_f32_16x16x32_bf16 v[36:39], v[180:183], v[222:225], v[36:39]
	v_mfma_f32_16x16x32_bf16 v[32:35], v[190:193], v[222:225], v[32:35]
	v_mfma_f32_16x16x32_bf16 v[72:75], v[186:189], v[202:205], v[72:75]
	v_mfma_f32_16x16x32_bf16 v[64:67], v[194:197], v[202:205], v[64:67]
	v_mfma_f32_16x16x32_bf16 v[56:59], v[186:189], v[210:213], v[56:59]
	v_mfma_f32_16x16x32_bf16 v[48:51], v[194:197], v[210:213], v[48:51]
	v_mfma_f32_16x16x32_bf16 v[44:47], v[186:189], v[218:221], v[44:47]
	v_mfma_f32_16x16x32_bf16 v[40:43], v[194:197], v[218:221], v[40:43]
	v_mfma_f32_16x16x32_bf16 v[36:39], v[186:189], v[226:229], v[36:39]
	v_mfma_f32_16x16x32_bf16 v[32:35], v[194:197], v[226:229], v[32:35]
	s_barrier
	s_add_i32 s28, s52, s34
	v_lshl_add_u64 v[156:157], v[156:157], 0, s[10:11]
	s_mov_b32 m0, s28
	ds_read_b128 v[198:201], v167 offset:49152
	ds_read_b128 v[202:205], v167 offset:50176
	ds_read_b128 v[206:209], v167 offset:51200
	ds_read_b128 v[210:213], v167 offset:52224
	ds_read_b128 v[214:217], v167 offset:53248
	ds_read_b128 v[218:221], v167 offset:54272
	ds_read_b128 v[222:225], v167 offset:55296
	ds_read_b128 v[226:229], v167 offset:56320
	global_load_lds_dwordx4 v[156:157], off
	s_add_i32 m0, s28, 0x2000
	s_add_u32 s26, s26, 0x40080
	v_lshl_add_u64 v[156:157], v[230:231], 0, s[10:11]
	s_addc_u32 s27, s27, 0
	s_add_i32 s28, s53, s34
	global_load_lds_dwordx4 v[156:157], off
	v_lshl_add_u64 v[156:157], s[26:27], 0, v[138:139]
	s_mov_b32 m0, s28
	s_nop 0
	global_load_lds_dwordx4 v[156:157], off
	v_lshl_add_u64 v[156:157], s[26:27], 0, v[142:143]
	s_add_i32 m0, s28, 0x2000
	s_nop 0
	global_load_lds_dwordx4 v[156:157], off
	v_lshl_add_u64 v[156:157], v[232:233], 0, s[10:11]
	s_mov_b32 m0, s39
	s_nop 0
	global_load_lds_dwordx4 v[156:157], off
	v_lshl_add_u64 v[156:157], v[234:235], 0, s[10:11]
	s_mov_b32 m0, s40
	s_nop 0
	global_load_lds_dwordx4 v[156:157], off
	s_waitcnt vmcnt(8)
	s_waitcnt lgkmcnt(0)
	s_barrier
	s_waitcnt lgkmcnt(0)
	v_mfma_f32_16x16x32_bf16 v[92:95], v[128:131], v[198:201], v[92:95]
	v_mfma_f32_16x16x32_bf16 v[88:91], v[172:175], v[198:201], v[88:91]
	v_mfma_f32_16x16x32_bf16 v[84:87], v[128:131], v[206:209], v[84:87]
	v_mfma_f32_16x16x32_bf16 v[80:83], v[172:175], v[206:209], v[80:83]
	v_mfma_f32_16x16x32_bf16 v[76:79], v[128:131], v[214:217], v[76:79]
	v_mfma_f32_16x16x32_bf16 v[68:71], v[172:175], v[214:217], v[68:71]
	v_mfma_f32_16x16x32_bf16 v[60:63], v[128:131], v[222:225], v[60:63]
	v_mfma_f32_16x16x32_bf16 v[52:55], v[172:175], v[222:225], v[52:55]
	v_mfma_f32_16x16x32_bf16 v[92:95], v[132:135], v[202:205], v[92:95]
	v_mfma_f32_16x16x32_bf16 v[88:91], v[176:179], v[202:205], v[88:91]
	v_mfma_f32_16x16x32_bf16 v[84:87], v[132:135], v[210:213], v[84:87]
	v_mfma_f32_16x16x32_bf16 v[80:83], v[176:179], v[210:213], v[80:83]
	v_mfma_f32_16x16x32_bf16 v[76:79], v[132:135], v[218:221], v[76:79]
	v_mfma_f32_16x16x32_bf16 v[68:71], v[176:179], v[218:221], v[68:71]
	v_mfma_f32_16x16x32_bf16 v[60:63], v[132:135], v[226:229], v[60:63]
	v_mfma_f32_16x16x32_bf16 v[52:55], v[176:179], v[226:229], v[52:55]
	v_mfma_f32_16x16x32_bf16 v[28:31], v[180:183], v[198:201], v[28:31]
	v_mfma_f32_16x16x32_bf16 v[24:27], v[190:193], v[198:201], v[24:27]
	v_mfma_f32_16x16x32_bf16 v[20:23], v[180:183], v[206:209], v[20:23]
	v_mfma_f32_16x16x32_bf16 v[16:19], v[190:193], v[206:209], v[16:19]
	v_mfma_f32_16x16x32_bf16 v[12:15], v[180:183], v[214:217], v[12:15]
	v_mfma_f32_16x16x32_bf16 v[8:11], v[190:193], v[214:217], v[8:11]
	v_mfma_f32_16x16x32_bf16 v[4:7], v[180:183], v[222:225], v[4:7]
	v_mfma_f32_16x16x32_bf16 v[0:3], v[190:193], v[222:225], v[0:3]
	v_mfma_f32_16x16x32_bf16 v[28:31], v[186:189], v[202:205], v[28:31]
	v_mfma_f32_16x16x32_bf16 v[24:27], v[194:197], v[202:205], v[24:27]
	v_mfma_f32_16x16x32_bf16 v[20:23], v[186:189], v[210:213], v[20:23]
	v_mfma_f32_16x16x32_bf16 v[16:19], v[194:197], v[210:213], v[16:19]
	v_mfma_f32_16x16x32_bf16 v[12:15], v[186:189], v[218:221], v[12:15]
	v_mfma_f32_16x16x32_bf16 v[8:11], v[194:197], v[218:221], v[8:11]
	v_mfma_f32_16x16x32_bf16 v[4:7], v[186:189], v[226:229], v[4:7]
	v_mfma_f32_16x16x32_bf16 v[0:3], v[194:197], v[226:229], v[0:3]
	s_barrier
	s_add_i32 s51, s51, 2
	s_add_u32 s24, s24, 0x100
	s_addc_u32 s25, s25, 0
	s_add_u32 s49, s49, 0x100
	s_addc_u32 s50, s50, 0
	s_cmp_gt_u32 s51, 13
	s_cbranch_scc0 .LBB0_1727
	s_and_b64 vcc, exec, s[12:13]
	s_cbranch_vccz .LBB0_1730
	s_barrier

.LBB0_1886:
	ds_read_b128 v[128:131], v188
	ds_read_b128 v[132:135], v188 offset:1024
	ds_read_b128 v[136:139], v188 offset:2048
	ds_read_b128 v[140:143], v188 offset:3072
	ds_read_b128 v[144:147], v189
	ds_read_b128 v[148:151], v189 offset:1024
	ds_read_b128 v[172:175], v189 offset:2048
	ds_read_b128 v[176:179], v189 offset:3072
	s_add_u32 s30, s28, 0xfffc0080
	s_addc_u32 s31, s29, -1
	s_cmp_eq_u32 s53, 12
	s_cselect_b32 s35, s17, s31
	s_cselect_b32 s34, s25, s30
	s_cselect_b32 s31, s19, s52
	s_cselect_b32 s30, s27, s51
	v_lshl_add_u64 v[220:221], s[28:29], 0, v[164:165]
	s_add_i32 m0, s39, 0xc000
	ds_read_b128 v[180:183], v190
	ds_read_b128 v[192:195], v190 offset:1024
	ds_read_b128 v[196:199], v190 offset:2048
	ds_read_b128 v[200:203], v190 offset:3072
	ds_read_b128 v[204:207], v190 offset:4096
	ds_read_b128 v[208:211], v190 offset:5120
	ds_read_b128 v[212:215], v190 offset:6144
	ds_read_b128 v[216:219], v190 offset:7168
	global_load_lds_dwordx4 v[220:221], off
	v_lshl_add_u64 v[220:221], s[28:29], 0, v[166:167]
	s_add_i32 m0, s39, 0xe000
	s_nop 0
	global_load_lds_dwordx4 v[220:221], off
	s_waitcnt vmcnt(8)
	s_waitcnt lgkmcnt(0)
	s_barrier
	s_waitcnt lgkmcnt(0)
	v_mfma_f32_16x16x32_bf16 v[124:127], v[128:131], v[180:183], v[124:127]
	v_mfma_f32_16x16x32_bf16 v[120:123], v[136:139], v[180:183], v[120:123]
	v_mfma_f32_16x16x32_bf16 v[108:111], v[128:131], v[196:199], v[108:111]
	v_mfma_f32_16x16x32_bf16 v[104:107], v[136:139], v[196:199], v[104:107]
	v_mfma_f32_16x16x32_bf16 v[92:95], v[128:131], v[204:207], v[92:95]
	v_mfma_f32_16x16x32_bf16 v[88:91], v[136:139], v[204:207], v[88:91]
	v_mfma_f32_16x16x32_bf16 v[76:79], v[128:131], v[212:215], v[76:79]
	v_mfma_f32_16x16x32_bf16 v[72:75], v[136:139], v[212:215], v[72:75]
	v_mfma_f32_16x16x32_bf16 v[124:127], v[132:135], v[192:195], v[124:127]
	v_mfma_f32_16x16x32_bf16 v[120:123], v[140:143], v[192:195], v[120:123]
	v_mfma_f32_16x16x32_bf16 v[108:111], v[132:135], v[200:203], v[108:111]
	v_mfma_f32_16x16x32_bf16 v[104:107], v[140:143], v[200:203], v[104:107]
	v_mfma_f32_16x16x32_bf16 v[92:95], v[132:135], v[208:211], v[92:95]
	v_mfma_f32_16x16x32_bf16 v[88:91], v[140:143], v[208:211], v[88:91]
	v_mfma_f32_16x16x32_bf16 v[76:79], v[132:135], v[216:219], v[76:79]
	v_mfma_f32_16x16x32_bf16 v[72:75], v[140:143], v[216:219], v[72:75]
	v_mfma_f32_16x16x32_bf16 v[116:119], v[144:147], v[180:183], v[116:119]
	v_mfma_f32_16x16x32_bf16 v[112:115], v[172:175], v[180:183], v[112:115]
	v_mfma_f32_16x16x32_bf16 v[100:103], v[144:147], v[196:199], v[100:103]
	v_mfma_f32_16x16x32_bf16 v[96:99], v[172:175], v[196:199], v[96:99]
	v_mfma_f32_16x16x32_bf16 v[84:87], v[144:147], v[204:207], v[84:87]
	v_mfma_f32_16x16x32_bf16 v[80:83], v[172:175], v[204:207], v[80:83]
	v_mfma_f32_16x16x32_bf16 v[68:71], v[144:147], v[212:215], v[68:71]
	v_mfma_f32_16x16x32_bf16 v[64:67], v[172:175], v[212:215], v[64:67]
	v_mfma_f32_16x16x32_bf16 v[116:119], v[148:151], v[192:195], v[116:119]
	v_mfma_f32_16x16x32_bf16 v[112:115], v[176:179], v[192:195], v[112:115]
	v_mfma_f32_16x16x32_bf16 v[100:103], v[148:151], v[200:203], v[100:103]
	v_mfma_f32_16x16x32_bf16 v[96:99], v[176:179], v[200:203], v[96:99]
	v_mfma_f32_16x16x32_bf16 v[84:87], v[148:151], v[208:211], v[84:87]
	v_mfma_f32_16x16x32_bf16 v[80:83], v[176:179], v[208:211], v[80:83]
	v_mfma_f32_16x16x32_bf16 v[68:71], v[148:151], v[216:219], v[68:71]
	v_mfma_f32_16x16x32_bf16 v[64:67], v[176:179], v[216:219], v[64:67]
	s_barrier
	s_add_i32 s54, s49, s38
	v_lshl_add_u64 v[220:221], s[30:31], 0, v[154:155]
	s_mov_b32 m0, s54
	ds_read_b128 v[180:183], v190 offset:16384
	ds_read_b128 v[192:195], v190 offset:17408
	ds_read_b128 v[196:199], v190 offset:18432
	ds_read_b128 v[200:203], v190 offset:19456
	ds_read_b128 v[204:207], v190 offset:20480
	ds_read_b128 v[208:211], v190 offset:21504
	ds_read_b128 v[212:215], v190 offset:22528
	ds_read_b128 v[216:219], v190 offset:23552
	global_load_lds_dwordx4 v[220:221], off
	s_add_i32 m0, s54, 0x2000
	s_add_u32 s54, s30, 0x40000
	v_lshl_add_u64 v[222:223], s[30:31], 0, v[158:159]
	s_addc_u32 s55, s31, 0
	s_add_i32 s56, s50, s38
	global_load_lds_dwordx4 v[222:223], off
	v_lshl_add_u64 v[224:225], s[54:55], 0, v[154:155]
	s_mov_b32 m0, s56
	v_lshl_add_u64 v[226:227], s[34:35], 0, v[156:157]
	global_load_lds_dwordx4 v[224:225], off
	v_lshl_add_u64 v[224:225], s[54:55], 0, v[158:159]
	s_add_i32 m0, s56, 0x2000
	s_nop 0
	global_load_lds_dwordx4 v[224:225], off
	v_lshl_add_u64 v[224:225], s[34:35], 0, v[152:153]
	s_mov_b32 m0, s39
	s_nop 0
	global_load_lds_dwordx4 v[224:225], off
	s_mov_b32 m0, s40
	s_nop 0
	global_load_lds_dwordx4 v[226:227], off
	s_waitcnt vmcnt(8)
	s_waitcnt lgkmcnt(0)
	s_barrier
	s_waitcnt lgkmcnt(0)
	v_mfma_f32_16x16x32_bf16 v[60:63], v[128:131], v[180:183], v[60:63]
	v_mfma_f32_16x16x32_bf16 v[56:59], v[136:139], v[180:183], v[56:59]
	v_mfma_f32_16x16x32_bf16 v[44:47], v[128:131], v[196:199], v[44:47]
	v_mfma_f32_16x16x32_bf16 v[40:43], v[136:139], v[196:199], v[40:43]
	v_mfma_f32_16x16x32_bf16 v[28:31], v[128:131], v[204:207], v[28:31]
	v_mfma_f32_16x16x32_bf16 v[24:27], v[136:139], v[204:207], v[24:27]
	v_mfma_f32_16x16x32_bf16 v[12:15], v[128:131], v[212:215], v[12:15]
	v_mfma_f32_16x16x32_bf16 v[8:11], v[136:139], v[212:215], v[8:11]
	v_mfma_f32_16x16x32_bf16 v[60:63], v[132:135], v[192:195], v[60:63]
	v_mfma_f32_16x16x32_bf16 v[56:59], v[140:143], v[192:195], v[56:59]
	v_mfma_f32_16x16x32_bf16 v[44:47], v[132:135], v[200:203], v[44:47]
	v_mfma_f32_16x16x32_bf16 v[40:43], v[140:143], v[200:203], v[40:43]
	v_mfma_f32_16x16x32_bf16 v[28:31], v[132:135], v[208:211], v[28:31]
	v_mfma_f32_16x16x32_bf16 v[24:27], v[140:143], v[208:211], v[24:27]
	v_mfma_f32_16x16x32_bf16 v[12:15], v[132:135], v[216:219], v[12:15]
	v_mfma_f32_16x16x32_bf16 v[8:11], v[140:143], v[216:219], v[8:11]
	v_mfma_f32_16x16x32_bf16 v[52:55], v[144:147], v[180:183], v[52:55]
	v_mfma_f32_16x16x32_bf16 v[48:51], v[172:175], v[180:183], v[48:51]
	v_mfma_f32_16x16x32_bf16 v[36:39], v[144:147], v[196:199], v[36:39]
	v_mfma_f32_16x16x32_bf16 v[32:35], v[172:175], v[196:199], v[32:35]
	v_mfma_f32_16x16x32_bf16 v[20:23], v[144:147], v[204:207], v[20:23]
	v_mfma_f32_16x16x32_bf16 v[16:19], v[172:175], v[204:207], v[16:19]
	v_mfma_f32_16x16x32_bf16 v[4:7], v[144:147], v[212:215], v[4:7]
	v_mfma_f32_16x16x32_bf16 v[0:3], v[172:175], v[212:215], v[0:3]
	v_mfma_f32_16x16x32_bf16 v[52:55], v[148:151], v[192:195], v[52:55]
	v_mfma_f32_16x16x32_bf16 v[48:51], v[176:179], v[192:195], v[48:51]
	v_mfma_f32_16x16x32_bf16 v[36:39], v[148:151], v[200:203], v[36:39]
	v_mfma_f32_16x16x32_bf16 v[32:35], v[176:179], v[200:203], v[32:35]
	v_mfma_f32_16x16x32_bf16 v[20:23], v[148:151], v[208:211], v[20:23]
	v_mfma_f32_16x16x32_bf16 v[16:19], v[176:179], v[208:211], v[16:19]
	v_mfma_f32_16x16x32_bf16 v[4:7], v[148:151], v[216:219], v[4:7]
	v_mfma_f32_16x16x32_bf16 v[0:3], v[176:179], v[216:219], v[0:3]
	s_barrier
	s_add_i32 s54, 0, 0x18000
	s_add_i32 s55, 0, 0x1c000
	v_add_u32_e32 v140, s54, v184
	v_add_u32_e32 v176, s55, v184
	ds_read_b128 v[128:131], v140
	ds_read_b128 v[132:135], v140 offset:1024
	ds_read_b128 v[136:139], v140 offset:2048
	ds_read_b128 v[140:143], v140 offset:3072
	ds_read_b128 v[144:147], v176
	ds_read_b128 v[148:151], v176 offset:1024
	ds_read_b128 v[172:175], v176 offset:2048
	ds_read_b128 v[176:179], v176 offset:3072
	s_add_u32 s34, s34, 0x40000
	s_addc_u32 s35, s35, 0
	s_mov_b32 m0, s41
	v_lshl_add_u64 v[228:229], s[34:35], 0, v[152:153]
	ds_read_b128 v[180:183], v190 offset:32768
	ds_read_b128 v[192:195], v190 offset:33792
	ds_read_b128 v[196:199], v190 offset:34816
	ds_read_b128 v[200:203], v190 offset:35840
	ds_read_b128 v[204:207], v190 offset:36864
	ds_read_b128 v[208:211], v190 offset:37888
	ds_read_b128 v[212:215], v190 offset:38912
	ds_read_b128 v[216:219], v190 offset:39936
	global_load_lds_dwordx4 v[228:229], off
	v_lshl_add_u64 v[228:229], s[34:35], 0, v[156:157]
	s_mov_b32 m0, s42
	s_nop 0
	global_load_lds_dwordx4 v[228:229], off
	s_waitcnt vmcnt(8)
	s_waitcnt lgkmcnt(0)
	s_barrier
	s_waitcnt lgkmcnt(0)
	v_mfma_f32_16x16x32_bf16 v[124:127], v[128:131], v[180:183], v[124:127]
	v_mfma_f32_16x16x32_bf16 v[120:123], v[136:139], v[180:183], v[120:123]
	v_mfma_f32_16x16x32_bf16 v[108:111], v[128:131], v[196:199], v[108:111]
	v_mfma_f32_16x16x32_bf16 v[104:107], v[136:139], v[196:199], v[104:107]
	v_mfma_f32_16x16x32_bf16 v[92:95], v[128:131], v[204:207], v[92:95]
	v_mfma_f32_16x16x32_bf16 v[88:91], v[136:139], v[204:207], v[88:91]
	v_mfma_f32_16x16x32_bf16 v[76:79], v[128:131], v[212:215], v[76:79]
	v_mfma_f32_16x16x32_bf16 v[72:75], v[136:139], v[212:215], v[72:75]
	v_mfma_f32_16x16x32_bf16 v[124:127], v[132:135], v[192:195], v[124:127]
	v_mfma_f32_16x16x32_bf16 v[120:123], v[140:143], v[192:195], v[120:123]
	v_mfma_f32_16x16x32_bf16 v[108:111], v[132:135], v[200:203], v[108:111]
	v_mfma_f32_16x16x32_bf16 v[104:107], v[140:143], v[200:203], v[104:107]
	v_mfma_f32_16x16x32_bf16 v[92:95], v[132:135], v[208:211], v[92:95]
	v_mfma_f32_16x16x32_bf16 v[88:91], v[140:143], v[208:211], v[88:91]
	v_mfma_f32_16x16x32_bf16 v[76:79], v[132:135], v[216:219], v[76:79]
	v_mfma_f32_16x16x32_bf16 v[72:75], v[140:143], v[216:219], v[72:75]
	v_mfma_f32_16x16x32_bf16 v[116:119], v[144:147], v[180:183], v[116:119]
	v_mfma_f32_16x16x32_bf16 v[112:115], v[172:175], v[180:183], v[112:115]
	v_mfma_f32_16x16x32_bf16 v[100:103], v[144:147], v[196:199], v[100:103]
	v_mfma_f32_16x16x32_bf16 v[96:99], v[172:175], v[196:199], v[96:99]
	v_mfma_f32_16x16x32_bf16 v[84:87], v[144:147], v[204:207], v[84:87]
	v_mfma_f32_16x16x32_bf16 v[80:83], v[172:175], v[204:207], v[80:83]
	v_mfma_f32_16x16x32_bf16 v[68:71], v[144:147], v[212:215], v[68:71]
	v_mfma_f32_16x16x32_bf16 v[64:67], v[172:175], v[212:215], v[64:67]
	v_mfma_f32_16x16x32_bf16 v[116:119], v[148:151], v[192:195], v[116:119]
	v_mfma_f32_16x16x32_bf16 v[112:115], v[176:179], v[192:195], v[112:115]
	v_mfma_f32_16x16x32_bf16 v[100:103], v[148:151], v[200:203], v[100:103]
	v_mfma_f32_16x16x32_bf16 v[96:99], v[176:179], v[200:203], v[96:99]
	v_mfma_f32_16x16x32_bf16 v[84:87], v[148:151], v[208:211], v[84:87]
	v_mfma_f32_16x16x32_bf16 v[80:83], v[176:179], v[208:211], v[80:83]
	v_mfma_f32_16x16x32_bf16 v[68:71], v[148:151], v[216:219], v[68:71]
	v_mfma_f32_16x16x32_bf16 v[64:67], v[176:179], v[216:219], v[64:67]
	s_barrier
	s_add_i32 s34, s54, s38
	v_lshl_add_u64 v[220:221], v[220:221], 0, s[12:13]
	s_mov_b32 m0, s34
	ds_read_b128 v[180:183], v190 offset:49152
	ds_read_b128 v[192:195], v190 offset:50176
	ds_read_b128 v[196:199], v190 offset:51200
	ds_read_b128 v[200:203], v190 offset:52224
	ds_read_b128 v[204:207], v190 offset:53248
	ds_read_b128 v[208:211], v190 offset:54272
	ds_read_b128 v[212:215], v190 offset:55296
	ds_read_b128 v[216:219], v190 offset:56320
	global_load_lds_dwordx4 v[220:221], off
	s_add_i32 m0, s34, 0x2000
	s_add_u32 s30, s30, 0x40080
	v_lshl_add_u64 v[220:221], v[222:223], 0, s[12:13]
	s_addc_u32 s31, s31, 0
	s_add_i32 s34, s55, s38
	global_load_lds_dwordx4 v[220:221], off
	v_lshl_add_u64 v[220:221], s[30:31], 0, v[154:155]
	s_mov_b32 m0, s34
	s_nop 0
	global_load_lds_dwordx4 v[220:221], off
	v_lshl_add_u64 v[220:221], s[30:31], 0, v[158:159]
	s_add_i32 m0, s34, 0x2000
	s_nop 0
	global_load_lds_dwordx4 v[220:221], off
	v_lshl_add_u64 v[220:221], v[224:225], 0, s[12:13]
	s_mov_b32 m0, s44
	s_nop 0
	global_load_lds_dwordx4 v[220:221], off
	v_lshl_add_u64 v[220:221], v[226:227], 0, s[12:13]
	s_mov_b32 m0, s45
	s_nop 0
	global_load_lds_dwordx4 v[220:221], off
	s_waitcnt vmcnt(8)
	s_waitcnt lgkmcnt(0)
	s_barrier
	s_waitcnt lgkmcnt(0)
	v_mfma_f32_16x16x32_bf16 v[60:63], v[128:131], v[180:183], v[60:63]
	v_mfma_f32_16x16x32_bf16 v[56:59], v[136:139], v[180:183], v[56:59]
	v_mfma_f32_16x16x32_bf16 v[44:47], v[128:131], v[196:199], v[44:47]
	v_mfma_f32_16x16x32_bf16 v[40:43], v[136:139], v[196:199], v[40:43]
	v_mfma_f32_16x16x32_bf16 v[28:31], v[128:131], v[204:207], v[28:31]
	v_mfma_f32_16x16x32_bf16 v[24:27], v[136:139], v[204:207], v[24:27]
	v_mfma_f32_16x16x32_bf16 v[12:15], v[128:131], v[212:215], v[12:15]
	v_mfma_f32_16x16x32_bf16 v[8:11], v[136:139], v[212:215], v[8:11]
	v_mfma_f32_16x16x32_bf16 v[60:63], v[132:135], v[192:195], v[60:63]
	v_mfma_f32_16x16x32_bf16 v[56:59], v[140:143], v[192:195], v[56:59]
	v_mfma_f32_16x16x32_bf16 v[44:47], v[132:135], v[200:203], v[44:47]
	v_mfma_f32_16x16x32_bf16 v[40:43], v[140:143], v[200:203], v[40:43]
	v_mfma_f32_16x16x32_bf16 v[28:31], v[132:135], v[208:211], v[28:31]
	v_mfma_f32_16x16x32_bf16 v[24:27], v[140:143], v[208:211], v[24:27]
	v_mfma_f32_16x16x32_bf16 v[12:15], v[132:135], v[216:219], v[12:15]
	v_mfma_f32_16x16x32_bf16 v[8:11], v[140:143], v[216:219], v[8:11]
	v_mfma_f32_16x16x32_bf16 v[52:55], v[144:147], v[180:183], v[52:55]
	v_mfma_f32_16x16x32_bf16 v[48:51], v[172:175], v[180:183], v[48:51]
	v_mfma_f32_16x16x32_bf16 v[36:39], v[144:147], v[196:199], v[36:39]
	v_mfma_f32_16x16x32_bf16 v[32:35], v[172:175], v[196:199], v[32:35]
	v_mfma_f32_16x16x32_bf16 v[20:23], v[144:147], v[204:207], v[20:23]
	v_mfma_f32_16x16x32_bf16 v[16:19], v[172:175], v[204:207], v[16:19]
	v_mfma_f32_16x16x32_bf16 v[4:7], v[144:147], v[212:215], v[4:7]
	v_mfma_f32_16x16x32_bf16 v[0:3], v[172:175], v[212:215], v[0:3]
	v_mfma_f32_16x16x32_bf16 v[52:55], v[148:151], v[192:195], v[52:55]
	v_mfma_f32_16x16x32_bf16 v[48:51], v[176:179], v[192:195], v[48:51]
	v_mfma_f32_16x16x32_bf16 v[36:39], v[148:151], v[200:203], v[36:39]
	v_mfma_f32_16x16x32_bf16 v[32:35], v[176:179], v[200:203], v[32:35]
	v_mfma_f32_16x16x32_bf16 v[20:23], v[148:151], v[208:211], v[20:23]
	v_mfma_f32_16x16x32_bf16 v[16:19], v[176:179], v[208:211], v[16:19]
	v_mfma_f32_16x16x32_bf16 v[4:7], v[148:151], v[216:219], v[4:7]
	v_mfma_f32_16x16x32_bf16 v[0:3], v[176:179], v[216:219], v[0:3]
	s_barrier
	s_add_i32 s53, s53, 2
	s_add_u32 s28, s28, 0x100
	s_addc_u32 s29, s29, 0
	s_add_u32 s51, s51, 0x100
	s_addc_u32 s52, s52, 0
	s_cmp_gt_u32 s53, 13
	s_cbranch_scc0 .LBB0_1886
	s_and_b64 vcc, exec, s[14:15]
	s_cbranch_vccz .LBB0_1889
	s_barrier

.LBB0_1975:
	ds_read_b128 v[144:147], v155
	ds_read_b128 v[160:163], v155 offset:1024
	ds_read_b128 v[164:167], v155 offset:2048
	ds_read_b128 v[168:171], v155 offset:3072
	ds_read_b128 v[172:175], v157
	ds_read_b128 v[176:179], v157 offset:1024
	ds_read_b128 v[180:183], v157 offset:2048
	ds_read_b128 v[186:189], v157 offset:3072
	s_add_u32 s26, s24, 0xfffc0080
	s_addc_u32 s27, s25, -1
	s_cmp_eq_u32 s51, 12
	s_cselect_b32 s29, s15, s27
	s_cselect_b32 s28, s47, s26
	s_cselect_b32 s27, s17, s50
	s_cselect_b32 s26, s48, s49
	v_lshl_add_u64 v[222:223], s[24:25], 0, v[136:137]
	s_add_i32 m0, s23, 0xc000
	ds_read_b128 v[190:193], v158
	ds_read_b128 v[194:197], v158 offset:1024
	ds_read_b128 v[198:201], v158 offset:2048
	ds_read_b128 v[202:205], v158 offset:3072
	ds_read_b128 v[206:209], v158 offset:4096
	ds_read_b128 v[210:213], v158 offset:5120
	ds_read_b128 v[214:217], v158 offset:6144
	ds_read_b128 v[218:221], v158 offset:7168
	global_load_lds_dwordx4 v[222:223], off
	v_lshl_add_u64 v[222:223], s[24:25], 0, v[138:139]
	s_add_i32 m0, s23, 0xe000
	s_nop 0
	global_load_lds_dwordx4 v[222:223], off
	s_waitcnt vmcnt(8)
	s_waitcnt lgkmcnt(0)
	s_barrier
	s_waitcnt lgkmcnt(0)
	v_mfma_f32_16x16x32_bf16 v[124:127], v[144:147], v[190:193], v[124:127]
	v_mfma_f32_16x16x32_bf16 v[120:123], v[164:167], v[190:193], v[120:123]
	v_mfma_f32_16x16x32_bf16 v[116:119], v[144:147], v[198:201], v[116:119]
	v_mfma_f32_16x16x32_bf16 v[104:107], v[164:167], v[198:201], v[104:107]
	v_mfma_f32_16x16x32_bf16 v[92:95], v[144:147], v[206:209], v[92:95]
	v_mfma_f32_16x16x32_bf16 v[88:91], v[164:167], v[206:209], v[88:91]
	v_mfma_f32_16x16x32_bf16 v[76:79], v[144:147], v[214:217], v[76:79]
	v_mfma_f32_16x16x32_bf16 v[72:75], v[164:167], v[214:217], v[72:75]
	v_mfma_f32_16x16x32_bf16 v[124:127], v[160:163], v[194:197], v[124:127]
	v_mfma_f32_16x16x32_bf16 v[120:123], v[168:171], v[194:197], v[120:123]
	v_mfma_f32_16x16x32_bf16 v[116:119], v[160:163], v[202:205], v[116:119]
	v_mfma_f32_16x16x32_bf16 v[104:107], v[168:171], v[202:205], v[104:107]
	v_mfma_f32_16x16x32_bf16 v[92:95], v[160:163], v[210:213], v[92:95]
	v_mfma_f32_16x16x32_bf16 v[88:91], v[168:171], v[210:213], v[88:91]
	v_mfma_f32_16x16x32_bf16 v[76:79], v[160:163], v[218:221], v[76:79]
	v_mfma_f32_16x16x32_bf16 v[72:75], v[168:171], v[218:221], v[72:75]
	v_mfma_f32_16x16x32_bf16 v[112:115], v[172:175], v[190:193], v[112:115]
	v_mfma_f32_16x16x32_bf16 v[108:111], v[180:183], v[190:193], v[108:111]
	v_mfma_f32_16x16x32_bf16 v[100:103], v[172:175], v[198:201], v[100:103]
	v_mfma_f32_16x16x32_bf16 v[96:99], v[180:183], v[198:201], v[96:99]
	v_mfma_f32_16x16x32_bf16 v[84:87], v[172:175], v[206:209], v[84:87]
	v_mfma_f32_16x16x32_bf16 v[80:83], v[180:183], v[206:209], v[80:83]
	v_mfma_f32_16x16x32_bf16 v[68:71], v[172:175], v[214:217], v[68:71]
	v_mfma_f32_16x16x32_bf16 v[64:67], v[180:183], v[214:217], v[64:67]
	v_mfma_f32_16x16x32_bf16 v[112:115], v[176:179], v[194:197], v[112:115]
	v_mfma_f32_16x16x32_bf16 v[108:111], v[186:189], v[194:197], v[108:111]
	v_mfma_f32_16x16x32_bf16 v[100:103], v[176:179], v[202:205], v[100:103]
	v_mfma_f32_16x16x32_bf16 v[96:99], v[186:189], v[202:205], v[96:99]
	v_mfma_f32_16x16x32_bf16 v[84:87], v[176:179], v[210:213], v[84:87]
	v_mfma_f32_16x16x32_bf16 v[80:83], v[186:189], v[210:213], v[80:83]
	v_mfma_f32_16x16x32_bf16 v[68:71], v[176:179], v[218:221], v[68:71]
	v_mfma_f32_16x16x32_bf16 v[64:67], v[186:189], v[218:221], v[64:67]
	s_barrier
	s_add_i32 s52, s43, s31
	v_lshl_add_u64 v[222:223], s[26:27], 0, v[132:133]
	s_mov_b32 m0, s52
	ds_read_b128 v[190:193], v158 offset:16384
	ds_read_b128 v[194:197], v158 offset:17408
	ds_read_b128 v[198:201], v158 offset:18432
	ds_read_b128 v[202:205], v158 offset:19456
	ds_read_b128 v[206:209], v158 offset:20480
	ds_read_b128 v[210:213], v158 offset:21504
	ds_read_b128 v[214:217], v158 offset:22528
	ds_read_b128 v[218:221], v158 offset:23552
	global_load_lds_dwordx4 v[222:223], off
	s_add_i32 m0, s52, 0x2000
	s_add_u32 s52, s26, 0x40000
	v_lshl_add_u64 v[224:225], s[26:27], 0, v[128:129]
	s_addc_u32 s53, s27, 0
	s_add_i32 s54, s44, s31
	global_load_lds_dwordx4 v[224:225], off
	v_lshl_add_u64 v[226:227], s[52:53], 0, v[132:133]
	s_mov_b32 m0, s54
	v_lshl_add_u64 v[228:229], s[28:29], 0, v[130:131]
	global_load_lds_dwordx4 v[226:227], off
	v_lshl_add_u64 v[226:227], s[52:53], 0, v[128:129]
	s_add_i32 m0, s54, 0x2000
	s_nop 0
	global_load_lds_dwordx4 v[226:227], off
	v_lshl_add_u64 v[226:227], s[28:29], 0, v[134:135]
	s_mov_b32 m0, s23
	s_nop 0
	global_load_lds_dwordx4 v[226:227], off
	s_mov_b32 m0, s35
	s_nop 0
	global_load_lds_dwordx4 v[228:229], off
	s_waitcnt vmcnt(8)
	s_waitcnt lgkmcnt(0)
	s_barrier
	s_waitcnt lgkmcnt(0)
	v_mfma_f32_16x16x32_bf16 v[60:63], v[144:147], v[190:193], v[60:63]
	v_mfma_f32_16x16x32_bf16 v[56:59], v[164:167], v[190:193], v[56:59]
	v_mfma_f32_16x16x32_bf16 v[44:47], v[144:147], v[198:201], v[44:47]
	v_mfma_f32_16x16x32_bf16 v[40:43], v[164:167], v[198:201], v[40:43]
	v_mfma_f32_16x16x32_bf16 v[28:31], v[144:147], v[206:209], v[28:31]
	v_mfma_f32_16x16x32_bf16 v[24:27], v[164:167], v[206:209], v[24:27]
	v_mfma_f32_16x16x32_bf16 v[12:15], v[144:147], v[214:217], v[12:15]
	v_mfma_f32_16x16x32_bf16 v[8:11], v[164:167], v[214:217], v[8:11]
	v_mfma_f32_16x16x32_bf16 v[60:63], v[160:163], v[194:197], v[60:63]
	v_mfma_f32_16x16x32_bf16 v[56:59], v[168:171], v[194:197], v[56:59]
	v_mfma_f32_16x16x32_bf16 v[44:47], v[160:163], v[202:205], v[44:47]
	v_mfma_f32_16x16x32_bf16 v[40:43], v[168:171], v[202:205], v[40:43]
	v_mfma_f32_16x16x32_bf16 v[28:31], v[160:163], v[210:213], v[28:31]
	v_mfma_f32_16x16x32_bf16 v[24:27], v[168:171], v[210:213], v[24:27]
	v_mfma_f32_16x16x32_bf16 v[12:15], v[160:163], v[218:221], v[12:15]
	v_mfma_f32_16x16x32_bf16 v[8:11], v[168:171], v[218:221], v[8:11]
	v_mfma_f32_16x16x32_bf16 v[52:55], v[172:175], v[190:193], v[52:55]
	v_mfma_f32_16x16x32_bf16 v[48:51], v[180:183], v[190:193], v[48:51]
	v_mfma_f32_16x16x32_bf16 v[36:39], v[172:175], v[198:201], v[36:39]
	v_mfma_f32_16x16x32_bf16 v[32:35], v[180:183], v[198:201], v[32:35]
	v_mfma_f32_16x16x32_bf16 v[20:23], v[172:175], v[206:209], v[20:23]
	v_mfma_f32_16x16x32_bf16 v[16:19], v[180:183], v[206:209], v[16:19]
	v_mfma_f32_16x16x32_bf16 v[4:7], v[172:175], v[214:217], v[4:7]
	v_mfma_f32_16x16x32_bf16 v[0:3], v[180:183], v[214:217], v[0:3]
	v_mfma_f32_16x16x32_bf16 v[52:55], v[176:179], v[194:197], v[52:55]
	v_mfma_f32_16x16x32_bf16 v[48:51], v[186:189], v[194:197], v[48:51]
	v_mfma_f32_16x16x32_bf16 v[36:39], v[176:179], v[202:205], v[36:39]
	v_mfma_f32_16x16x32_bf16 v[32:35], v[186:189], v[202:205], v[32:35]
	v_mfma_f32_16x16x32_bf16 v[20:23], v[176:179], v[210:213], v[20:23]
	v_mfma_f32_16x16x32_bf16 v[16:19], v[186:189], v[210:213], v[16:19]
	v_mfma_f32_16x16x32_bf16 v[4:7], v[176:179], v[218:221], v[4:7]
	v_mfma_f32_16x16x32_bf16 v[0:3], v[186:189], v[218:221], v[0:3]
	s_barrier
	s_add_i32 s52, 0, 0x18000
	v_add_u32_e32 v148, s52, v151
	s_add_i32 s53, 0, 0x1c000
	ds_read_b128 v[144:147], v148
	ds_read_b128 v[160:163], v148 offset:1024
	ds_read_b128 v[164:167], v148 offset:2048
	ds_read_b128 v[168:171], v148 offset:3072
	v_add_u32_e32 v148, s53, v151
	ds_read_b128 v[172:175], v148
	ds_read_b128 v[176:179], v148 offset:1024
	ds_read_b128 v[180:183], v148 offset:2048
	ds_read_b128 v[186:189], v148 offset:3072
	s_add_u32 s28, s28, 0x40000
	s_addc_u32 s29, s29, 0
	s_mov_b32 m0, s36
	v_lshl_add_u64 v[230:231], s[28:29], 0, v[134:135]
	ds_read_b128 v[190:193], v158 offset:32768
	ds_read_b128 v[194:197], v158 offset:33792
	ds_read_b128 v[198:201], v158 offset:34816
	ds_read_b128 v[202:205], v158 offset:35840
	ds_read_b128 v[206:209], v158 offset:36864
	ds_read_b128 v[210:213], v158 offset:37888
	ds_read_b128 v[214:217], v158 offset:38912
	ds_read_b128 v[218:221], v158 offset:39936
	global_load_lds_dwordx4 v[230:231], off
	v_lshl_add_u64 v[230:231], s[28:29], 0, v[130:131]
	s_mov_b32 m0, s37
	s_nop 0
	global_load_lds_dwordx4 v[230:231], off
	s_waitcnt vmcnt(8)
	s_waitcnt lgkmcnt(0)
	s_barrier
	s_waitcnt lgkmcnt(0)
	v_mfma_f32_16x16x32_bf16 v[124:127], v[144:147], v[190:193], v[124:127]
	v_mfma_f32_16x16x32_bf16 v[120:123], v[164:167], v[190:193], v[120:123]
	v_mfma_f32_16x16x32_bf16 v[116:119], v[144:147], v[198:201], v[116:119]
	v_mfma_f32_16x16x32_bf16 v[104:107], v[164:167], v[198:201], v[104:107]
	v_mfma_f32_16x16x32_bf16 v[92:95], v[144:147], v[206:209], v[92:95]
	v_mfma_f32_16x16x32_bf16 v[88:91], v[164:167], v[206:209], v[88:91]
	v_mfma_f32_16x16x32_bf16 v[76:79], v[144:147], v[214:217], v[76:79]
	v_mfma_f32_16x16x32_bf16 v[72:75], v[164:167], v[214:217], v[72:75]
	v_mfma_f32_16x16x32_bf16 v[124:127], v[160:163], v[194:197], v[124:127]
	v_mfma_f32_16x16x32_bf16 v[120:123], v[168:171], v[194:197], v[120:123]
	v_mfma_f32_16x16x32_bf16 v[116:119], v[160:163], v[202:205], v[116:119]
	v_mfma_f32_16x16x32_bf16 v[104:107], v[168:171], v[202:205], v[104:107]
	v_mfma_f32_16x16x32_bf16 v[92:95], v[160:163], v[210:213], v[92:95]
	v_mfma_f32_16x16x32_bf16 v[88:91], v[168:171], v[210:213], v[88:91]
	v_mfma_f32_16x16x32_bf16 v[76:79], v[160:163], v[218:221], v[76:79]
	v_mfma_f32_16x16x32_bf16 v[72:75], v[168:171], v[218:221], v[72:75]
	v_mfma_f32_16x16x32_bf16 v[112:115], v[172:175], v[190:193], v[112:115]
	v_mfma_f32_16x16x32_bf16 v[108:111], v[180:183], v[190:193], v[108:111]
	v_mfma_f32_16x16x32_bf16 v[100:103], v[172:175], v[198:201], v[100:103]
	v_mfma_f32_16x16x32_bf16 v[96:99], v[180:183], v[198:201], v[96:99]
	v_mfma_f32_16x16x32_bf16 v[84:87], v[172:175], v[206:209], v[84:87]
	v_mfma_f32_16x16x32_bf16 v[80:83], v[180:183], v[206:209], v[80:83]
	v_mfma_f32_16x16x32_bf16 v[68:71], v[172:175], v[214:217], v[68:71]
	v_mfma_f32_16x16x32_bf16 v[64:67], v[180:183], v[214:217], v[64:67]
	v_mfma_f32_16x16x32_bf16 v[112:115], v[176:179], v[194:197], v[112:115]
	v_mfma_f32_16x16x32_bf16 v[108:111], v[186:189], v[194:197], v[108:111]
	v_mfma_f32_16x16x32_bf16 v[100:103], v[176:179], v[202:205], v[100:103]
	v_mfma_f32_16x16x32_bf16 v[96:99], v[186:189], v[202:205], v[96:99]
	v_mfma_f32_16x16x32_bf16 v[84:87], v[176:179], v[210:213], v[84:87]
	v_mfma_f32_16x16x32_bf16 v[80:83], v[186:189], v[210:213], v[80:83]
	v_mfma_f32_16x16x32_bf16 v[68:71], v[176:179], v[218:221], v[68:71]
	v_mfma_f32_16x16x32_bf16 v[64:67], v[186:189], v[218:221], v[64:67]
	s_barrier
	s_add_i32 s28, s52, s31
	v_lshl_add_u64 v[222:223], v[222:223], 0, s[10:11]
	s_mov_b32 m0, s28
	ds_read_b128 v[190:193], v158 offset:49152
	ds_read_b128 v[194:197], v158 offset:50176
	ds_read_b128 v[198:201], v158 offset:51200
	ds_read_b128 v[202:205], v158 offset:52224
	ds_read_b128 v[206:209], v158 offset:53248
	ds_read_b128 v[210:213], v158 offset:54272
	ds_read_b128 v[214:217], v158 offset:55296
	ds_read_b128 v[218:221], v158 offset:56320
	global_load_lds_dwordx4 v[222:223], off
	s_add_i32 m0, s28, 0x2000
	s_add_u32 s26, s26, 0x40080
	v_lshl_add_u64 v[222:223], v[224:225], 0, s[10:11]
	s_addc_u32 s27, s27, 0
	s_add_i32 s28, s53, s31
	global_load_lds_dwordx4 v[222:223], off
	v_lshl_add_u64 v[222:223], s[26:27], 0, v[132:133]
	s_mov_b32 m0, s28
	s_nop 0
	global_load_lds_dwordx4 v[222:223], off
	v_lshl_add_u64 v[222:223], s[26:27], 0, v[128:129]
	s_add_i32 m0, s28, 0x2000
	s_nop 0
	global_load_lds_dwordx4 v[222:223], off
	v_lshl_add_u64 v[222:223], v[226:227], 0, s[10:11]
	s_mov_b32 m0, s39
	s_nop 0
	global_load_lds_dwordx4 v[222:223], off
	v_lshl_add_u64 v[222:223], v[228:229], 0, s[10:11]
	s_mov_b32 m0, s40
	s_nop 0
	global_load_lds_dwordx4 v[222:223], off
	s_waitcnt vmcnt(8)
	s_waitcnt lgkmcnt(0)
	s_barrier
	s_waitcnt lgkmcnt(0)
	v_mfma_f32_16x16x32_bf16 v[60:63], v[144:147], v[190:193], v[60:63]
	v_mfma_f32_16x16x32_bf16 v[56:59], v[164:167], v[190:193], v[56:59]
	v_mfma_f32_16x16x32_bf16 v[44:47], v[144:147], v[198:201], v[44:47]
	v_mfma_f32_16x16x32_bf16 v[40:43], v[164:167], v[198:201], v[40:43]
	v_mfma_f32_16x16x32_bf16 v[28:31], v[144:147], v[206:209], v[28:31]
	v_mfma_f32_16x16x32_bf16 v[24:27], v[164:167], v[206:209], v[24:27]
	v_mfma_f32_16x16x32_bf16 v[12:15], v[144:147], v[214:217], v[12:15]
	v_mfma_f32_16x16x32_bf16 v[8:11], v[164:167], v[214:217], v[8:11]
	v_mfma_f32_16x16x32_bf16 v[60:63], v[160:163], v[194:197], v[60:63]
	v_mfma_f32_16x16x32_bf16 v[56:59], v[168:171], v[194:197], v[56:59]
	v_mfma_f32_16x16x32_bf16 v[44:47], v[160:163], v[202:205], v[44:47]
	v_mfma_f32_16x16x32_bf16 v[40:43], v[168:171], v[202:205], v[40:43]
	v_mfma_f32_16x16x32_bf16 v[28:31], v[160:163], v[210:213], v[28:31]
	v_mfma_f32_16x16x32_bf16 v[24:27], v[168:171], v[210:213], v[24:27]
	v_mfma_f32_16x16x32_bf16 v[12:15], v[160:163], v[218:221], v[12:15]
	v_mfma_f32_16x16x32_bf16 v[8:11], v[168:171], v[218:221], v[8:11]
	v_mfma_f32_16x16x32_bf16 v[52:55], v[172:175], v[190:193], v[52:55]
	v_mfma_f32_16x16x32_bf16 v[48:51], v[180:183], v[190:193], v[48:51]
	v_mfma_f32_16x16x32_bf16 v[36:39], v[172:175], v[198:201], v[36:39]
	v_mfma_f32_16x16x32_bf16 v[32:35], v[180:183], v[198:201], v[32:35]
	v_mfma_f32_16x16x32_bf16 v[20:23], v[172:175], v[206:209], v[20:23]
	v_mfma_f32_16x16x32_bf16 v[16:19], v[180:183], v[206:209], v[16:19]
	v_mfma_f32_16x16x32_bf16 v[4:7], v[172:175], v[214:217], v[4:7]
	v_mfma_f32_16x16x32_bf16 v[0:3], v[180:183], v[214:217], v[0:3]
	v_mfma_f32_16x16x32_bf16 v[52:55], v[176:179], v[194:197], v[52:55]
	v_mfma_f32_16x16x32_bf16 v[48:51], v[186:189], v[194:197], v[48:51]
	v_mfma_f32_16x16x32_bf16 v[36:39], v[176:179], v[202:205], v[36:39]
	v_mfma_f32_16x16x32_bf16 v[32:35], v[186:189], v[202:205], v[32:35]
	v_mfma_f32_16x16x32_bf16 v[20:23], v[176:179], v[210:213], v[20:23]
	v_mfma_f32_16x16x32_bf16 v[16:19], v[186:189], v[210:213], v[16:19]
	v_mfma_f32_16x16x32_bf16 v[4:7], v[176:179], v[218:221], v[4:7]
	v_mfma_f32_16x16x32_bf16 v[0:3], v[186:189], v[218:221], v[0:3]
	s_barrier
	s_add_i32 s51, s51, 2
	s_add_u32 s24, s24, 0x100
	s_addc_u32 s25, s25, 0
	s_add_u32 s49, s49, 0x100
	s_addc_u32 s50, s50, 0
	s_cmp_gt_u32 s51, 13
	s_cbranch_scc0 .LBB0_1975
	s_and_b64 vcc, exec, s[12:13]
	s_cbranch_vccz .LBB0_1978
	s_barrier

.LBB0_2058:
	ds_read_b128 v[146:149], v155
	ds_read_b128 v[150:153], v155 offset:1024
	ds_read_b128 v[158:161], v155 offset:2048
	ds_read_b128 v[162:165], v155 offset:3072
	ds_read_b128 v[166:169], v156
	ds_read_b128 v[170:173], v156 offset:1024
	ds_read_b128 v[174:177], v156 offset:2048
	ds_read_b128 v[178:181], v156 offset:3072
	s_add_u32 s20, s18, 0xfff50080
	s_addc_u32 s21, s19, -1
	s_cmp_eq_u32 s43, 40
	s_cselect_b32 s23, s5, s21
	s_cselect_b32 s22, s4, s20
	s_cselect_b32 s21, s15, s42
	s_cselect_b32 s20, s14, s17
	v_lshl_add_u64 v[214:215], s[18:19], 0, v[138:139]
	s_add_i32 m0, s27, 0xc000
	ds_read_b128 v[182:185], v157
	ds_read_b128 v[186:189], v157 offset:1024
	ds_read_b128 v[190:193], v157 offset:2048
	ds_read_b128 v[194:197], v157 offset:3072
	ds_read_b128 v[198:201], v157 offset:4096
	ds_read_b128 v[202:205], v157 offset:5120
	ds_read_b128 v[206:209], v157 offset:6144
	ds_read_b128 v[210:213], v157 offset:7168
	global_load_lds_dwordx4 v[214:215], off
	v_lshl_add_u64 v[214:215], s[18:19], 0, v[140:141]
	s_add_i32 m0, s27, 0xe000
	s_nop 0
	global_load_lds_dwordx4 v[214:215], off
	s_waitcnt vmcnt(8)
	s_waitcnt lgkmcnt(0)
	s_barrier
	s_waitcnt lgkmcnt(0)
	v_mfma_f32_16x16x32_bf16 v[124:127], v[146:149], v[182:185], v[124:127]
	v_mfma_f32_16x16x32_bf16 v[120:123], v[158:161], v[182:185], v[120:123]
	v_mfma_f32_16x16x32_bf16 v[116:119], v[146:149], v[190:193], v[116:119]
	v_mfma_f32_16x16x32_bf16 v[112:115], v[158:161], v[190:193], v[112:115]
	v_mfma_f32_16x16x32_bf16 v[96:99], v[146:149], v[198:201], v[96:99]
	v_mfma_f32_16x16x32_bf16 v[88:91], v[158:161], v[198:201], v[88:91]
	v_mfma_f32_16x16x32_bf16 v[80:83], v[146:149], v[206:209], v[80:83]
	v_mfma_f32_16x16x32_bf16 v[72:75], v[158:161], v[206:209], v[72:75]
	v_mfma_f32_16x16x32_bf16 v[124:127], v[150:153], v[186:189], v[124:127]
	v_mfma_f32_16x16x32_bf16 v[120:123], v[162:165], v[186:189], v[120:123]
	v_mfma_f32_16x16x32_bf16 v[116:119], v[150:153], v[194:197], v[116:119]
	v_mfma_f32_16x16x32_bf16 v[112:115], v[162:165], v[194:197], v[112:115]
	v_mfma_f32_16x16x32_bf16 v[96:99], v[150:153], v[202:205], v[96:99]
	v_mfma_f32_16x16x32_bf16 v[88:91], v[162:165], v[202:205], v[88:91]
	v_mfma_f32_16x16x32_bf16 v[80:83], v[150:153], v[210:213], v[80:83]
	v_mfma_f32_16x16x32_bf16 v[72:75], v[162:165], v[210:213], v[72:75]
	v_mfma_f32_16x16x32_bf16 v[108:111], v[166:169], v[182:185], v[108:111]
	v_mfma_f32_16x16x32_bf16 v[104:107], v[174:177], v[182:185], v[104:107]
	v_mfma_f32_16x16x32_bf16 v[100:103], v[166:169], v[190:193], v[100:103]
	v_mfma_f32_16x16x32_bf16 v[92:95], v[174:177], v[190:193], v[92:95]
	v_mfma_f32_16x16x32_bf16 v[84:87], v[166:169], v[198:201], v[84:87]
	v_mfma_f32_16x16x32_bf16 v[76:79], v[174:177], v[198:201], v[76:79]
	v_mfma_f32_16x16x32_bf16 v[68:71], v[166:169], v[206:209], v[68:71]
	v_mfma_f32_16x16x32_bf16 v[64:67], v[174:177], v[206:209], v[64:67]
	v_mfma_f32_16x16x32_bf16 v[108:111], v[170:173], v[186:189], v[108:111]
	v_mfma_f32_16x16x32_bf16 v[104:107], v[178:181], v[186:189], v[104:107]
	v_mfma_f32_16x16x32_bf16 v[100:103], v[170:173], v[194:197], v[100:103]
	v_mfma_f32_16x16x32_bf16 v[92:95], v[178:181], v[194:197], v[92:95]
	v_mfma_f32_16x16x32_bf16 v[84:87], v[170:173], v[202:205], v[84:87]
	v_mfma_f32_16x16x32_bf16 v[76:79], v[178:181], v[202:205], v[76:79]
	v_mfma_f32_16x16x32_bf16 v[68:71], v[170:173], v[210:213], v[68:71]
	v_mfma_f32_16x16x32_bf16 v[64:67], v[178:181], v[210:213], v[64:67]
	s_barrier
	s_add_i32 s44, s37, s26
	v_lshl_add_u64 v[214:215], s[20:21], 0, v[130:131]
	s_mov_b32 m0, s44
	ds_read_b128 v[182:185], v157 offset:16384
	ds_read_b128 v[186:189], v157 offset:17408
	ds_read_b128 v[190:193], v157 offset:18432
	ds_read_b128 v[194:197], v157 offset:19456
	ds_read_b128 v[198:201], v157 offset:20480
	ds_read_b128 v[202:205], v157 offset:21504
	ds_read_b128 v[206:209], v157 offset:22528
	ds_read_b128 v[210:213], v157 offset:23552
	global_load_lds_dwordx4 v[214:215], off
	s_add_i32 m0, s44, 0x2000
	s_add_u32 s44, s20, 0xb0000
	v_lshl_add_u64 v[216:217], s[20:21], 0, v[134:135]
	s_addc_u32 s45, s21, 0
	s_add_i32 s46, s38, s26
	global_load_lds_dwordx4 v[216:217], off
	v_lshl_add_u64 v[218:219], s[44:45], 0, v[130:131]
	s_mov_b32 m0, s46
	v_lshl_add_u64 v[220:221], s[22:23], 0, v[132:133]
	global_load_lds_dwordx4 v[218:219], off
	v_lshl_add_u64 v[218:219], s[44:45], 0, v[134:135]
	s_add_i32 m0, s46, 0x2000
	s_nop 0
	global_load_lds_dwordx4 v[218:219], off
	v_lshl_add_u64 v[218:219], s[22:23], 0, v[128:129]
	s_mov_b32 m0, s27
	s_nop 0
	global_load_lds_dwordx4 v[218:219], off
	s_mov_b32 m0, s28
	s_nop 0
	global_load_lds_dwordx4 v[220:221], off
	s_waitcnt vmcnt(8)
	s_waitcnt lgkmcnt(0)
	s_barrier
	s_waitcnt lgkmcnt(0)
	v_mfma_f32_16x16x32_bf16 v[60:63], v[146:149], v[182:185], v[60:63]
	v_mfma_f32_16x16x32_bf16 v[56:59], v[158:161], v[182:185], v[56:59]
	v_mfma_f32_16x16x32_bf16 v[48:51], v[146:149], v[190:193], v[48:51]
	v_mfma_f32_16x16x32_bf16 v[40:43], v[158:161], v[190:193], v[40:43]
	v_mfma_f32_16x16x32_bf16 v[32:35], v[146:149], v[198:201], v[32:35]
	v_mfma_f32_16x16x32_bf16 v[24:27], v[158:161], v[198:201], v[24:27]
	v_mfma_f32_16x16x32_bf16 v[16:19], v[146:149], v[206:209], v[16:19]
	v_mfma_f32_16x16x32_bf16 v[8:11], v[158:161], v[206:209], v[8:11]
	v_mfma_f32_16x16x32_bf16 v[60:63], v[150:153], v[186:189], v[60:63]
	v_mfma_f32_16x16x32_bf16 v[56:59], v[162:165], v[186:189], v[56:59]
	v_mfma_f32_16x16x32_bf16 v[48:51], v[150:153], v[194:197], v[48:51]
	v_mfma_f32_16x16x32_bf16 v[40:43], v[162:165], v[194:197], v[40:43]
	v_mfma_f32_16x16x32_bf16 v[32:35], v[150:153], v[202:205], v[32:35]
	v_mfma_f32_16x16x32_bf16 v[24:27], v[162:165], v[202:205], v[24:27]
	v_mfma_f32_16x16x32_bf16 v[16:19], v[150:153], v[210:213], v[16:19]
	v_mfma_f32_16x16x32_bf16 v[8:11], v[162:165], v[210:213], v[8:11]
	v_mfma_f32_16x16x32_bf16 v[52:55], v[166:169], v[182:185], v[52:55]
	v_mfma_f32_16x16x32_bf16 v[44:47], v[174:177], v[182:185], v[44:47]
	v_mfma_f32_16x16x32_bf16 v[36:39], v[166:169], v[190:193], v[36:39]
	v_mfma_f32_16x16x32_bf16 v[28:31], v[174:177], v[190:193], v[28:31]
	v_mfma_f32_16x16x32_bf16 v[20:23], v[166:169], v[198:201], v[20:23]
	v_mfma_f32_16x16x32_bf16 v[12:15], v[174:177], v[198:201], v[12:15]
	v_mfma_f32_16x16x32_bf16 v[4:7], v[166:169], v[206:209], v[4:7]
	v_mfma_f32_16x16x32_bf16 v[0:3], v[174:177], v[206:209], v[0:3]
	v_mfma_f32_16x16x32_bf16 v[52:55], v[170:173], v[186:189], v[52:55]
	v_mfma_f32_16x16x32_bf16 v[44:47], v[178:181], v[186:189], v[44:47]
	v_mfma_f32_16x16x32_bf16 v[36:39], v[170:173], v[194:197], v[36:39]
	v_mfma_f32_16x16x32_bf16 v[28:31], v[178:181], v[194:197], v[28:31]
	v_mfma_f32_16x16x32_bf16 v[20:23], v[170:173], v[202:205], v[20:23]
	v_mfma_f32_16x16x32_bf16 v[12:15], v[178:181], v[202:205], v[12:15]
	v_mfma_f32_16x16x32_bf16 v[4:7], v[170:173], v[210:213], v[4:7]
	v_mfma_f32_16x16x32_bf16 v[0:3], v[178:181], v[210:213], v[0:3]
	s_barrier
	s_add_i32 s44, 0, 0x18000
	s_add_i32 s45, 0, 0x1c000
	v_add_u32_e32 v162, s44, v154
	v_add_u32_e32 v178, s45, v154
	ds_read_b128 v[146:149], v162
	ds_read_b128 v[150:153], v162 offset:1024
	ds_read_b128 v[158:161], v162 offset:2048
	ds_read_b128 v[162:165], v162 offset:3072
	ds_read_b128 v[166:169], v178
	ds_read_b128 v[170:173], v178 offset:1024
	ds_read_b128 v[174:177], v178 offset:2048
	ds_read_b128 v[178:181], v178 offset:3072
	s_add_u32 s22, s22, 0xb0000
	s_addc_u32 s23, s23, 0
	s_mov_b32 m0, s29
	v_lshl_add_u64 v[222:223], s[22:23], 0, v[128:129]
	ds_read_b128 v[182:185], v157 offset:32768
	ds_read_b128 v[186:189], v157 offset:33792
	ds_read_b128 v[190:193], v157 offset:34816
	ds_read_b128 v[194:197], v157 offset:35840
	ds_read_b128 v[198:201], v157 offset:36864
	ds_read_b128 v[202:205], v157 offset:37888
	ds_read_b128 v[206:209], v157 offset:38912
	ds_read_b128 v[210:213], v157 offset:39936
	global_load_lds_dwordx4 v[222:223], off
	v_lshl_add_u64 v[222:223], s[22:23], 0, v[132:133]
	s_mov_b32 m0, s30
	s_nop 0
	global_load_lds_dwordx4 v[222:223], off
	s_waitcnt vmcnt(8)
	s_waitcnt lgkmcnt(0)
	s_barrier
	s_waitcnt lgkmcnt(0)
	v_mfma_f32_16x16x32_bf16 v[124:127], v[146:149], v[182:185], v[124:127]
	v_mfma_f32_16x16x32_bf16 v[120:123], v[158:161], v[182:185], v[120:123]
	v_mfma_f32_16x16x32_bf16 v[116:119], v[146:149], v[190:193], v[116:119]
	v_mfma_f32_16x16x32_bf16 v[112:115], v[158:161], v[190:193], v[112:115]
	v_mfma_f32_16x16x32_bf16 v[96:99], v[146:149], v[198:201], v[96:99]
	v_mfma_f32_16x16x32_bf16 v[88:91], v[158:161], v[198:201], v[88:91]
	v_mfma_f32_16x16x32_bf16 v[80:83], v[146:149], v[206:209], v[80:83]
	v_mfma_f32_16x16x32_bf16 v[72:75], v[158:161], v[206:209], v[72:75]
	v_mfma_f32_16x16x32_bf16 v[124:127], v[150:153], v[186:189], v[124:127]
	v_mfma_f32_16x16x32_bf16 v[120:123], v[162:165], v[186:189], v[120:123]
	v_mfma_f32_16x16x32_bf16 v[116:119], v[150:153], v[194:197], v[116:119]
	v_mfma_f32_16x16x32_bf16 v[112:115], v[162:165], v[194:197], v[112:115]
	v_mfma_f32_16x16x32_bf16 v[96:99], v[150:153], v[202:205], v[96:99]
	v_mfma_f32_16x16x32_bf16 v[88:91], v[162:165], v[202:205], v[88:91]
	v_mfma_f32_16x16x32_bf16 v[80:83], v[150:153], v[210:213], v[80:83]
	v_mfma_f32_16x16x32_bf16 v[72:75], v[162:165], v[210:213], v[72:75]
	v_mfma_f32_16x16x32_bf16 v[108:111], v[166:169], v[182:185], v[108:111]
	v_mfma_f32_16x16x32_bf16 v[104:107], v[174:177], v[182:185], v[104:107]
	v_mfma_f32_16x16x32_bf16 v[100:103], v[166:169], v[190:193], v[100:103]
	v_mfma_f32_16x16x32_bf16 v[92:95], v[174:177], v[190:193], v[92:95]
	v_mfma_f32_16x16x32_bf16 v[84:87], v[166:169], v[198:201], v[84:87]
	v_mfma_f32_16x16x32_bf16 v[76:79], v[174:177], v[198:201], v[76:79]
	v_mfma_f32_16x16x32_bf16 v[68:71], v[166:169], v[206:209], v[68:71]
	v_mfma_f32_16x16x32_bf16 v[64:67], v[174:177], v[206:209], v[64:67]
	v_mfma_f32_16x16x32_bf16 v[108:111], v[170:173], v[186:189], v[108:111]
	v_mfma_f32_16x16x32_bf16 v[104:107], v[178:181], v[186:189], v[104:107]
	v_mfma_f32_16x16x32_bf16 v[100:103], v[170:173], v[194:197], v[100:103]
	v_mfma_f32_16x16x32_bf16 v[92:95], v[178:181], v[194:197], v[92:95]
	v_mfma_f32_16x16x32_bf16 v[84:87], v[170:173], v[202:205], v[84:87]
	v_mfma_f32_16x16x32_bf16 v[76:79], v[178:181], v[202:205], v[76:79]
	v_mfma_f32_16x16x32_bf16 v[68:71], v[170:173], v[210:213], v[68:71]
	v_mfma_f32_16x16x32_bf16 v[64:67], v[178:181], v[210:213], v[64:67]
	s_barrier
	s_add_i32 s22, s44, s26
	v_lshl_add_u64 v[214:215], v[214:215], 0, s[10:11]
	s_mov_b32 m0, s22
	ds_read_b128 v[182:185], v157 offset:49152
	ds_read_b128 v[186:189], v157 offset:50176
	ds_read_b128 v[190:193], v157 offset:51200
	ds_read_b128 v[194:197], v157 offset:52224
	ds_read_b128 v[198:201], v157 offset:53248
	ds_read_b128 v[202:205], v157 offset:54272
	ds_read_b128 v[206:209], v157 offset:55296
	ds_read_b128 v[210:213], v157 offset:56320
	global_load_lds_dwordx4 v[214:215], off
	s_add_i32 m0, s22, 0x2000
	s_add_u32 s20, s20, 0xb0080
	v_lshl_add_u64 v[214:215], v[216:217], 0, s[10:11]
	s_addc_u32 s21, s21, 0
	s_add_i32 s22, s45, s26
	global_load_lds_dwordx4 v[214:215], off
	v_lshl_add_u64 v[214:215], s[20:21], 0, v[130:131]
	s_mov_b32 m0, s22
	s_nop 0
	global_load_lds_dwordx4 v[214:215], off
	v_lshl_add_u64 v[214:215], s[20:21], 0, v[134:135]
	s_add_i32 m0, s22, 0x2000
	s_nop 0
	global_load_lds_dwordx4 v[214:215], off
	v_lshl_add_u64 v[214:215], v[218:219], 0, s[10:11]
	s_mov_b32 m0, s33
	s_nop 0
	global_load_lds_dwordx4 v[214:215], off
	v_lshl_add_u64 v[214:215], v[220:221], 0, s[10:11]
	s_mov_b32 m0, s34
	s_nop 0
	global_load_lds_dwordx4 v[214:215], off
	s_waitcnt vmcnt(8)
	s_waitcnt lgkmcnt(0)
	s_barrier
	s_waitcnt lgkmcnt(0)
	v_mfma_f32_16x16x32_bf16 v[60:63], v[146:149], v[182:185], v[60:63]
	v_mfma_f32_16x16x32_bf16 v[56:59], v[158:161], v[182:185], v[56:59]
	v_mfma_f32_16x16x32_bf16 v[48:51], v[146:149], v[190:193], v[48:51]
	v_mfma_f32_16x16x32_bf16 v[40:43], v[158:161], v[190:193], v[40:43]
	v_mfma_f32_16x16x32_bf16 v[32:35], v[146:149], v[198:201], v[32:35]
	v_mfma_f32_16x16x32_bf16 v[24:27], v[158:161], v[198:201], v[24:27]
	v_mfma_f32_16x16x32_bf16 v[16:19], v[146:149], v[206:209], v[16:19]
	v_mfma_f32_16x16x32_bf16 v[8:11], v[158:161], v[206:209], v[8:11]
	v_mfma_f32_16x16x32_bf16 v[60:63], v[150:153], v[186:189], v[60:63]
	v_mfma_f32_16x16x32_bf16 v[56:59], v[162:165], v[186:189], v[56:59]
	v_mfma_f32_16x16x32_bf16 v[48:51], v[150:153], v[194:197], v[48:51]
	v_mfma_f32_16x16x32_bf16 v[40:43], v[162:165], v[194:197], v[40:43]
	v_mfma_f32_16x16x32_bf16 v[32:35], v[150:153], v[202:205], v[32:35]
	v_mfma_f32_16x16x32_bf16 v[24:27], v[162:165], v[202:205], v[24:27]
	v_mfma_f32_16x16x32_bf16 v[16:19], v[150:153], v[210:213], v[16:19]
	v_mfma_f32_16x16x32_bf16 v[8:11], v[162:165], v[210:213], v[8:11]
	v_mfma_f32_16x16x32_bf16 v[52:55], v[166:169], v[182:185], v[52:55]
	v_mfma_f32_16x16x32_bf16 v[44:47], v[174:177], v[182:185], v[44:47]
	v_mfma_f32_16x16x32_bf16 v[36:39], v[166:169], v[190:193], v[36:39]
	v_mfma_f32_16x16x32_bf16 v[28:31], v[174:177], v[190:193], v[28:31]
	v_mfma_f32_16x16x32_bf16 v[20:23], v[166:169], v[198:201], v[20:23]
	v_mfma_f32_16x16x32_bf16 v[12:15], v[174:177], v[198:201], v[12:15]
	v_mfma_f32_16x16x32_bf16 v[4:7], v[166:169], v[206:209], v[4:7]
	v_mfma_f32_16x16x32_bf16 v[0:3], v[174:177], v[206:209], v[0:3]
	v_mfma_f32_16x16x32_bf16 v[52:55], v[170:173], v[186:189], v[52:55]
	v_mfma_f32_16x16x32_bf16 v[44:47], v[178:181], v[186:189], v[44:47]
	v_mfma_f32_16x16x32_bf16 v[36:39], v[170:173], v[194:197], v[36:39]
	v_mfma_f32_16x16x32_bf16 v[28:31], v[178:181], v[194:197], v[28:31]
	v_mfma_f32_16x16x32_bf16 v[20:23], v[170:173], v[202:205], v[20:23]
	v_mfma_f32_16x16x32_bf16 v[12:15], v[178:181], v[202:205], v[12:15]
	v_mfma_f32_16x16x32_bf16 v[4:7], v[170:173], v[210:213], v[4:7]
	v_mfma_f32_16x16x32_bf16 v[0:3], v[178:181], v[210:213], v[0:3]
	s_barrier
	s_add_i32 s43, s43, 2
	s_add_u32 s18, s18, 0x100
	s_addc_u32 s19, s19, 0
	s_add_u32 s17, s17, 0x100
	s_addc_u32 s42, s42, 0
	s_cmp_gt_u32 s43, 41
	s_cbranch_scc0 .LBB0_2058
	s_and_b64 vcc, exec, s[12:13]
	s_cbranch_vccz .LBB0_2061
	s_barrier
